# static s_setprio 1 for waves 4-7 at entry, all 256 per-segment priority flips in the GEMM K-loops deleted
# speedup vs baseline: 1.0062x; 1.0062x over previous
; __device__ __forceinline__ int lbid() { int b = blockIdx.x; asm volatile("" : "+s"(b)); return b; }
; __device__ __forceinline__ int lgrid() { int g = gridDim.x; asm volatile("" : "+s"(g)); return g; }
; #define LAS __attribute__((address_space(3)))
; __device__ __forceinline__ void p0_prologue(const Args& a, LAS unsigned char* lds, int tid, int lane, int wave) {
;     const int BID = lbid(), GRD = lgrid();
;     unsigned char* ws = a.ws;
;     LAS float* scr = (LAS float*)(lds + wave * 16384);
;     const int G = GRD, gw = BID * NWAVES + wave, NGW = G * NWAVES;
;     constexpr int I_GU = (D / 64) * (FF / 32), I_D = (FF / 64) * (D / 32), I_IN = (D / 64) * (3072 / 32), I_SQ = (D / 64) * (D / 32), I_SIN = (D / 64) * (2048 / 32), I_PP = (PLE / 64) * (D / 32);
;     constexpr int NITEMS = 8 * I_GU + 4 * I_D + I_IN + I_SQ + I_SIN + I_SQ + 2 * I_SQ + 2 * I_PP;
;     for (int it = gw; it < NITEMS; it += NGW) {
;         int r = it;
;         if (r < 8 * I_GU) { const int j = r / I_GU, mat = j >> 1, up = j & 1; r -= j * I_GU;
;             const bool ln = (mat & 1); const int li_ = mat >> 1;
;             transpose_item((up ? a.in[5] : a.in[4]) + (size_t)mat * D * FF, D, FF / 32, FF, (bf16*)(ws + WS_WGU + (size_t)mat * SZ_WGU), up ? 2 : 1, scr, r, lane,
;                            ln ? a.in[2] + (li_ * 3 + 1) * D : nullptr, ln ? a.in[3] + (li_ * 3 + 1) * D : nullptr, (float*)(ws + WS_PCS) + (li_ ? CS_WGU11 : CS_WGU01), (float*)(ws + WS_PCB) + (li_ ? CS_WGU11 : CS_WGU01)); continue; } r -= 8 * I_GU;
; __global__ void __launch_bounds__(NWAVES * 64, 2) mega_fwd(Args a0) {
;     ...
;     const int tid = threadIdx.x, lane = tid & 63, wave = __builtin_amdgcn_readfirstlane(tid >> 6);
;     cg::grid_group grid = cg::this_grid();
;     volatile LAS unsigned* MISC = (volatile LAS unsigned*)(L + 131072);
;     if (threadIdx.x < 16) MISC[threadIdx.x] = 0u;
;     __syncthreads();
_Z8mega_fwd4Args:
	s_load_dwordx4 s[92:95], s[0:1], 0xa8
	s_load_dwordx2 s[84:85], s[0:1], 0xb8
	s_load_dword s3, s[0:1], 0xc0
	s_add_u32 s28, s0, 0xb8
	v_and_b32_e32 v254, 0x3ff, v0
	s_addc_u32 s29, s1, 0
	v_readfirstlane_b32 s98, v254
	s_nop 3
	s_cmpk_lt_u32 s98, 0x100
	s_cbranch_scc1 .Lprio_done
	s_setprio 1
.Lprio_done:
	v_cmp_gt_u32_e32 vcc, 16, v254
	s_and_saveexec_b64 s[4:5], vcc
	v_lshl_add_u32 v1, v254, 2, 0
	v_add_u32_e32 v1, 0x20000, v1
	v_mov_b32_e32 v2, 0
	ds_write_b32 v1, v2
	s_or_b64 exec, exec, s[4:5]
	s_waitcnt lgkmcnt(0)
	s_cmp_lt_i32 s94, 1
	s_cselect_b64 s[4:5], -1, 0
	s_cmp_gt_i32 s95, 0
	s_cselect_b64 s[6:7], -1, 0
	s_and_b64 s[4:5], s[4:5], s[6:7]
	s_mov_b32 s74, 0
	s_andn2_b64 vcc, exec, s[4:5]
	s_mov_b32 s33, 0
	s_barrier
	s_cbranch_vccnz .LBB0_241
	v_mov_b32_e32 v10, v254
	s_mov_b32 s4, s2
	s_mov_b32 s4, s84
	s_mov_b64 s[4:5], s[0:1]
	s_load_dwordx16 s[8:23], s[4:5], 0x0
	s_load_dwordx2 s[38:39], s[4:5], 0x78
	s_load_dwordx2 s[30:31], s[4:5], 0xa8
	v_readfirstlane_b32 s6, v10
	s_mov_b32 s34, s2
	s_ashr_i32 s6, s6, 6
	s_lshl_b32 s7, s34, 3
	s_add_i32 s33, s7, s6
	s_mov_b32 s36, s84
	s_cmpk_gt_i32 s33, 0x54ff
	s_cbranch_scc1 .LBB0_199
	s_load_dwordx2 s[44:45], s[4:5], 0x48
	s_load_dwordx2 s[46:47], s[4:5], 0x58
	s_load_dwordx2 s[40:41], s[4:5], 0x98
	s_load_dwordx4 s[24:27], s[4:5], 0x88
	s_lshl_b32 s4, s6, 14
	v_and_b32_e32 v3, 7, v10
	v_bfe_u32 v11, v10, 3, 3
	v_and_b32_e32 v1, 63, v10
	s_add_i32 s4, s4, 0
	v_mul_u32_u24_e32 v5, 0x420, v3
	v_lshlrev_b32_e32 v6, 2, v11
	v_add3_u32 v13, s4, v5, v6
	v_mov_b32_e32 v5, 0x1be00000
	v_mov_b32_e32 v6, 0x1bc00000
	v_cmp_gt_u32_e32 vcc, 32, v1
	s_lshl_b32 s35, s36, 3
	v_and_b32_e32 v2, 31, v10
	v_mov_b32_e32 v15, 0
	v_cndmask_b32_e32 v14, v5, v6, vcc
	s_waitcnt lgkmcnt(0)
	s_add_u32 s37, s30, 0x5600000
	v_lshlrev_b32_e32 v4, 2, v2
	v_lshl_add_u64 v[20:21], s[30:31], 0, v[14:15]
	v_lshlrev_b32_e32 v14, 4, v3
	s_addc_u32 s52, s31, 0
	v_add_u32_e32 v16, s4, v4
	v_lshl_add_u64 v[6:7], s[30:31], 0, v[14:15]
	s_mov_b64 s[4:5], 0x5000000
	s_add_u32 s53, s30, 0x5200000
	v_lshl_add_u64 v[22:23], v[6:7], 0, s[4:5]
	s_mov_b64 s[4:5], 0x4c00000
	s_addc_u32 s54, s31, 0
	v_cmp_lt_u32_e64 s[6:7], 31, v1
	v_lshl_add_u64 v[24:25], v[6:7], 0, s[4:5]
	v_mov_b32_e32 v1, 0x1be03000
	v_mov_b32_e32 v5, 0x1bc03000
	s_mov_b64 s[4:5], 0x4a00000
	v_cndmask_b32_e32 v14, v1, v5, vcc
	v_lshl_add_u64 v[28:29], v[6:7], 0, s[4:5]
	s_mov_b64 s[4:5], 0x2e00000
	s_add_u32 s55, s30, 0x200000
	v_lshl_add_u64 v[26:27], s[30:31], 0, v[14:15]
	v_lshl_add_u64 v[30:31], v[6:7], 0, s[4:5]
	s_addc_u32 s56, s31, 0
	s_mov_b64 s[4:5], 0x4400000
	v_lshlrev_b32_e32 v14, 5, v3
	v_bfe_u32 v12, v10, 5, 1
	v_lshlrev_b32_e32 v18, 3, v3
	v_lshl_add_u64 v[32:33], v[6:7], 0, s[4:5]
	v_mov_b32_e32 v5, v15
	v_lshl_add_u64 v[38:39], s[12:13], 0, v[14:15]
	s_mov_b64 s[4:5], 0x3000
	s_cmp_lg_u64 s[12:13], 0
	s_mov_b32 s43, 0
	v_or_b32_e32 v17, 8, v11
	v_or_b32_e32 v19, 16, v11
	v_or_b32_e32 v52, 24, v11
	v_lshl_add_u64 v[34:35], s[24:25], 0, v[4:5]
	v_lshl_add_u64 v[36:37], s[46:47], 0, v[4:5]
	v_lshl_add_u64 v[40:41], v[38:39], 0, s[4:5]
	v_lshl_add_u64 v[42:43], s[44:45], 0, v[4:5]
	v_lshl_add_u64 v[44:45], s[22:23], 0, v[4:5]
	s_cselect_b64 s[24:25], -1, 0
	v_mov_b32_e32 v1, v12
	s_add_i32 s57, s33, 0xffffb000
	s_add_i32 s58, s33, 0xb600
	s_movk_i32 s59, 0x84
	s_movk_i32 s60, 0x7fff
	s_mov_b32 s61, 0xffff0000
	s_mov_b32 s62, 0x10000
	v_mov_b32_e32 v53, 0x3000
	s_movk_i32 s63, 0x3020
	s_movk_i32 s64, 0x2c00
	v_mov_b32_e32 v54, 0x1000
	s_movk_i32 s65, 0x5000
	v_lshlrev_b32_e32 v46, 2, v2
	v_lshlrev_b32_e32 v48, 1, v18
	v_mov_b32_e32 v55, 0x12000
	s_branch .LBB0_8

; #define PG8_STAGE(bufoff, gbase, voff) do { _Pragma("unroll") for (int _i = 0; _i < 2; ++_i) \
;         __builtin_amdgcn_global_load_lds((const unsigned*)((const char*)(gbase) + (voff)[_i]), (PG8_LAS unsigned*)(lds + (bufoff) + ldsw + _i * 8192), 16, 0, 0); } while (0)
; #define PG8_LDA(dst, b, h) do { _Pragma("unroll") for (int m = 0; m < 4; ++m) _Pragma("unroll") for (int k = 0; k < 2; ++k) dst[m][k] = *(const PG8_LAS bf16x8*)(lds + PG8_SA(b, h) + aoff + m * 2048 + k * 1024); } while (0)
; #define PG8_LDB(dst, b, h) do { _Pragma("unroll") for (int n = 0; n < 2; ++n) _Pragma("unroll") for (int k = 0; k < 2; ++k) dst[n][k] = *(const PG8_LAS bf16x8*)(lds + PG8_SB(b, h) + boff + n * 2048 + k * 1024); } while (0)
; #define PG8_MMA(ai, bj, At, Bt) do { __builtin_amdgcn_s_setprio(1); _Pragma("unroll") for (int m = 0; m < 4; ++m) _Pragma("unroll") for (int n = 0; n < 2; ++n) _Pragma("unroll") for (int k = 0; k < 2; ++k) \
;         acc[ai][bj][m][n] = __builtin_amdgcn_mfma_f32_16x16x32_bf16(Bt[n][k], At[m][k], acc[ai][bj][m][n], 0, 0, 0); __builtin_amdgcn_s_setprio(0); } while (0)
; #define PG8_WAIT_V(n) asm volatile("s_waitcnt vmcnt(" #n ")" ::: "memory")
; #define PG8_WAIT_L(n) asm volatile("s_waitcnt lgkmcnt(" #n ")" ::: "memory")
; #define PG8_BAR __builtin_amdgcn_s_barrier()
; #define PG8_SCHED __builtin_amdgcn_sched_barrier(0)
; template <class Epi, class Sched, bool ALIGN_EPI = false, bool SP2 = false>
; __device__ __forceinline__ void gemm_phase(PG8_LAS unsigned char* lds, const Gemm g, const Sched& S, const Epi& E) {
;     ...
;             PG8_LDB(B0, 0, 0); PG8_LDB(B1, 0, 1); PG8_SCHED; PG8_LDA(At, 0, 0); PG8_STAGE(PG8_SA(1, 1), a1 + hstepA, voffA);
;             PG8_WAIT_V(8); PG8_WAIT_L(0); PG8_BAR; PG8_MMA(0, 0, At, B0); PG8_MMA(0, 1, At, B1); PG8_BAR; PG8_SCHED;
;             PG8_LDA(At, 0, 1); PG8_STAGE(PG8_SB(0, 0), b2, voffB); PG8_STAGE(PG8_SB(0, 1), b2 + hstepB, voffB); PG8_STAGE(PG8_SA(0, 0), a2, voffA);
.LBB0_259:
	ds_read_b128 v[152:155], v149
	ds_read_b128 v[156:159], v149 offset:1024
	ds_read_b128 v[160:163], v149 offset:2048
	ds_read_b128 v[164:167], v149 offset:3072
	ds_read_b128 v[168:171], v150
	ds_read_b128 v[172:175], v150 offset:1024
	ds_read_b128 v[176:179], v150 offset:2048
	ds_read_b128 v[180:183], v150 offset:3072
	s_add_i32 s62, s28, 2
	s_add_u32 s29, s26, 0xfffc0080
	s_addc_u32 s30, s27, -1
	s_cmp_eq_u32 s52, s28
	s_cselect_b32 s28, s59, s60
	s_cselect_b32 s31, s17, s30
	s_cselect_b32 s30, s19, s29
	s_cselect_b32 s29, s58, s61
	v_lshl_add_u64 v[144:145], s[26:27], 0, v[136:137]
	s_add_i32 m0, s43, 0xc000
	ds_read_b128 v[184:187], v151
	ds_read_b128 v[188:191], v151 offset:1024
	ds_read_b128 v[192:195], v151 offset:2048
	ds_read_b128 v[196:199], v151 offset:3072
	ds_read_b128 v[200:203], v151 offset:4096
	ds_read_b128 v[204:207], v151 offset:5120
	ds_read_b128 v[208:211], v151 offset:6144
	ds_read_b128 v[212:215], v151 offset:7168
	global_load_lds_dwordx4 v[144:145], off
	v_lshl_add_u64 v[144:145], s[26:27], 0, v[138:139]
	s_add_i32 m0, s43, 0xe000
	s_nop 0
	global_load_lds_dwordx4 v[144:145], off
	s_waitcnt vmcnt(8)
	s_waitcnt lgkmcnt(0)
	s_barrier
	s_waitcnt lgkmcnt(0)
	v_mfma_f32_16x16x32_bf16 v[124:127], v[152:155], v[184:187], v[124:127]
	v_mfma_f32_16x16x32_bf16 v[116:119], v[160:163], v[184:187], v[116:119]
	v_mfma_f32_16x16x32_bf16 v[108:111], v[152:155], v[192:195], v[108:111]
	v_mfma_f32_16x16x32_bf16 v[100:103], v[160:163], v[192:195], v[100:103]
	v_mfma_f32_16x16x32_bf16 v[92:95], v[152:155], v[200:203], v[92:95]
	v_mfma_f32_16x16x32_bf16 v[84:87], v[160:163], v[200:203], v[84:87]
	v_mfma_f32_16x16x32_bf16 v[76:79], v[152:155], v[208:211], v[76:79]
	v_mfma_f32_16x16x32_bf16 v[68:71], v[160:163], v[208:211], v[68:71]
	v_mfma_f32_16x16x32_bf16 v[124:127], v[156:159], v[188:191], v[124:127]
	v_mfma_f32_16x16x32_bf16 v[116:119], v[164:167], v[188:191], v[116:119]
	v_mfma_f32_16x16x32_bf16 v[108:111], v[156:159], v[196:199], v[108:111]
	v_mfma_f32_16x16x32_bf16 v[100:103], v[164:167], v[196:199], v[100:103]
	v_mfma_f32_16x16x32_bf16 v[92:95], v[156:159], v[204:207], v[92:95]
	v_mfma_f32_16x16x32_bf16 v[84:87], v[164:167], v[204:207], v[84:87]
	v_mfma_f32_16x16x32_bf16 v[76:79], v[156:159], v[212:215], v[76:79]
	v_mfma_f32_16x16x32_bf16 v[68:71], v[164:167], v[212:215], v[68:71]
	v_mfma_f32_16x16x32_bf16 v[120:123], v[168:171], v[184:187], v[120:123]
	v_mfma_f32_16x16x32_bf16 v[112:115], v[176:179], v[184:187], v[112:115]
	v_mfma_f32_16x16x32_bf16 v[104:107], v[168:171], v[192:195], v[104:107]
	v_mfma_f32_16x16x32_bf16 v[96:99], v[176:179], v[192:195], v[96:99]
	v_mfma_f32_16x16x32_bf16 v[88:91], v[168:171], v[200:203], v[88:91]
	v_mfma_f32_16x16x32_bf16 v[80:83], v[176:179], v[200:203], v[80:83]
	v_mfma_f32_16x16x32_bf16 v[72:75], v[168:171], v[208:211], v[72:75]
	v_mfma_f32_16x16x32_bf16 v[64:67], v[176:179], v[208:211], v[64:67]
	v_mfma_f32_16x16x32_bf16 v[120:123], v[172:175], v[188:191], v[120:123]
	v_mfma_f32_16x16x32_bf16 v[112:115], v[180:183], v[188:191], v[112:115]
	v_mfma_f32_16x16x32_bf16 v[104:107], v[172:175], v[196:199], v[104:107]
	v_mfma_f32_16x16x32_bf16 v[96:99], v[180:183], v[196:199], v[96:99]
	v_mfma_f32_16x16x32_bf16 v[88:91], v[172:175], v[204:207], v[88:91]
	v_mfma_f32_16x16x32_bf16 v[80:83], v[180:183], v[204:207], v[80:83]
	v_mfma_f32_16x16x32_bf16 v[72:75], v[172:175], v[212:215], v[72:75]
	v_mfma_f32_16x16x32_bf16 v[64:67], v[180:183], v[212:215], v[64:67]
	s_barrier
	s_add_i32 s63, s56, s38
	v_lshl_add_u64 v[144:145], s[28:29], 0, v[132:133]
	s_mov_b32 m0, s63
	ds_read_b128 v[184:187], v151 offset:16384
	ds_read_b128 v[188:191], v151 offset:17408
	ds_read_b128 v[192:195], v151 offset:18432
	ds_read_b128 v[196:199], v151 offset:19456
	ds_read_b128 v[200:203], v151 offset:20480
	ds_read_b128 v[204:207], v151 offset:21504
	ds_read_b128 v[208:211], v151 offset:22528
	ds_read_b128 v[212:215], v151 offset:23552
	global_load_lds_dwordx4 v[144:145], off
	s_add_i32 m0, s63, 0x2000
	s_add_u32 s64, s28, 0x40000
	v_lshl_add_u64 v[216:217], s[28:29], 0, v[128:129]
	s_addc_u32 s65, s29, 0
	s_add_i32 s63, s57, s38
	global_load_lds_dwordx4 v[216:217], off
	v_lshl_add_u64 v[218:219], s[64:65], 0, v[132:133]
	s_mov_b32 m0, s63
	v_lshl_add_u64 v[220:221], s[30:31], 0, v[130:131]
	global_load_lds_dwordx4 v[218:219], off
	v_lshl_add_u64 v[218:219], s[64:65], 0, v[128:129]
	s_add_i32 m0, s63, 0x2000
	s_nop 0
	global_load_lds_dwordx4 v[218:219], off
	v_lshl_add_u64 v[218:219], s[30:31], 0, v[134:135]
	s_mov_b32 m0, s43
	s_nop 0
	global_load_lds_dwordx4 v[218:219], off
	s_mov_b32 m0, s44
	s_nop 0
	global_load_lds_dwordx4 v[220:221], off
	s_waitcnt vmcnt(8)
	s_waitcnt lgkmcnt(0)
	s_barrier
; #define PG8_STAGE(bufoff, gbase, voff) do { _Pragma("unroll") for (int _i = 0; _i < 2; ++_i) \
;         __builtin_amdgcn_global_load_lds((const unsigned*)((const char*)(gbase) + (voff)[_i]), (PG8_LAS unsigned*)(lds + (bufoff) + ldsw + _i * 8192), 16, 0, 0); } while (0)
; #define PG8_LDA(dst, b, h) do { _Pragma("unroll") for (int m = 0; m < 4; ++m) _Pragma("unroll") for (int k = 0; k < 2; ++k) dst[m][k] = *(const PG8_LAS bf16x8*)(lds + PG8_SA(b, h) + aoff + m * 2048 + k * 1024); } while (0)
; #define PG8_LDB(dst, b, h) do { _Pragma("unroll") for (int n = 0; n < 2; ++n) _Pragma("unroll") for (int k = 0; k < 2; ++k) dst[n][k] = *(const PG8_LAS bf16x8*)(lds + PG8_SB(b, h) + boff + n * 2048 + k * 1024); } while (0)
; #define PG8_MMA(ai, bj, At, Bt) do { __builtin_amdgcn_s_setprio(1); _Pragma("unroll") for (int m = 0; m < 4; ++m) _Pragma("unroll") for (int n = 0; n < 2; ++n) _Pragma("unroll") for (int k = 0; k < 2; ++k) \
;         acc[ai][bj][m][n] = __builtin_amdgcn_mfma_f32_16x16x32_bf16(Bt[n][k], At[m][k], acc[ai][bj][m][n], 0, 0, 0); __builtin_amdgcn_s_setprio(0); } while (0)
; #define PG8_WAIT_V(n) asm volatile("s_waitcnt vmcnt(" #n ")" ::: "memory")
; #define PG8_WAIT_L(n) asm volatile("s_waitcnt lgkmcnt(" #n ")" ::: "memory")
; #define PG8_BAR __builtin_amdgcn_s_barrier()
; #define PG8_SCHED __builtin_amdgcn_sched_barrier(0)
; template <class Epi, class Sched, bool ALIGN_EPI = false, bool SP2 = false>
; __device__ __forceinline__ void gemm_phase(PG8_LAS unsigned char* lds, const Gemm g, const Sched& S, const Epi& E) {
;     ...
;             PG8_WAIT_V(8); PG8_WAIT_L(0); PG8_BAR; PG8_MMA(1, 0, At, B0); PG8_MMA(1, 1, At, B1); PG8_BAR; PG8_SCHED;
;             PG8_LDB(B0, 1, 0); PG8_LDB(B1, 1, 1); PG8_SCHED; PG8_LDA(At, 1, 0); PG8_STAGE(PG8_SA(0, 1), a2 + hstepA, voffA);
;             PG8_WAIT_V(8); PG8_WAIT_L(0); PG8_BAR; PG8_MMA(0, 0, At, B0); PG8_MMA(0, 1, At, B1); PG8_BAR; PG8_SCHED;
	s_waitcnt lgkmcnt(0)
	v_mfma_f32_16x16x32_bf16 v[60:63], v[152:155], v[184:187], v[60:63]
	v_mfma_f32_16x16x32_bf16 v[52:55], v[160:163], v[184:187], v[52:55]
	v_mfma_f32_16x16x32_bf16 v[44:47], v[152:155], v[192:195], v[44:47]
	v_mfma_f32_16x16x32_bf16 v[36:39], v[160:163], v[192:195], v[36:39]
	v_mfma_f32_16x16x32_bf16 v[28:31], v[152:155], v[200:203], v[28:31]
	v_mfma_f32_16x16x32_bf16 v[20:23], v[160:163], v[200:203], v[20:23]
	v_mfma_f32_16x16x32_bf16 v[12:15], v[152:155], v[208:211], v[12:15]
	v_mfma_f32_16x16x32_bf16 v[4:7], v[160:163], v[208:211], v[4:7]
	v_mfma_f32_16x16x32_bf16 v[60:63], v[156:159], v[188:191], v[60:63]
	v_mfma_f32_16x16x32_bf16 v[52:55], v[164:167], v[188:191], v[52:55]
	v_mfma_f32_16x16x32_bf16 v[44:47], v[156:159], v[196:199], v[44:47]
	v_mfma_f32_16x16x32_bf16 v[36:39], v[164:167], v[196:199], v[36:39]
	v_mfma_f32_16x16x32_bf16 v[28:31], v[156:159], v[204:207], v[28:31]
	v_mfma_f32_16x16x32_bf16 v[20:23], v[164:167], v[204:207], v[20:23]
	v_mfma_f32_16x16x32_bf16 v[12:15], v[156:159], v[212:215], v[12:15]
	v_mfma_f32_16x16x32_bf16 v[4:7], v[164:167], v[212:215], v[4:7]
	v_mfma_f32_16x16x32_bf16 v[56:59], v[168:171], v[184:187], v[56:59]
	v_mfma_f32_16x16x32_bf16 v[48:51], v[176:179], v[184:187], v[48:51]
	v_mfma_f32_16x16x32_bf16 v[40:43], v[168:171], v[192:195], v[40:43]
	v_mfma_f32_16x16x32_bf16 v[32:35], v[176:179], v[192:195], v[32:35]
	v_mfma_f32_16x16x32_bf16 v[24:27], v[168:171], v[200:203], v[24:27]
	v_mfma_f32_16x16x32_bf16 v[16:19], v[176:179], v[200:203], v[16:19]
	v_mfma_f32_16x16x32_bf16 v[8:11], v[168:171], v[208:211], v[8:11]
	v_mfma_f32_16x16x32_bf16 v[0:3], v[176:179], v[208:211], v[0:3]
	v_mfma_f32_16x16x32_bf16 v[56:59], v[172:175], v[188:191], v[56:59]
	v_mfma_f32_16x16x32_bf16 v[48:51], v[180:183], v[188:191], v[48:51]
	v_mfma_f32_16x16x32_bf16 v[40:43], v[172:175], v[196:199], v[40:43]
	v_mfma_f32_16x16x32_bf16 v[32:35], v[180:183], v[196:199], v[32:35]
	v_mfma_f32_16x16x32_bf16 v[24:27], v[172:175], v[204:207], v[24:27]
	v_mfma_f32_16x16x32_bf16 v[16:19], v[180:183], v[204:207], v[16:19]
	v_mfma_f32_16x16x32_bf16 v[8:11], v[172:175], v[212:215], v[8:11]
	v_mfma_f32_16x16x32_bf16 v[0:3], v[180:183], v[212:215], v[0:3]
	s_barrier
	s_add_i32 s63, 0, 0x18000
	s_add_i32 s64, 0, 0x1c000
	v_add_u32_e32 v164, s63, v148
	v_add_u32_e32 v180, s64, v148
	ds_read_b128 v[152:155], v164
	ds_read_b128 v[156:159], v164 offset:1024
	ds_read_b128 v[160:163], v164 offset:2048
	ds_read_b128 v[164:167], v164 offset:3072
	ds_read_b128 v[168:171], v180
	ds_read_b128 v[172:175], v180 offset:1024
	ds_read_b128 v[176:179], v180 offset:2048
	ds_read_b128 v[180:183], v180 offset:3072
	s_add_u32 s30, s30, 0x40000
	s_addc_u32 s31, s31, 0
	s_mov_b32 m0, s45
	v_lshl_add_u64 v[222:223], s[30:31], 0, v[134:135]
	ds_read_b128 v[184:187], v151 offset:32768
	ds_read_b128 v[188:191], v151 offset:33792
	ds_read_b128 v[192:195], v151 offset:34816
	ds_read_b128 v[196:199], v151 offset:35840
	ds_read_b128 v[200:203], v151 offset:36864
	ds_read_b128 v[204:207], v151 offset:37888
	ds_read_b128 v[208:211], v151 offset:38912
	ds_read_b128 v[212:215], v151 offset:39936
	global_load_lds_dwordx4 v[222:223], off
	v_lshl_add_u64 v[222:223], s[30:31], 0, v[130:131]
	s_mov_b32 m0, s46
	s_nop 0
	global_load_lds_dwordx4 v[222:223], off
	s_waitcnt vmcnt(8)
	s_waitcnt lgkmcnt(0)
	s_barrier
	s_waitcnt lgkmcnt(0)
	v_mfma_f32_16x16x32_bf16 v[124:127], v[152:155], v[184:187], v[124:127]
	v_mfma_f32_16x16x32_bf16 v[116:119], v[160:163], v[184:187], v[116:119]
	v_mfma_f32_16x16x32_bf16 v[108:111], v[152:155], v[192:195], v[108:111]
	v_mfma_f32_16x16x32_bf16 v[100:103], v[160:163], v[192:195], v[100:103]
	v_mfma_f32_16x16x32_bf16 v[92:95], v[152:155], v[200:203], v[92:95]
	v_mfma_f32_16x16x32_bf16 v[84:87], v[160:163], v[200:203], v[84:87]
	v_mfma_f32_16x16x32_bf16 v[76:79], v[152:155], v[208:211], v[76:79]
	v_mfma_f32_16x16x32_bf16 v[68:71], v[160:163], v[208:211], v[68:71]
	v_mfma_f32_16x16x32_bf16 v[124:127], v[156:159], v[188:191], v[124:127]
	v_mfma_f32_16x16x32_bf16 v[116:119], v[164:167], v[188:191], v[116:119]
	v_mfma_f32_16x16x32_bf16 v[108:111], v[156:159], v[196:199], v[108:111]
	v_mfma_f32_16x16x32_bf16 v[100:103], v[164:167], v[196:199], v[100:103]
	v_mfma_f32_16x16x32_bf16 v[92:95], v[156:159], v[204:207], v[92:95]
	v_mfma_f32_16x16x32_bf16 v[84:87], v[164:167], v[204:207], v[84:87]
	v_mfma_f32_16x16x32_bf16 v[76:79], v[156:159], v[212:215], v[76:79]
	v_mfma_f32_16x16x32_bf16 v[68:71], v[164:167], v[212:215], v[68:71]
	v_mfma_f32_16x16x32_bf16 v[120:123], v[168:171], v[184:187], v[120:123]
	v_mfma_f32_16x16x32_bf16 v[112:115], v[176:179], v[184:187], v[112:115]
	v_mfma_f32_16x16x32_bf16 v[104:107], v[168:171], v[192:195], v[104:107]
	v_mfma_f32_16x16x32_bf16 v[96:99], v[176:179], v[192:195], v[96:99]
	v_mfma_f32_16x16x32_bf16 v[88:91], v[168:171], v[200:203], v[88:91]
	v_mfma_f32_16x16x32_bf16 v[80:83], v[176:179], v[200:203], v[80:83]
	v_mfma_f32_16x16x32_bf16 v[72:75], v[168:171], v[208:211], v[72:75]
	v_mfma_f32_16x16x32_bf16 v[64:67], v[176:179], v[208:211], v[64:67]
	v_mfma_f32_16x16x32_bf16 v[120:123], v[172:175], v[188:191], v[120:123]
	v_mfma_f32_16x16x32_bf16 v[112:115], v[180:183], v[188:191], v[112:115]
	v_mfma_f32_16x16x32_bf16 v[104:107], v[172:175], v[196:199], v[104:107]
	v_mfma_f32_16x16x32_bf16 v[96:99], v[180:183], v[196:199], v[96:99]
	v_mfma_f32_16x16x32_bf16 v[88:91], v[172:175], v[204:207], v[88:91]
	v_mfma_f32_16x16x32_bf16 v[80:83], v[180:183], v[204:207], v[80:83]
	v_mfma_f32_16x16x32_bf16 v[72:75], v[172:175], v[212:215], v[72:75]
	v_mfma_f32_16x16x32_bf16 v[64:67], v[180:183], v[212:215], v[64:67]
	s_barrier
; #define PG8_STAGE(bufoff, gbase, voff) do { _Pragma("unroll") for (int _i = 0; _i < 2; ++_i) \
;         __builtin_amdgcn_global_load_lds((const unsigned*)((const char*)(gbase) + (voff)[_i]), (PG8_LAS unsigned*)(lds + (bufoff) + ldsw + _i * 8192), 16, 0, 0); } while (0)
; #define PG8_LDA(dst, b, h) do { _Pragma("unroll") for (int m = 0; m < 4; ++m) _Pragma("unroll") for (int k = 0; k < 2; ++k) dst[m][k] = *(const PG8_LAS bf16x8*)(lds + PG8_SA(b, h) + aoff + m * 2048 + k * 1024); } while (0)
; #define PG8_MMA(ai, bj, At, Bt) do { __builtin_amdgcn_s_setprio(1); _Pragma("unroll") for (int m = 0; m < 4; ++m) _Pragma("unroll") for (int n = 0; n < 2; ++n) _Pragma("unroll") for (int k = 0; k < 2; ++k) \
;         acc[ai][bj][m][n] = __builtin_amdgcn_mfma_f32_16x16x32_bf16(Bt[n][k], At[m][k], acc[ai][bj][m][n], 0, 0, 0); __builtin_amdgcn_s_setprio(0); } while (0)
; #define PG8_WAIT_V(n) asm volatile("s_waitcnt vmcnt(" #n ")" ::: "memory")
; #define PG8_WAIT_L(n) asm volatile("s_waitcnt lgkmcnt(" #n ")" ::: "memory")
; #define PG8_BAR __builtin_amdgcn_s_barrier()
; #define PG8_SCHED __builtin_amdgcn_sched_barrier(0)
; template <class Epi, class Sched, bool ALIGN_EPI = false, bool SP2 = false>
; __device__ __forceinline__ void gemm_phase(PG8_LAS unsigned char* lds, const Gemm g, const Sched& S, const Epi& E) {
;     ...
;         for (int t = 0; t < nt; t += 2) {
;     ...
;             PG8_LDA(At, 1, 1); PG8_STAGE(PG8_SB(1, 0), b3, voffB); PG8_STAGE(PG8_SB(1, 1), b3 + hstepB, voffB); PG8_STAGE(PG8_SA(1, 0), a3, voffA);
;             PG8_WAIT_V(8); PG8_WAIT_L(0); PG8_BAR; PG8_MMA(1, 0, At, B0); PG8_MMA(1, 1, At, B1); PG8_BAR; PG8_SCHED;
	s_add_i32 s30, s63, s38
	v_lshl_add_u64 v[144:145], v[144:145], 0, s[12:13]
	s_mov_b32 m0, s30
	ds_read_b128 v[184:187], v151 offset:49152
	ds_read_b128 v[188:191], v151 offset:50176
	ds_read_b128 v[192:195], v151 offset:51200
	ds_read_b128 v[196:199], v151 offset:52224
	ds_read_b128 v[200:203], v151 offset:53248
	ds_read_b128 v[204:207], v151 offset:54272
	ds_read_b128 v[208:211], v151 offset:55296
	ds_read_b128 v[212:215], v151 offset:56320
	global_load_lds_dwordx4 v[144:145], off
	s_add_i32 m0, s30, 0x2000
	s_add_u32 s28, s28, 0x40080
	v_lshl_add_u64 v[144:145], v[216:217], 0, s[12:13]
	s_addc_u32 s29, s29, 0
	s_add_i32 s30, s64, s38
	global_load_lds_dwordx4 v[144:145], off
	v_lshl_add_u64 v[144:145], s[28:29], 0, v[132:133]
	s_mov_b32 m0, s30
	s_nop 0
	global_load_lds_dwordx4 v[144:145], off
	v_lshl_add_u64 v[144:145], s[28:29], 0, v[128:129]
	s_add_i32 m0, s30, 0x2000
	s_nop 0
	global_load_lds_dwordx4 v[144:145], off
	v_lshl_add_u64 v[144:145], v[218:219], 0, s[12:13]
	s_mov_b32 m0, s50
	s_nop 0
	global_load_lds_dwordx4 v[144:145], off
	v_lshl_add_u64 v[144:145], v[220:221], 0, s[12:13]
	s_mov_b32 m0, s51
	s_nop 0
	global_load_lds_dwordx4 v[144:145], off
	s_waitcnt vmcnt(8)
	s_waitcnt lgkmcnt(0)
	s_barrier
	s_waitcnt lgkmcnt(0)
	v_mfma_f32_16x16x32_bf16 v[60:63], v[152:155], v[184:187], v[60:63]
	v_mfma_f32_16x16x32_bf16 v[52:55], v[160:163], v[184:187], v[52:55]
	v_mfma_f32_16x16x32_bf16 v[44:47], v[152:155], v[192:195], v[44:47]
	v_mfma_f32_16x16x32_bf16 v[36:39], v[160:163], v[192:195], v[36:39]
	v_mfma_f32_16x16x32_bf16 v[28:31], v[152:155], v[200:203], v[28:31]
	v_mfma_f32_16x16x32_bf16 v[20:23], v[160:163], v[200:203], v[20:23]
	v_mfma_f32_16x16x32_bf16 v[12:15], v[152:155], v[208:211], v[12:15]
	v_mfma_f32_16x16x32_bf16 v[4:7], v[160:163], v[208:211], v[4:7]
	v_mfma_f32_16x16x32_bf16 v[60:63], v[156:159], v[188:191], v[60:63]
	v_mfma_f32_16x16x32_bf16 v[52:55], v[164:167], v[188:191], v[52:55]
	v_mfma_f32_16x16x32_bf16 v[44:47], v[156:159], v[196:199], v[44:47]
	v_mfma_f32_16x16x32_bf16 v[36:39], v[164:167], v[196:199], v[36:39]
	v_mfma_f32_16x16x32_bf16 v[28:31], v[156:159], v[204:207], v[28:31]
	v_mfma_f32_16x16x32_bf16 v[20:23], v[164:167], v[204:207], v[20:23]
	v_mfma_f32_16x16x32_bf16 v[12:15], v[156:159], v[212:215], v[12:15]
	v_mfma_f32_16x16x32_bf16 v[4:7], v[164:167], v[212:215], v[4:7]
	v_mfma_f32_16x16x32_bf16 v[56:59], v[168:171], v[184:187], v[56:59]
	v_mfma_f32_16x16x32_bf16 v[48:51], v[176:179], v[184:187], v[48:51]
	v_mfma_f32_16x16x32_bf16 v[40:43], v[168:171], v[192:195], v[40:43]
	v_mfma_f32_16x16x32_bf16 v[32:35], v[176:179], v[192:195], v[32:35]
	v_mfma_f32_16x16x32_bf16 v[24:27], v[168:171], v[200:203], v[24:27]
	v_mfma_f32_16x16x32_bf16 v[16:19], v[176:179], v[200:203], v[16:19]
	v_mfma_f32_16x16x32_bf16 v[8:11], v[168:171], v[208:211], v[8:11]
	v_mfma_f32_16x16x32_bf16 v[0:3], v[176:179], v[208:211], v[0:3]
	v_mfma_f32_16x16x32_bf16 v[56:59], v[172:175], v[188:191], v[56:59]
	v_mfma_f32_16x16x32_bf16 v[48:51], v[180:183], v[188:191], v[48:51]
	v_mfma_f32_16x16x32_bf16 v[40:43], v[172:175], v[196:199], v[40:43]
	v_mfma_f32_16x16x32_bf16 v[32:35], v[180:183], v[196:199], v[32:35]
	v_mfma_f32_16x16x32_bf16 v[24:27], v[172:175], v[204:207], v[24:27]
	v_mfma_f32_16x16x32_bf16 v[16:19], v[180:183], v[204:207], v[16:19]
	v_mfma_f32_16x16x32_bf16 v[8:11], v[172:175], v[212:215], v[8:11]
	v_mfma_f32_16x16x32_bf16 v[0:3], v[180:183], v[212:215], v[0:3]
	s_barrier
	s_add_u32 s26, s26, 0x100
	s_addc_u32 s27, s27, 0
	s_add_u32 s60, s60, 0x100
	s_addc_u32 s61, s61, 0
	s_cmp_ge_i32 s62, s48
	s_mov_b32 s28, s62
	s_cbranch_scc0 .LBB0_259

; #define PG8_STAGE(bufoff, gbase, voff) do { _Pragma("unroll") for (int _i = 0; _i < 2; ++_i) \
;         __builtin_amdgcn_global_load_lds((const unsigned*)((const char*)(gbase) + (voff)[_i]), (PG8_LAS unsigned*)(lds + (bufoff) + ldsw + _i * 8192), 16, 0, 0); } while (0)
; #define PG8_LDA(dst, b, h) do { _Pragma("unroll") for (int m = 0; m < 4; ++m) _Pragma("unroll") for (int k = 0; k < 2; ++k) dst[m][k] = *(const PG8_LAS bf16x8*)(lds + PG8_SA(b, h) + aoff + m * 2048 + k * 1024); } while (0)
; #define PG8_LDB(dst, b, h) do { _Pragma("unroll") for (int n = 0; n < 2; ++n) _Pragma("unroll") for (int k = 0; k < 2; ++k) dst[n][k] = *(const PG8_LAS bf16x8*)(lds + PG8_SB(b, h) + boff + n * 2048 + k * 1024); } while (0)
; #define PG8_MMA(ai, bj, At, Bt) do { __builtin_amdgcn_s_setprio(1); _Pragma("unroll") for (int m = 0; m < 4; ++m) _Pragma("unroll") for (int n = 0; n < 2; ++n) _Pragma("unroll") for (int k = 0; k < 2; ++k) \
;         acc[ai][bj][m][n] = __builtin_amdgcn_mfma_f32_16x16x32_bf16(Bt[n][k], At[m][k], acc[ai][bj][m][n], 0, 0, 0); __builtin_amdgcn_s_setprio(0); } while (0)
; #define PG8_WAIT_V(n) asm volatile("s_waitcnt vmcnt(" #n ")" ::: "memory")
; #define PG8_WAIT_L(n) asm volatile("s_waitcnt lgkmcnt(" #n ")" ::: "memory")
; #define PG8_BAR __builtin_amdgcn_s_barrier()
; #define PG8_SCHED __builtin_amdgcn_sched_barrier(0)
; template <class Epi, class Sched, bool ALIGN_EPI = false, bool SP2 = false>
; __device__ __forceinline__ void gemm_phase(PG8_LAS unsigned char* lds, const Gemm g, const Sched& S, const Epi& E) {
;     ...
;             PG8_LDB(B0, 0, 0); PG8_LDB(B1, 0, 1); PG8_SCHED; PG8_LDA(At, 0, 0); PG8_STAGE(PG8_SA(1, 1), a1 + hstepA, voffA);
;             PG8_WAIT_V(8); PG8_WAIT_L(0); PG8_BAR; PG8_MMA(0, 0, At, B0); PG8_MMA(0, 1, At, B1); PG8_BAR; PG8_SCHED;
;             PG8_LDA(At, 0, 1); PG8_STAGE(PG8_SB(0, 0), b2, voffB); PG8_STAGE(PG8_SB(0, 1), b2 + hstepB, voffB); PG8_STAGE(PG8_SA(0, 0), a2, voffA);
.LBB0_338:
	ds_read_b128 v[150:153], v169
	ds_read_b128 v[154:157], v169 offset:1024
	ds_read_b128 v[158:161], v169 offset:2048
	ds_read_b128 v[162:165], v169 offset:3072
	ds_read_b128 v[174:177], v170
	ds_read_b128 v[178:181], v170 offset:1024
	ds_read_b128 v[182:185], v170 offset:2048
	ds_read_b128 v[186:189], v170 offset:3072
	s_add_i32 s64, s44, 2
	s_add_u32 s45, s42, 0x3fc000
	s_addc_u32 s46, s43, 0
	s_cmp_eq_u32 s57, s44
	s_cselect_b32 s48, s8, s45
	s_cselect_b32 s49, s7, s46
	s_cselect_b32 s46, s29, s31
	s_cselect_b32 s47, s9, s41
	s_add_u32 s44, s48, 0x400000
	s_addc_u32 s45, s49, 0
	v_lshl_add_u64 v[166:167], s[42:43], 0, v[138:139]
	s_add_i32 m0, s20, 0xc000
	ds_read_b128 v[190:193], v171
	ds_read_b128 v[194:197], v171 offset:1024
	ds_read_b128 v[198:201], v171 offset:2048
	ds_read_b128 v[202:205], v171 offset:3072
	ds_read_b128 v[206:209], v171 offset:4096
	ds_read_b128 v[210:213], v171 offset:5120
	ds_read_b128 v[214:217], v171 offset:6144
	ds_read_b128 v[218:221], v171 offset:7168
	global_load_lds_dwordx4 v[166:167], off
	v_lshl_add_u64 v[166:167], s[42:43], 0, v[140:141]
	s_add_i32 m0, s20, 0xe000
	s_nop 0
	global_load_lds_dwordx4 v[166:167], off
	s_waitcnt vmcnt(8)
	s_waitcnt lgkmcnt(0)
	s_barrier
	s_waitcnt lgkmcnt(0)
	v_mfma_f32_16x16x32_bf16 v[124:127], v[150:153], v[190:193], v[124:127]
	v_mfma_f32_16x16x32_bf16 v[120:123], v[158:161], v[190:193], v[120:123]
	v_mfma_f32_16x16x32_bf16 v[116:119], v[150:153], v[198:201], v[116:119]
	v_mfma_f32_16x16x32_bf16 v[112:115], v[158:161], v[198:201], v[112:115]
	v_mfma_f32_16x16x32_bf16 v[108:111], v[150:153], v[206:209], v[108:111]
	v_mfma_f32_16x16x32_bf16 v[104:107], v[158:161], v[206:209], v[104:107]
	v_mfma_f32_16x16x32_bf16 v[100:103], v[150:153], v[214:217], v[100:103]
	v_mfma_f32_16x16x32_bf16 v[96:99], v[158:161], v[214:217], v[96:99]
	v_mfma_f32_16x16x32_bf16 v[124:127], v[154:157], v[194:197], v[124:127]
	v_mfma_f32_16x16x32_bf16 v[120:123], v[162:165], v[194:197], v[120:123]
	v_mfma_f32_16x16x32_bf16 v[116:119], v[154:157], v[202:205], v[116:119]
	v_mfma_f32_16x16x32_bf16 v[112:115], v[162:165], v[202:205], v[112:115]
	v_mfma_f32_16x16x32_bf16 v[108:111], v[154:157], v[210:213], v[108:111]
	v_mfma_f32_16x16x32_bf16 v[104:107], v[162:165], v[210:213], v[104:107]
	v_mfma_f32_16x16x32_bf16 v[100:103], v[154:157], v[218:221], v[100:103]
	v_mfma_f32_16x16x32_bf16 v[96:99], v[162:165], v[218:221], v[96:99]
	v_mfma_f32_16x16x32_bf16 v[60:63], v[174:177], v[190:193], v[60:63]
	v_mfma_f32_16x16x32_bf16 v[56:59], v[182:185], v[190:193], v[56:59]
	v_mfma_f32_16x16x32_bf16 v[52:55], v[174:177], v[198:201], v[52:55]
	v_mfma_f32_16x16x32_bf16 v[48:51], v[182:185], v[198:201], v[48:51]
	v_mfma_f32_16x16x32_bf16 v[44:47], v[174:177], v[206:209], v[44:47]
	v_mfma_f32_16x16x32_bf16 v[40:43], v[182:185], v[206:209], v[40:43]
	v_mfma_f32_16x16x32_bf16 v[36:39], v[174:177], v[214:217], v[36:39]
	v_mfma_f32_16x16x32_bf16 v[32:35], v[182:185], v[214:217], v[32:35]
	v_mfma_f32_16x16x32_bf16 v[60:63], v[178:181], v[194:197], v[60:63]
	v_mfma_f32_16x16x32_bf16 v[56:59], v[186:189], v[194:197], v[56:59]
	v_mfma_f32_16x16x32_bf16 v[52:55], v[178:181], v[202:205], v[52:55]
	v_mfma_f32_16x16x32_bf16 v[48:51], v[186:189], v[202:205], v[48:51]
	v_mfma_f32_16x16x32_bf16 v[44:47], v[178:181], v[210:213], v[44:47]
	v_mfma_f32_16x16x32_bf16 v[40:43], v[186:189], v[210:213], v[40:43]
	v_mfma_f32_16x16x32_bf16 v[36:39], v[178:181], v[218:221], v[36:39]
	v_mfma_f32_16x16x32_bf16 v[32:35], v[186:189], v[218:221], v[32:35]
	s_barrier
	s_add_i32 s65, s62, s19
	v_lshl_add_u64 v[166:167], s[46:47], 0, v[130:131]
	s_mov_b32 m0, s65
	ds_read_b128 v[190:193], v171 offset:16384
	ds_read_b128 v[194:197], v171 offset:17408
	ds_read_b128 v[198:201], v171 offset:18432
	ds_read_b128 v[202:205], v171 offset:19456
	ds_read_b128 v[206:209], v171 offset:20480
	ds_read_b128 v[210:213], v171 offset:21504
	ds_read_b128 v[214:217], v171 offset:22528
	ds_read_b128 v[218:221], v171 offset:23552
	global_load_lds_dwordx4 v[166:167], off
	s_add_i32 m0, s65, 0x2000
	s_add_u32 s66, s46, 0x4000
	v_lshl_add_u64 v[166:167], s[46:47], 0, v[134:135]
	s_addc_u32 s67, s47, 0
	s_add_i32 s65, s63, s19
	global_load_lds_dwordx4 v[166:167], off
	v_lshl_add_u64 v[166:167], s[66:67], 0, v[130:131]
	s_mov_b32 m0, s65
	s_nop 0
	global_load_lds_dwordx4 v[166:167], off
	v_lshl_add_u64 v[166:167], s[66:67], 0, v[134:135]
	s_add_i32 m0, s65, 0x2000
	s_nop 0
	global_load_lds_dwordx4 v[166:167], off
	v_lshl_add_u64 v[166:167], s[48:49], 0, v[128:129]
	s_mov_b32 m0, s20
	s_nop 0
	global_load_lds_dwordx4 v[166:167], off
	v_lshl_add_u64 v[166:167], s[48:49], 0, v[132:133]
	s_mov_b32 m0, s21
	s_nop 0
	global_load_lds_dwordx4 v[166:167], off
	s_waitcnt vmcnt(8)
	s_waitcnt lgkmcnt(0)
	s_barrier
; #define PG8_STAGE(bufoff, gbase, voff) do { _Pragma("unroll") for (int _i = 0; _i < 2; ++_i) \
;         __builtin_amdgcn_global_load_lds((const unsigned*)((const char*)(gbase) + (voff)[_i]), (PG8_LAS unsigned*)(lds + (bufoff) + ldsw + _i * 8192), 16, 0, 0); } while (0)
; #define PG8_LDA(dst, b, h) do { _Pragma("unroll") for (int m = 0; m < 4; ++m) _Pragma("unroll") for (int k = 0; k < 2; ++k) dst[m][k] = *(const PG8_LAS bf16x8*)(lds + PG8_SA(b, h) + aoff + m * 2048 + k * 1024); } while (0)
; #define PG8_LDB(dst, b, h) do { _Pragma("unroll") for (int n = 0; n < 2; ++n) _Pragma("unroll") for (int k = 0; k < 2; ++k) dst[n][k] = *(const PG8_LAS bf16x8*)(lds + PG8_SB(b, h) + boff + n * 2048 + k * 1024); } while (0)
; #define PG8_MMA(ai, bj, At, Bt) do { __builtin_amdgcn_s_setprio(1); _Pragma("unroll") for (int m = 0; m < 4; ++m) _Pragma("unroll") for (int n = 0; n < 2; ++n) _Pragma("unroll") for (int k = 0; k < 2; ++k) \
;         acc[ai][bj][m][n] = __builtin_amdgcn_mfma_f32_16x16x32_bf16(Bt[n][k], At[m][k], acc[ai][bj][m][n], 0, 0, 0); __builtin_amdgcn_s_setprio(0); } while (0)
; #define PG8_WAIT_V(n) asm volatile("s_waitcnt vmcnt(" #n ")" ::: "memory")
; #define PG8_WAIT_L(n) asm volatile("s_waitcnt lgkmcnt(" #n ")" ::: "memory")
; #define PG8_BAR __builtin_amdgcn_s_barrier()
; #define PG8_SCHED __builtin_amdgcn_sched_barrier(0)
; template <class Epi, class Sched, bool ALIGN_EPI = false, bool SP2 = false>
; __device__ __forceinline__ void gemm_phase(PG8_LAS unsigned char* lds, const Gemm g, const Sched& S, const Epi& E) {
;     ...
;             PG8_WAIT_V(8); PG8_WAIT_L(0); PG8_BAR; PG8_MMA(1, 0, At, B0); PG8_MMA(1, 1, At, B1); PG8_BAR; PG8_SCHED;
;             PG8_LDB(B0, 1, 0); PG8_LDB(B1, 1, 1); PG8_SCHED; PG8_LDA(At, 1, 0); PG8_STAGE(PG8_SA(0, 1), a2 + hstepA, voffA);
;             PG8_WAIT_V(8); PG8_WAIT_L(0); PG8_BAR; PG8_MMA(0, 0, At, B0); PG8_MMA(0, 1, At, B1); PG8_BAR; PG8_SCHED;
	s_waitcnt lgkmcnt(0)
	v_mfma_f32_16x16x32_bf16 v[92:95], v[150:153], v[190:193], v[92:95]
	v_mfma_f32_16x16x32_bf16 v[88:91], v[158:161], v[190:193], v[88:91]
	v_mfma_f32_16x16x32_bf16 v[84:87], v[150:153], v[198:201], v[84:87]
	v_mfma_f32_16x16x32_bf16 v[80:83], v[158:161], v[198:201], v[80:83]
	v_mfma_f32_16x16x32_bf16 v[76:79], v[150:153], v[206:209], v[76:79]
	v_mfma_f32_16x16x32_bf16 v[72:75], v[158:161], v[206:209], v[72:75]
	v_mfma_f32_16x16x32_bf16 v[68:71], v[150:153], v[214:217], v[68:71]
	v_mfma_f32_16x16x32_bf16 v[64:67], v[158:161], v[214:217], v[64:67]
	v_mfma_f32_16x16x32_bf16 v[92:95], v[154:157], v[194:197], v[92:95]
	v_mfma_f32_16x16x32_bf16 v[88:91], v[162:165], v[194:197], v[88:91]
	v_mfma_f32_16x16x32_bf16 v[84:87], v[154:157], v[202:205], v[84:87]
	v_mfma_f32_16x16x32_bf16 v[80:83], v[162:165], v[202:205], v[80:83]
	v_mfma_f32_16x16x32_bf16 v[76:79], v[154:157], v[210:213], v[76:79]
	v_mfma_f32_16x16x32_bf16 v[72:75], v[162:165], v[210:213], v[72:75]
	v_mfma_f32_16x16x32_bf16 v[68:71], v[154:157], v[218:221], v[68:71]
	v_mfma_f32_16x16x32_bf16 v[64:67], v[162:165], v[218:221], v[64:67]
	v_mfma_f32_16x16x32_bf16 v[28:31], v[174:177], v[190:193], v[28:31]
	v_mfma_f32_16x16x32_bf16 v[24:27], v[182:185], v[190:193], v[24:27]
	v_mfma_f32_16x16x32_bf16 v[20:23], v[174:177], v[198:201], v[20:23]
	v_mfma_f32_16x16x32_bf16 v[16:19], v[182:185], v[198:201], v[16:19]
	v_mfma_f32_16x16x32_bf16 v[12:15], v[174:177], v[206:209], v[12:15]
	v_mfma_f32_16x16x32_bf16 v[8:11], v[182:185], v[206:209], v[8:11]
	v_mfma_f32_16x16x32_bf16 v[4:7], v[174:177], v[214:217], v[4:7]
	v_mfma_f32_16x16x32_bf16 v[0:3], v[182:185], v[214:217], v[0:3]
	v_mfma_f32_16x16x32_bf16 v[28:31], v[178:181], v[194:197], v[28:31]
	v_mfma_f32_16x16x32_bf16 v[24:27], v[186:189], v[194:197], v[24:27]
	v_mfma_f32_16x16x32_bf16 v[20:23], v[178:181], v[202:205], v[20:23]
	v_mfma_f32_16x16x32_bf16 v[16:19], v[186:189], v[202:205], v[16:19]
	v_mfma_f32_16x16x32_bf16 v[12:15], v[178:181], v[210:213], v[12:15]
	v_mfma_f32_16x16x32_bf16 v[8:11], v[186:189], v[210:213], v[8:11]
	v_mfma_f32_16x16x32_bf16 v[4:7], v[178:181], v[218:221], v[4:7]
	v_mfma_f32_16x16x32_bf16 v[0:3], v[186:189], v[218:221], v[0:3]
	s_barrier
	s_add_i32 s65, 0, 0x18000
	v_add_u32_e32 v137, s65, v168
	s_add_i32 s66, 0, 0x1c000
	ds_read_b128 v[150:153], v137
	ds_read_b128 v[154:157], v137 offset:1024
	ds_read_b128 v[158:161], v137 offset:2048
	ds_read_b128 v[162:165], v137 offset:3072
	v_add_u32_e32 v137, s66, v168
	ds_read_b128 v[174:177], v137
	ds_read_b128 v[178:181], v137 offset:1024
	ds_read_b128 v[182:185], v137 offset:2048
	ds_read_b128 v[186:189], v137 offset:3072
	s_add_u32 s48, s48, 0x4000
	s_addc_u32 s49, s49, 0
	s_mov_b32 m0, s33
	v_lshl_add_u64 v[166:167], s[48:49], 0, v[128:129]
	ds_read_b128 v[190:193], v171 offset:32768
	ds_read_b128 v[194:197], v171 offset:33792
	ds_read_b128 v[198:201], v171 offset:34816
	ds_read_b128 v[202:205], v171 offset:35840
	ds_read_b128 v[206:209], v171 offset:36864
	ds_read_b128 v[210:213], v171 offset:37888
	ds_read_b128 v[214:217], v171 offset:38912
	ds_read_b128 v[218:221], v171 offset:39936
	global_load_lds_dwordx4 v[166:167], off
	v_lshl_add_u64 v[166:167], s[48:49], 0, v[132:133]
	s_mov_b32 m0, s50
	s_nop 0
	global_load_lds_dwordx4 v[166:167], off
	s_waitcnt vmcnt(8)
	s_waitcnt lgkmcnt(0)
	s_barrier
	s_waitcnt lgkmcnt(0)
	v_mfma_f32_16x16x32_bf16 v[124:127], v[150:153], v[190:193], v[124:127]
	v_mfma_f32_16x16x32_bf16 v[120:123], v[158:161], v[190:193], v[120:123]
	v_mfma_f32_16x16x32_bf16 v[116:119], v[150:153], v[198:201], v[116:119]
	v_mfma_f32_16x16x32_bf16 v[112:115], v[158:161], v[198:201], v[112:115]
	v_mfma_f32_16x16x32_bf16 v[108:111], v[150:153], v[206:209], v[108:111]
	v_mfma_f32_16x16x32_bf16 v[104:107], v[158:161], v[206:209], v[104:107]
	v_mfma_f32_16x16x32_bf16 v[100:103], v[150:153], v[214:217], v[100:103]
	v_mfma_f32_16x16x32_bf16 v[96:99], v[158:161], v[214:217], v[96:99]
	v_mfma_f32_16x16x32_bf16 v[124:127], v[154:157], v[194:197], v[124:127]
	v_mfma_f32_16x16x32_bf16 v[120:123], v[162:165], v[194:197], v[120:123]
	v_mfma_f32_16x16x32_bf16 v[116:119], v[154:157], v[202:205], v[116:119]
	v_mfma_f32_16x16x32_bf16 v[112:115], v[162:165], v[202:205], v[112:115]
	v_mfma_f32_16x16x32_bf16 v[108:111], v[154:157], v[210:213], v[108:111]
	v_mfma_f32_16x16x32_bf16 v[104:107], v[162:165], v[210:213], v[104:107]
	v_mfma_f32_16x16x32_bf16 v[100:103], v[154:157], v[218:221], v[100:103]
	v_mfma_f32_16x16x32_bf16 v[96:99], v[162:165], v[218:221], v[96:99]
	v_mfma_f32_16x16x32_bf16 v[60:63], v[174:177], v[190:193], v[60:63]
	v_mfma_f32_16x16x32_bf16 v[56:59], v[182:185], v[190:193], v[56:59]
	v_mfma_f32_16x16x32_bf16 v[52:55], v[174:177], v[198:201], v[52:55]
	v_mfma_f32_16x16x32_bf16 v[48:51], v[182:185], v[198:201], v[48:51]
	v_mfma_f32_16x16x32_bf16 v[44:47], v[174:177], v[206:209], v[44:47]
	v_mfma_f32_16x16x32_bf16 v[40:43], v[182:185], v[206:209], v[40:43]
	v_mfma_f32_16x16x32_bf16 v[36:39], v[174:177], v[214:217], v[36:39]
	v_mfma_f32_16x16x32_bf16 v[32:35], v[182:185], v[214:217], v[32:35]
	v_mfma_f32_16x16x32_bf16 v[60:63], v[178:181], v[194:197], v[60:63]
	v_mfma_f32_16x16x32_bf16 v[56:59], v[186:189], v[194:197], v[56:59]
	v_mfma_f32_16x16x32_bf16 v[52:55], v[178:181], v[202:205], v[52:55]
	v_mfma_f32_16x16x32_bf16 v[48:51], v[186:189], v[202:205], v[48:51]
	v_mfma_f32_16x16x32_bf16 v[44:47], v[178:181], v[210:213], v[44:47]
	v_mfma_f32_16x16x32_bf16 v[40:43], v[186:189], v[210:213], v[40:43]
	v_mfma_f32_16x16x32_bf16 v[36:39], v[178:181], v[218:221], v[36:39]
	v_mfma_f32_16x16x32_bf16 v[32:35], v[186:189], v[218:221], v[32:35]
	s_barrier
; #define PG8_STAGE(bufoff, gbase, voff) do { _Pragma("unroll") for (int _i = 0; _i < 2; ++_i) \
;         __builtin_amdgcn_global_load_lds((const unsigned*)((const char*)(gbase) + (voff)[_i]), (PG8_LAS unsigned*)(lds + (bufoff) + ldsw + _i * 8192), 16, 0, 0); } while (0)
; #define PG8_LDA(dst, b, h) do { _Pragma("unroll") for (int m = 0; m < 4; ++m) _Pragma("unroll") for (int k = 0; k < 2; ++k) dst[m][k] = *(const PG8_LAS bf16x8*)(lds + PG8_SA(b, h) + aoff + m * 2048 + k * 1024); } while (0)
; #define PG8_MMA(ai, bj, At, Bt) do { __builtin_amdgcn_s_setprio(1); _Pragma("unroll") for (int m = 0; m < 4; ++m) _Pragma("unroll") for (int n = 0; n < 2; ++n) _Pragma("unroll") for (int k = 0; k < 2; ++k) \
;         acc[ai][bj][m][n] = __builtin_amdgcn_mfma_f32_16x16x32_bf16(Bt[n][k], At[m][k], acc[ai][bj][m][n], 0, 0, 0); __builtin_amdgcn_s_setprio(0); } while (0)
; #define PG8_WAIT_V(n) asm volatile("s_waitcnt vmcnt(" #n ")" ::: "memory")
; #define PG8_WAIT_L(n) asm volatile("s_waitcnt lgkmcnt(" #n ")" ::: "memory")
; #define PG8_BAR __builtin_amdgcn_s_barrier()
; #define PG8_SCHED __builtin_amdgcn_sched_barrier(0)
; template <class Epi, class Sched, bool ALIGN_EPI = false, bool SP2 = false>
; __device__ __forceinline__ void gemm_phase(PG8_LAS unsigned char* lds, const Gemm g, const Sched& S, const Epi& E) {
;     ...
;         for (int t = 0; t < nt; t += 2) {
;     ...
;             PG8_LDA(At, 1, 1); PG8_STAGE(PG8_SB(1, 0), b3, voffB); PG8_STAGE(PG8_SB(1, 1), b3 + hstepB, voffB); PG8_STAGE(PG8_SA(1, 0), a3, voffA);
;             PG8_WAIT_V(8); PG8_WAIT_L(0); PG8_BAR; PG8_MMA(1, 0, At, B0); PG8_MMA(1, 1, At, B1); PG8_BAR; PG8_SCHED;
	s_add_u32 s48, s46, 0x20000
	s_addc_u32 s49, s47, 0
	s_add_i32 s65, s65, s19
	v_lshl_add_u64 v[166:167], s[48:49], 0, v[130:131]
	s_mov_b32 m0, s65
	ds_read_b128 v[190:193], v171 offset:49152
	ds_read_b128 v[194:197], v171 offset:50176
	ds_read_b128 v[198:201], v171 offset:51200
	ds_read_b128 v[202:205], v171 offset:52224
	ds_read_b128 v[206:209], v171 offset:53248
	ds_read_b128 v[210:213], v171 offset:54272
	ds_read_b128 v[214:217], v171 offset:55296
	ds_read_b128 v[218:221], v171 offset:56320
	global_load_lds_dwordx4 v[166:167], off
	s_add_i32 m0, s65, 0x2000
	s_add_u32 s46, s46, 0x24000
	v_lshl_add_u64 v[166:167], s[48:49], 0, v[134:135]
	s_addc_u32 s47, s47, 0
	s_add_i32 s48, s66, s19
	global_load_lds_dwordx4 v[166:167], off
	v_lshl_add_u64 v[166:167], s[46:47], 0, v[130:131]
	s_mov_b32 m0, s48
	s_nop 0
	global_load_lds_dwordx4 v[166:167], off
	v_lshl_add_u64 v[166:167], s[46:47], 0, v[134:135]
	s_add_i32 m0, s48, 0x2000
	s_nop 0
	global_load_lds_dwordx4 v[166:167], off
	v_lshl_add_u64 v[166:167], s[44:45], 0, v[128:129]
	s_mov_b32 m0, s55
	s_nop 0
	global_load_lds_dwordx4 v[166:167], off
	v_lshl_add_u64 v[166:167], s[44:45], 0, v[132:133]
	s_mov_b32 m0, s56
	s_nop 0
	global_load_lds_dwordx4 v[166:167], off
	s_waitcnt vmcnt(8)
	s_waitcnt lgkmcnt(0)
	s_barrier
	s_waitcnt lgkmcnt(0)
	v_mfma_f32_16x16x32_bf16 v[92:95], v[150:153], v[190:193], v[92:95]
	v_mfma_f32_16x16x32_bf16 v[88:91], v[158:161], v[190:193], v[88:91]
	v_mfma_f32_16x16x32_bf16 v[84:87], v[150:153], v[198:201], v[84:87]
	v_mfma_f32_16x16x32_bf16 v[80:83], v[158:161], v[198:201], v[80:83]
	v_mfma_f32_16x16x32_bf16 v[76:79], v[150:153], v[206:209], v[76:79]
	v_mfma_f32_16x16x32_bf16 v[72:75], v[158:161], v[206:209], v[72:75]
	v_mfma_f32_16x16x32_bf16 v[68:71], v[150:153], v[214:217], v[68:71]
	v_mfma_f32_16x16x32_bf16 v[64:67], v[158:161], v[214:217], v[64:67]
	v_mfma_f32_16x16x32_bf16 v[92:95], v[154:157], v[194:197], v[92:95]
	v_mfma_f32_16x16x32_bf16 v[88:91], v[162:165], v[194:197], v[88:91]
	v_mfma_f32_16x16x32_bf16 v[84:87], v[154:157], v[202:205], v[84:87]
	v_mfma_f32_16x16x32_bf16 v[80:83], v[162:165], v[202:205], v[80:83]
	v_mfma_f32_16x16x32_bf16 v[76:79], v[154:157], v[210:213], v[76:79]
	v_mfma_f32_16x16x32_bf16 v[72:75], v[162:165], v[210:213], v[72:75]
	v_mfma_f32_16x16x32_bf16 v[68:71], v[154:157], v[218:221], v[68:71]
	v_mfma_f32_16x16x32_bf16 v[64:67], v[162:165], v[218:221], v[64:67]
	v_mfma_f32_16x16x32_bf16 v[28:31], v[174:177], v[190:193], v[28:31]
	v_mfma_f32_16x16x32_bf16 v[24:27], v[182:185], v[190:193], v[24:27]
	v_mfma_f32_16x16x32_bf16 v[20:23], v[174:177], v[198:201], v[20:23]
	v_mfma_f32_16x16x32_bf16 v[16:19], v[182:185], v[198:201], v[16:19]
	v_mfma_f32_16x16x32_bf16 v[12:15], v[174:177], v[206:209], v[12:15]
	v_mfma_f32_16x16x32_bf16 v[8:11], v[182:185], v[206:209], v[8:11]
	v_mfma_f32_16x16x32_bf16 v[4:7], v[174:177], v[214:217], v[4:7]
	v_mfma_f32_16x16x32_bf16 v[0:3], v[182:185], v[214:217], v[0:3]
	v_mfma_f32_16x16x32_bf16 v[28:31], v[178:181], v[194:197], v[28:31]
	v_mfma_f32_16x16x32_bf16 v[24:27], v[186:189], v[194:197], v[24:27]
	v_mfma_f32_16x16x32_bf16 v[20:23], v[178:181], v[202:205], v[20:23]
	v_mfma_f32_16x16x32_bf16 v[16:19], v[186:189], v[202:205], v[16:19]
	v_mfma_f32_16x16x32_bf16 v[12:15], v[178:181], v[210:213], v[12:15]
	v_mfma_f32_16x16x32_bf16 v[8:11], v[186:189], v[210:213], v[8:11]
	v_mfma_f32_16x16x32_bf16 v[4:7], v[178:181], v[218:221], v[4:7]
	v_mfma_f32_16x16x32_bf16 v[0:3], v[186:189], v[218:221], v[0:3]
	s_barrier
	s_add_u32 s31, s31, 0x40000
	s_addc_u32 s41, s41, 0
	s_add_u32 s42, s42, 0x800000
	s_addc_u32 s43, s43, 0
	s_cmp_ge_i32 s64, s52
	s_mov_b32 s44, s64
	s_cbranch_scc0 .LBB0_338

; #define PG8_STAGE(bufoff, gbase, voff) do { _Pragma("unroll") for (int _i = 0; _i < 2; ++_i) \
;         __builtin_amdgcn_global_load_lds((const unsigned*)((const char*)(gbase) + (voff)[_i]), (PG8_LAS unsigned*)(lds + (bufoff) + ldsw + _i * 8192), 16, 0, 0); } while (0)
; #define PG8_LDA(dst, b, h) do { _Pragma("unroll") for (int m = 0; m < 4; ++m) _Pragma("unroll") for (int k = 0; k < 2; ++k) dst[m][k] = *(const PG8_LAS bf16x8*)(lds + PG8_SA(b, h) + aoff + m * 2048 + k * 1024); } while (0)
; #define PG8_LDB(dst, b, h) do { _Pragma("unroll") for (int n = 0; n < 2; ++n) _Pragma("unroll") for (int k = 0; k < 2; ++k) dst[n][k] = *(const PG8_LAS bf16x8*)(lds + PG8_SB(b, h) + boff + n * 2048 + k * 1024); } while (0)
; #define PG8_MMA(ai, bj, At, Bt) do { __builtin_amdgcn_s_setprio(1); _Pragma("unroll") for (int m = 0; m < 4; ++m) _Pragma("unroll") for (int n = 0; n < 2; ++n) _Pragma("unroll") for (int k = 0; k < 2; ++k) \
;         acc[ai][bj][m][n] = __builtin_amdgcn_mfma_f32_16x16x32_bf16(Bt[n][k], At[m][k], acc[ai][bj][m][n], 0, 0, 0); __builtin_amdgcn_s_setprio(0); } while (0)
; #define PG8_WAIT_V(n) asm volatile("s_waitcnt vmcnt(" #n ")" ::: "memory")
; #define PG8_WAIT_L(n) asm volatile("s_waitcnt lgkmcnt(" #n ")" ::: "memory")
; #define PG8_BAR __builtin_amdgcn_s_barrier()
; #define PG8_SCHED __builtin_amdgcn_sched_barrier(0)
; template <class Epi, class Sched, bool ALIGN_EPI = false, bool SP2 = false>
; __device__ __forceinline__ void gemm_phase(PG8_LAS unsigned char* lds, const Gemm g, const Sched& S, const Epi& E) {
;     ...
;             PG8_LDB(B0, 0, 0); PG8_LDB(B1, 0, 1); PG8_SCHED; PG8_LDA(At, 0, 0); PG8_STAGE(PG8_SA(1, 1), a1 + hstepA, voffA);
;             PG8_WAIT_V(8); PG8_WAIT_L(0); PG8_BAR; PG8_MMA(0, 0, At, B0); PG8_MMA(0, 1, At, B1); PG8_BAR; PG8_SCHED;
;             PG8_LDA(At, 0, 1); PG8_STAGE(PG8_SB(0, 0), b2, voffB); PG8_STAGE(PG8_SB(0, 1), b2 + hstepB, voffB); PG8_STAGE(PG8_SA(0, 0), a2, voffA);
.LBB0_433:
	ds_read_b128 v[128:131], v199
	ds_read_b128 v[132:135], v199 offset:1024
	ds_read_b128 v[136:139], v199 offset:2048
	ds_read_b128 v[140:143], v199 offset:3072
	ds_read_b128 v[144:147], v205
	ds_read_b128 v[148:151], v205 offset:1024
	ds_read_b128 v[152:155], v205 offset:2048
	ds_read_b128 v[156:159], v205 offset:3072
	s_add_i32 s68, s52, 2
	s_add_u32 s53, s50, 0xfffc0080
	s_addc_u32 s54, s51, -1
	s_cmp_eq_u32 s61, s52
	s_cselect_b32 s52, s41, s47
	s_cselect_b32 s55, s8, s54
	s_cselect_b32 s54, s9, s53
	s_cselect_b32 s53, s37, s67
	v_lshl_add_u64 v[196:197], s[50:51], 0, v[170:171]
	s_add_i32 m0, s18, 0xc000
	ds_read_b128 v[178:181], v213
	ds_read_b128 v[184:187], v213 offset:1024
	ds_read_b128 v[190:193], v213 offset:2048
	ds_read_b128 v[200:203], v213 offset:3072
	ds_read_b128 v[206:209], v213 offset:4096
	ds_read_b128 v[214:217], v213 offset:5120
	ds_read_b128 v[220:223], v213 offset:6144
	ds_read_b128 v[226:229], v213 offset:7168
	global_load_lds_dwordx4 v[196:197], off
	v_lshl_add_u64 v[196:197], s[50:51], 0, v[172:173]
	s_add_i32 m0, s18, 0xe000
	s_nop 0
	global_load_lds_dwordx4 v[196:197], off
	s_waitcnt vmcnt(8)
	s_waitcnt lgkmcnt(0)
	s_barrier
	s_waitcnt lgkmcnt(0)
	v_mfma_f32_16x16x32_bf16 v[124:127], v[128:131], v[178:181], v[124:127]
	v_mfma_f32_16x16x32_bf16 v[120:123], v[136:139], v[178:181], v[120:123]
	v_mfma_f32_16x16x32_bf16 v[108:111], v[128:131], v[190:193], v[108:111]
	v_mfma_f32_16x16x32_bf16 v[104:107], v[136:139], v[190:193], v[104:107]
	v_mfma_f32_16x16x32_bf16 v[92:95], v[128:131], v[206:209], v[92:95]
	v_mfma_f32_16x16x32_bf16 v[88:91], v[136:139], v[206:209], v[88:91]
	v_mfma_f32_16x16x32_bf16 v[76:79], v[128:131], v[220:223], v[76:79]
	v_mfma_f32_16x16x32_bf16 v[72:75], v[136:139], v[220:223], v[72:75]
	v_mfma_f32_16x16x32_bf16 v[124:127], v[132:135], v[184:187], v[124:127]
	v_mfma_f32_16x16x32_bf16 v[120:123], v[140:143], v[184:187], v[120:123]
	v_mfma_f32_16x16x32_bf16 v[108:111], v[132:135], v[200:203], v[108:111]
	v_mfma_f32_16x16x32_bf16 v[104:107], v[140:143], v[200:203], v[104:107]
	v_mfma_f32_16x16x32_bf16 v[92:95], v[132:135], v[214:217], v[92:95]
	v_mfma_f32_16x16x32_bf16 v[88:91], v[140:143], v[214:217], v[88:91]
	v_mfma_f32_16x16x32_bf16 v[76:79], v[132:135], v[226:229], v[76:79]
	v_mfma_f32_16x16x32_bf16 v[72:75], v[140:143], v[226:229], v[72:75]
	v_mfma_f32_16x16x32_bf16 v[116:119], v[144:147], v[178:181], v[116:119]
	v_mfma_f32_16x16x32_bf16 v[112:115], v[152:155], v[178:181], v[112:115]
	v_mfma_f32_16x16x32_bf16 v[100:103], v[144:147], v[190:193], v[100:103]
	v_mfma_f32_16x16x32_bf16 v[96:99], v[152:155], v[190:193], v[96:99]
	v_mfma_f32_16x16x32_bf16 v[84:87], v[144:147], v[206:209], v[84:87]
	v_mfma_f32_16x16x32_bf16 v[80:83], v[152:155], v[206:209], v[80:83]
	v_mfma_f32_16x16x32_bf16 v[68:71], v[144:147], v[220:223], v[68:71]
	v_mfma_f32_16x16x32_bf16 v[64:67], v[152:155], v[220:223], v[64:67]
	v_mfma_f32_16x16x32_bf16 v[116:119], v[148:151], v[184:187], v[116:119]
	v_mfma_f32_16x16x32_bf16 v[112:115], v[156:159], v[184:187], v[112:115]
	v_mfma_f32_16x16x32_bf16 v[100:103], v[148:151], v[200:203], v[100:103]
	v_mfma_f32_16x16x32_bf16 v[96:99], v[156:159], v[200:203], v[96:99]
	v_mfma_f32_16x16x32_bf16 v[84:87], v[148:151], v[214:217], v[84:87]
	v_mfma_f32_16x16x32_bf16 v[80:83], v[156:159], v[214:217], v[80:83]
	v_mfma_f32_16x16x32_bf16 v[68:71], v[148:151], v[226:229], v[68:71]
	v_mfma_f32_16x16x32_bf16 v[64:67], v[156:159], v[226:229], v[64:67]
	s_barrier
	s_add_i32 s69, s65, s17
	v_lshl_add_u64 v[196:197], s[52:53], 0, v[162:163]
	s_mov_b32 m0, s69
	ds_read_b128 v[178:181], v213 offset:16384
	ds_read_b128 v[184:187], v213 offset:17408
	ds_read_b128 v[190:193], v213 offset:18432
	ds_read_b128 v[200:203], v213 offset:19456
	ds_read_b128 v[206:209], v213 offset:20480
	ds_read_b128 v[214:217], v213 offset:21504
	ds_read_b128 v[220:223], v213 offset:22528
	ds_read_b128 v[226:229], v213 offset:23552
	global_load_lds_dwordx4 v[196:197], off
	s_add_i32 m0, s69, 0x2000
	s_add_u32 s70, s52, 0x40000
	v_lshl_add_u64 v[210:211], s[52:53], 0, v[166:167]
	s_addc_u32 s71, s53, 0
	s_add_i32 s69, s66, s17
	global_load_lds_dwordx4 v[210:211], off
	v_lshl_add_u64 v[230:231], s[70:71], 0, v[162:163]
	s_mov_b32 m0, s69
	v_lshl_add_u64 v[232:233], s[54:55], 0, v[164:165]
	global_load_lds_dwordx4 v[230:231], off
	v_lshl_add_u64 v[230:231], s[70:71], 0, v[166:167]
	s_add_i32 m0, s69, 0x2000
	s_nop 0
	global_load_lds_dwordx4 v[230:231], off
	v_lshl_add_u64 v[230:231], s[54:55], 0, v[160:161]
	s_mov_b32 m0, s18
	s_nop 0
	global_load_lds_dwordx4 v[230:231], off
	s_mov_b32 m0, s19
	s_nop 0
	global_load_lds_dwordx4 v[232:233], off
	s_waitcnt vmcnt(8)
	s_waitcnt lgkmcnt(0)
	s_barrier
; #define PG8_STAGE(bufoff, gbase, voff) do { _Pragma("unroll") for (int _i = 0; _i < 2; ++_i) \
;         __builtin_amdgcn_global_load_lds((const unsigned*)((const char*)(gbase) + (voff)[_i]), (PG8_LAS unsigned*)(lds + (bufoff) + ldsw + _i * 8192), 16, 0, 0); } while (0)
; #define PG8_LDA(dst, b, h) do { _Pragma("unroll") for (int m = 0; m < 4; ++m) _Pragma("unroll") for (int k = 0; k < 2; ++k) dst[m][k] = *(const PG8_LAS bf16x8*)(lds + PG8_SA(b, h) + aoff + m * 2048 + k * 1024); } while (0)
; #define PG8_LDB(dst, b, h) do { _Pragma("unroll") for (int n = 0; n < 2; ++n) _Pragma("unroll") for (int k = 0; k < 2; ++k) dst[n][k] = *(const PG8_LAS bf16x8*)(lds + PG8_SB(b, h) + boff + n * 2048 + k * 1024); } while (0)
; #define PG8_MMA(ai, bj, At, Bt) do { __builtin_amdgcn_s_setprio(1); _Pragma("unroll") for (int m = 0; m < 4; ++m) _Pragma("unroll") for (int n = 0; n < 2; ++n) _Pragma("unroll") for (int k = 0; k < 2; ++k) \
;         acc[ai][bj][m][n] = __builtin_amdgcn_mfma_f32_16x16x32_bf16(Bt[n][k], At[m][k], acc[ai][bj][m][n], 0, 0, 0); __builtin_amdgcn_s_setprio(0); } while (0)
; #define PG8_WAIT_V(n) asm volatile("s_waitcnt vmcnt(" #n ")" ::: "memory")
; #define PG8_WAIT_L(n) asm volatile("s_waitcnt lgkmcnt(" #n ")" ::: "memory")
; #define PG8_BAR __builtin_amdgcn_s_barrier()
; #define PG8_SCHED __builtin_amdgcn_sched_barrier(0)
; template <class Epi, class Sched, bool ALIGN_EPI = false, bool SP2 = false>
; __device__ __forceinline__ void gemm_phase(PG8_LAS unsigned char* lds, const Gemm g, const Sched& S, const Epi& E) {
;     ...
;             PG8_WAIT_V(8); PG8_WAIT_L(0); PG8_BAR; PG8_MMA(1, 0, At, B0); PG8_MMA(1, 1, At, B1); PG8_BAR; PG8_SCHED;
;             PG8_LDB(B0, 1, 0); PG8_LDB(B1, 1, 1); PG8_SCHED; PG8_LDA(At, 1, 0); PG8_STAGE(PG8_SA(0, 1), a2 + hstepA, voffA);
;             PG8_WAIT_V(8); PG8_WAIT_L(0); PG8_BAR; PG8_MMA(0, 0, At, B0); PG8_MMA(0, 1, At, B1); PG8_BAR; PG8_SCHED;
	s_waitcnt lgkmcnt(0)
	v_mfma_f32_16x16x32_bf16 v[60:63], v[128:131], v[178:181], v[60:63]
	v_mfma_f32_16x16x32_bf16 v[56:59], v[136:139], v[178:181], v[56:59]
	v_mfma_f32_16x16x32_bf16 v[44:47], v[128:131], v[190:193], v[44:47]
	v_mfma_f32_16x16x32_bf16 v[40:43], v[136:139], v[190:193], v[40:43]
	v_mfma_f32_16x16x32_bf16 v[28:31], v[128:131], v[206:209], v[28:31]
	v_mfma_f32_16x16x32_bf16 v[24:27], v[136:139], v[206:209], v[24:27]
	v_mfma_f32_16x16x32_bf16 v[12:15], v[128:131], v[220:223], v[12:15]
	v_mfma_f32_16x16x32_bf16 v[8:11], v[136:139], v[220:223], v[8:11]
	v_mfma_f32_16x16x32_bf16 v[60:63], v[132:135], v[184:187], v[60:63]
	v_mfma_f32_16x16x32_bf16 v[56:59], v[140:143], v[184:187], v[56:59]
	v_mfma_f32_16x16x32_bf16 v[44:47], v[132:135], v[200:203], v[44:47]
	v_mfma_f32_16x16x32_bf16 v[40:43], v[140:143], v[200:203], v[40:43]
	v_mfma_f32_16x16x32_bf16 v[28:31], v[132:135], v[214:217], v[28:31]
	v_mfma_f32_16x16x32_bf16 v[24:27], v[140:143], v[214:217], v[24:27]
	v_mfma_f32_16x16x32_bf16 v[12:15], v[132:135], v[226:229], v[12:15]
	v_mfma_f32_16x16x32_bf16 v[8:11], v[140:143], v[226:229], v[8:11]
	v_mfma_f32_16x16x32_bf16 v[52:55], v[144:147], v[178:181], v[52:55]
	v_mfma_f32_16x16x32_bf16 v[48:51], v[152:155], v[178:181], v[48:51]
	v_mfma_f32_16x16x32_bf16 v[36:39], v[144:147], v[190:193], v[36:39]
	v_mfma_f32_16x16x32_bf16 v[32:35], v[152:155], v[190:193], v[32:35]
	v_mfma_f32_16x16x32_bf16 v[20:23], v[144:147], v[206:209], v[20:23]
	v_mfma_f32_16x16x32_bf16 v[16:19], v[152:155], v[206:209], v[16:19]
	v_mfma_f32_16x16x32_bf16 v[4:7], v[144:147], v[220:223], v[4:7]
	v_mfma_f32_16x16x32_bf16 v[0:3], v[152:155], v[220:223], v[0:3]
	v_mfma_f32_16x16x32_bf16 v[52:55], v[148:151], v[184:187], v[52:55]
	v_mfma_f32_16x16x32_bf16 v[48:51], v[156:159], v[184:187], v[48:51]
	v_mfma_f32_16x16x32_bf16 v[36:39], v[148:151], v[200:203], v[36:39]
	v_mfma_f32_16x16x32_bf16 v[32:35], v[156:159], v[200:203], v[32:35]
	v_mfma_f32_16x16x32_bf16 v[20:23], v[148:151], v[214:217], v[20:23]
	v_mfma_f32_16x16x32_bf16 v[16:19], v[156:159], v[214:217], v[16:19]
	v_mfma_f32_16x16x32_bf16 v[4:7], v[148:151], v[226:229], v[4:7]
	v_mfma_f32_16x16x32_bf16 v[0:3], v[156:159], v[226:229], v[0:3]
	s_barrier
	s_add_i32 s69, 0, 0x18000
	s_add_i32 s70, 0, 0x1c000
	v_add_u32_e32 v140, s69, v195
	v_add_u32_e32 v156, s70, v195
	ds_read_b128 v[128:131], v140
	ds_read_b128 v[132:135], v140 offset:1024
	ds_read_b128 v[136:139], v140 offset:2048
	ds_read_b128 v[140:143], v140 offset:3072
	ds_read_b128 v[144:147], v156
	ds_read_b128 v[148:151], v156 offset:1024
	ds_read_b128 v[152:155], v156 offset:2048
	ds_read_b128 v[156:159], v156 offset:3072
	s_add_u32 s54, s54, 0x40000
	s_addc_u32 s55, s55, 0
	s_mov_b32 m0, s20
	v_lshl_add_u64 v[234:235], s[54:55], 0, v[160:161]
	ds_read_b128 v[178:181], v213 offset:32768
	ds_read_b128 v[184:187], v213 offset:33792
	ds_read_b128 v[190:193], v213 offset:34816
	ds_read_b128 v[200:203], v213 offset:35840
	ds_read_b128 v[206:209], v213 offset:36864
	ds_read_b128 v[214:217], v213 offset:37888
	ds_read_b128 v[220:223], v213 offset:38912
	ds_read_b128 v[226:229], v213 offset:39936
	global_load_lds_dwordx4 v[234:235], off
	v_lshl_add_u64 v[234:235], s[54:55], 0, v[164:165]
	s_mov_b32 m0, s21
	s_nop 0
	global_load_lds_dwordx4 v[234:235], off
	s_waitcnt vmcnt(8)
	s_waitcnt lgkmcnt(0)
	s_barrier
	s_waitcnt lgkmcnt(0)
	v_mfma_f32_16x16x32_bf16 v[124:127], v[128:131], v[178:181], v[124:127]
	v_mfma_f32_16x16x32_bf16 v[120:123], v[136:139], v[178:181], v[120:123]
	v_mfma_f32_16x16x32_bf16 v[108:111], v[128:131], v[190:193], v[108:111]
	v_mfma_f32_16x16x32_bf16 v[104:107], v[136:139], v[190:193], v[104:107]
	v_mfma_f32_16x16x32_bf16 v[92:95], v[128:131], v[206:209], v[92:95]
	v_mfma_f32_16x16x32_bf16 v[88:91], v[136:139], v[206:209], v[88:91]
	v_mfma_f32_16x16x32_bf16 v[76:79], v[128:131], v[220:223], v[76:79]
	v_mfma_f32_16x16x32_bf16 v[72:75], v[136:139], v[220:223], v[72:75]
	v_mfma_f32_16x16x32_bf16 v[124:127], v[132:135], v[184:187], v[124:127]
	v_mfma_f32_16x16x32_bf16 v[120:123], v[140:143], v[184:187], v[120:123]
	v_mfma_f32_16x16x32_bf16 v[108:111], v[132:135], v[200:203], v[108:111]
	v_mfma_f32_16x16x32_bf16 v[104:107], v[140:143], v[200:203], v[104:107]
	v_mfma_f32_16x16x32_bf16 v[92:95], v[132:135], v[214:217], v[92:95]
	v_mfma_f32_16x16x32_bf16 v[88:91], v[140:143], v[214:217], v[88:91]
	v_mfma_f32_16x16x32_bf16 v[76:79], v[132:135], v[226:229], v[76:79]
	v_mfma_f32_16x16x32_bf16 v[72:75], v[140:143], v[226:229], v[72:75]
	v_mfma_f32_16x16x32_bf16 v[116:119], v[144:147], v[178:181], v[116:119]
	v_mfma_f32_16x16x32_bf16 v[112:115], v[152:155], v[178:181], v[112:115]
	v_mfma_f32_16x16x32_bf16 v[100:103], v[144:147], v[190:193], v[100:103]
	v_mfma_f32_16x16x32_bf16 v[96:99], v[152:155], v[190:193], v[96:99]
	v_mfma_f32_16x16x32_bf16 v[84:87], v[144:147], v[206:209], v[84:87]
	v_mfma_f32_16x16x32_bf16 v[80:83], v[152:155], v[206:209], v[80:83]
	v_mfma_f32_16x16x32_bf16 v[68:71], v[144:147], v[220:223], v[68:71]
	v_mfma_f32_16x16x32_bf16 v[64:67], v[152:155], v[220:223], v[64:67]
	v_mfma_f32_16x16x32_bf16 v[116:119], v[148:151], v[184:187], v[116:119]
	v_mfma_f32_16x16x32_bf16 v[112:115], v[156:159], v[184:187], v[112:115]
	v_mfma_f32_16x16x32_bf16 v[100:103], v[148:151], v[200:203], v[100:103]
	v_mfma_f32_16x16x32_bf16 v[96:99], v[156:159], v[200:203], v[96:99]
	v_mfma_f32_16x16x32_bf16 v[84:87], v[148:151], v[214:217], v[84:87]
	v_mfma_f32_16x16x32_bf16 v[80:83], v[156:159], v[214:217], v[80:83]
	v_mfma_f32_16x16x32_bf16 v[68:71], v[148:151], v[226:229], v[68:71]
	v_mfma_f32_16x16x32_bf16 v[64:67], v[156:159], v[226:229], v[64:67]
	s_barrier
; #define PG8_STAGE(bufoff, gbase, voff) do { _Pragma("unroll") for (int _i = 0; _i < 2; ++_i) \
;         __builtin_amdgcn_global_load_lds((const unsigned*)((const char*)(gbase) + (voff)[_i]), (PG8_LAS unsigned*)(lds + (bufoff) + ldsw + _i * 8192), 16, 0, 0); } while (0)
; #define PG8_LDA(dst, b, h) do { _Pragma("unroll") for (int m = 0; m < 4; ++m) _Pragma("unroll") for (int k = 0; k < 2; ++k) dst[m][k] = *(const PG8_LAS bf16x8*)(lds + PG8_SA(b, h) + aoff + m * 2048 + k * 1024); } while (0)
; #define PG8_MMA(ai, bj, At, Bt) do { __builtin_amdgcn_s_setprio(1); _Pragma("unroll") for (int m = 0; m < 4; ++m) _Pragma("unroll") for (int n = 0; n < 2; ++n) _Pragma("unroll") for (int k = 0; k < 2; ++k) \
;         acc[ai][bj][m][n] = __builtin_amdgcn_mfma_f32_16x16x32_bf16(Bt[n][k], At[m][k], acc[ai][bj][m][n], 0, 0, 0); __builtin_amdgcn_s_setprio(0); } while (0)
; #define PG8_WAIT_V(n) asm volatile("s_waitcnt vmcnt(" #n ")" ::: "memory")
; #define PG8_WAIT_L(n) asm volatile("s_waitcnt lgkmcnt(" #n ")" ::: "memory")
; #define PG8_BAR __builtin_amdgcn_s_barrier()
; #define PG8_SCHED __builtin_amdgcn_sched_barrier(0)
; template <class Epi, class Sched, bool ALIGN_EPI = false, bool SP2 = false>
; __device__ __forceinline__ void gemm_phase(PG8_LAS unsigned char* lds, const Gemm g, const Sched& S, const Epi& E) {
;     ...
;         for (int t = 0; t < nt; t += 2) {
;     ...
;             PG8_LDA(At, 1, 1); PG8_STAGE(PG8_SB(1, 0), b3, voffB); PG8_STAGE(PG8_SB(1, 1), b3 + hstepB, voffB); PG8_STAGE(PG8_SA(1, 0), a3, voffA);
;             PG8_WAIT_V(8); PG8_WAIT_L(0); PG8_BAR; PG8_MMA(1, 0, At, B0); PG8_MMA(1, 1, At, B1); PG8_BAR; PG8_SCHED;
	s_add_i32 s54, s69, s17
	v_lshl_add_u64 v[196:197], v[196:197], 0, s[26:27]
	s_mov_b32 m0, s54
	ds_read_b128 v[178:181], v213 offset:49152
	ds_read_b128 v[184:187], v213 offset:50176
	ds_read_b128 v[190:193], v213 offset:51200
	ds_read_b128 v[200:203], v213 offset:52224
	ds_read_b128 v[206:209], v213 offset:53248
	ds_read_b128 v[214:217], v213 offset:54272
	ds_read_b128 v[220:223], v213 offset:55296
	ds_read_b128 v[226:229], v213 offset:56320
	global_load_lds_dwordx4 v[196:197], off
	s_add_i32 m0, s54, 0x2000
	s_add_u32 s52, s52, 0x40080
	v_lshl_add_u64 v[196:197], v[210:211], 0, s[26:27]
	s_addc_u32 s53, s53, 0
	s_add_i32 s54, s70, s17
	global_load_lds_dwordx4 v[196:197], off
	v_lshl_add_u64 v[196:197], s[52:53], 0, v[162:163]
	s_mov_b32 m0, s54
	s_nop 0
	global_load_lds_dwordx4 v[196:197], off
	v_lshl_add_u64 v[196:197], s[52:53], 0, v[166:167]
	s_add_i32 m0, s54, 0x2000
	s_nop 0
	global_load_lds_dwordx4 v[196:197], off
	v_lshl_add_u64 v[196:197], v[230:231], 0, s[26:27]
	s_mov_b32 m0, s59
	s_nop 0
	global_load_lds_dwordx4 v[196:197], off
	v_lshl_add_u64 v[196:197], v[232:233], 0, s[26:27]
	s_mov_b32 m0, s60
	s_nop 0
	global_load_lds_dwordx4 v[196:197], off
	s_waitcnt vmcnt(8)
	s_waitcnt lgkmcnt(0)
	s_barrier
	s_waitcnt lgkmcnt(0)
	v_mfma_f32_16x16x32_bf16 v[60:63], v[128:131], v[178:181], v[60:63]
	v_mfma_f32_16x16x32_bf16 v[56:59], v[136:139], v[178:181], v[56:59]
	v_mfma_f32_16x16x32_bf16 v[44:47], v[128:131], v[190:193], v[44:47]
	v_mfma_f32_16x16x32_bf16 v[40:43], v[136:139], v[190:193], v[40:43]
	v_mfma_f32_16x16x32_bf16 v[28:31], v[128:131], v[206:209], v[28:31]
	v_mfma_f32_16x16x32_bf16 v[24:27], v[136:139], v[206:209], v[24:27]
	v_mfma_f32_16x16x32_bf16 v[12:15], v[128:131], v[220:223], v[12:15]
	v_mfma_f32_16x16x32_bf16 v[8:11], v[136:139], v[220:223], v[8:11]
	v_mfma_f32_16x16x32_bf16 v[60:63], v[132:135], v[184:187], v[60:63]
	v_mfma_f32_16x16x32_bf16 v[56:59], v[140:143], v[184:187], v[56:59]
	v_mfma_f32_16x16x32_bf16 v[44:47], v[132:135], v[200:203], v[44:47]
	v_mfma_f32_16x16x32_bf16 v[40:43], v[140:143], v[200:203], v[40:43]
	v_mfma_f32_16x16x32_bf16 v[28:31], v[132:135], v[214:217], v[28:31]
	v_mfma_f32_16x16x32_bf16 v[24:27], v[140:143], v[214:217], v[24:27]
	v_mfma_f32_16x16x32_bf16 v[12:15], v[132:135], v[226:229], v[12:15]
	v_mfma_f32_16x16x32_bf16 v[8:11], v[140:143], v[226:229], v[8:11]
	v_mfma_f32_16x16x32_bf16 v[52:55], v[144:147], v[178:181], v[52:55]
	v_mfma_f32_16x16x32_bf16 v[48:51], v[152:155], v[178:181], v[48:51]
	v_mfma_f32_16x16x32_bf16 v[36:39], v[144:147], v[190:193], v[36:39]
	v_mfma_f32_16x16x32_bf16 v[32:35], v[152:155], v[190:193], v[32:35]
	v_mfma_f32_16x16x32_bf16 v[20:23], v[144:147], v[206:209], v[20:23]
	v_mfma_f32_16x16x32_bf16 v[16:19], v[152:155], v[206:209], v[16:19]
	v_mfma_f32_16x16x32_bf16 v[4:7], v[144:147], v[220:223], v[4:7]
	v_mfma_f32_16x16x32_bf16 v[0:3], v[152:155], v[220:223], v[0:3]
	v_mfma_f32_16x16x32_bf16 v[52:55], v[148:151], v[184:187], v[52:55]
	v_mfma_f32_16x16x32_bf16 v[48:51], v[156:159], v[184:187], v[48:51]
	v_mfma_f32_16x16x32_bf16 v[36:39], v[148:151], v[200:203], v[36:39]
	v_mfma_f32_16x16x32_bf16 v[32:35], v[156:159], v[200:203], v[32:35]
	v_mfma_f32_16x16x32_bf16 v[20:23], v[148:151], v[214:217], v[20:23]
	v_mfma_f32_16x16x32_bf16 v[16:19], v[156:159], v[214:217], v[16:19]
	v_mfma_f32_16x16x32_bf16 v[4:7], v[148:151], v[226:229], v[4:7]
	v_mfma_f32_16x16x32_bf16 v[0:3], v[156:159], v[226:229], v[0:3]
	s_barrier
	s_add_u32 s50, s50, 0x100
	s_addc_u32 s51, s51, 0
	s_add_u32 s47, s47, 0x100
	s_addc_u32 s67, s67, 0
	s_cmp_ge_i32 s68, s35
	s_mov_b32 s52, s68
	s_cbranch_scc0 .LBB0_433

; #define PG8_STAGE(bufoff, gbase, voff) do { _Pragma("unroll") for (int _i = 0; _i < 2; ++_i) \
;         __builtin_amdgcn_global_load_lds((const unsigned*)((const char*)(gbase) + (voff)[_i]), (PG8_LAS unsigned*)(lds + (bufoff) + ldsw + _i * 8192), 16, 0, 0); } while (0)
; #define PG8_LDA(dst, b, h) do { _Pragma("unroll") for (int m = 0; m < 4; ++m) _Pragma("unroll") for (int k = 0; k < 2; ++k) dst[m][k] = *(const PG8_LAS bf16x8*)(lds + PG8_SA(b, h) + aoff + m * 2048 + k * 1024); } while (0)
; #define PG8_LDB(dst, b, h) do { _Pragma("unroll") for (int n = 0; n < 2; ++n) _Pragma("unroll") for (int k = 0; k < 2; ++k) dst[n][k] = *(const PG8_LAS bf16x8*)(lds + PG8_SB(b, h) + boff + n * 2048 + k * 1024); } while (0)
; #define PG8_MMA(ai, bj, At, Bt) do { __builtin_amdgcn_s_setprio(1); _Pragma("unroll") for (int m = 0; m < 4; ++m) _Pragma("unroll") for (int n = 0; n < 2; ++n) _Pragma("unroll") for (int k = 0; k < 2; ++k) \
;         acc[ai][bj][m][n] = __builtin_amdgcn_mfma_f32_16x16x32_bf16(Bt[n][k], At[m][k], acc[ai][bj][m][n], 0, 0, 0); __builtin_amdgcn_s_setprio(0); } while (0)
; #define PG8_WAIT_V(n) asm volatile("s_waitcnt vmcnt(" #n ")" ::: "memory")
; #define PG8_WAIT_L(n) asm volatile("s_waitcnt lgkmcnt(" #n ")" ::: "memory")
; #define PG8_BAR __builtin_amdgcn_s_barrier()
; #define PG8_SCHED __builtin_amdgcn_sched_barrier(0)
; template <class Epi, class Sched, bool ALIGN_EPI = false, bool SP2 = false>
; __device__ __forceinline__ void gemm_phase(PG8_LAS unsigned char* lds, const Gemm g, const Sched& S, const Epi& E) {
;     ...
;             PG8_LDB(B0, 0, 0); PG8_LDB(B1, 0, 1); PG8_SCHED; PG8_LDA(At, 0, 0); PG8_STAGE(PG8_SA(1, 1), a1 + hstepA, voffA);
;             PG8_WAIT_V(8); PG8_WAIT_L(0); PG8_BAR; PG8_MMA(0, 0, At, B0); PG8_MMA(0, 1, At, B1); PG8_BAR; PG8_SCHED;
;             PG8_LDA(At, 0, 1); PG8_STAGE(PG8_SB(0, 0), b2, voffB); PG8_STAGE(PG8_SB(0, 1), b2 + hstepB, voffB); PG8_STAGE(PG8_SA(0, 0), a2, voffA);
.LBB0_1172:
	ds_read_b128 v[128:131], v183
	ds_read_b128 v[132:135], v183 offset:1024
	ds_read_b128 v[136:139], v183 offset:2048
	ds_read_b128 v[140:143], v183 offset:3072
	ds_read_b128 v[144:147], v187
	ds_read_b128 v[148:151], v187 offset:1024
	ds_read_b128 v[152:155], v187 offset:2048
	ds_read_b128 v[196:199], v187 offset:3072
	s_add_i32 s69, s52, 2
	s_add_u32 s53, s50, 0xfffc0080
	s_addc_u32 s54, s51, -1
	s_cmp_eq_u32 s20, s52
	s_cselect_b32 s52, s43, s45
	s_cselect_b32 s55, s8, s54
	s_cselect_b32 s54, s9, s53
	s_cselect_b32 s53, s11, s49
	v_lshl_add_u64 v[180:181], s[50:51], 0, v[166:167]
	s_add_i32 m0, s33, 0xc000
	ds_read_b128 v[200:203], v191
	ds_read_b128 v[204:207], v191 offset:1024
	ds_read_b128 v[208:211], v191 offset:2048
	ds_read_b128 v[212:215], v191 offset:3072
	ds_read_b128 v[216:219], v191 offset:4096
	ds_read_b128 v[220:223], v191 offset:5120
	ds_read_b128 v[224:227], v191 offset:6144
	ds_read_b128 v[228:231], v191 offset:7168
	global_load_lds_dwordx4 v[180:181], off
	v_lshl_add_u64 v[180:181], s[50:51], 0, v[168:169]
	s_add_i32 m0, s33, 0xe000
	s_nop 0
	global_load_lds_dwordx4 v[180:181], off
	s_waitcnt vmcnt(8)
	s_waitcnt lgkmcnt(0)
	s_barrier
	s_waitcnt lgkmcnt(0)
	v_mfma_f32_16x16x32_bf16 v[124:127], v[128:131], v[200:203], v[124:127]
	v_mfma_f32_16x16x32_bf16 v[120:123], v[136:139], v[200:203], v[120:123]
	v_mfma_f32_16x16x32_bf16 v[116:119], v[128:131], v[208:211], v[116:119]
	v_mfma_f32_16x16x32_bf16 v[112:115], v[136:139], v[208:211], v[112:115]
	v_mfma_f32_16x16x32_bf16 v[108:111], v[128:131], v[216:219], v[108:111]
	v_mfma_f32_16x16x32_bf16 v[104:107], v[136:139], v[216:219], v[104:107]
	v_mfma_f32_16x16x32_bf16 v[100:103], v[128:131], v[224:227], v[100:103]
	v_mfma_f32_16x16x32_bf16 v[96:99], v[136:139], v[224:227], v[96:99]
	v_mfma_f32_16x16x32_bf16 v[124:127], v[132:135], v[204:207], v[124:127]
	v_mfma_f32_16x16x32_bf16 v[120:123], v[140:143], v[204:207], v[120:123]
	v_mfma_f32_16x16x32_bf16 v[116:119], v[132:135], v[212:215], v[116:119]
	v_mfma_f32_16x16x32_bf16 v[112:115], v[140:143], v[212:215], v[112:115]
	v_mfma_f32_16x16x32_bf16 v[108:111], v[132:135], v[220:223], v[108:111]
	v_mfma_f32_16x16x32_bf16 v[104:107], v[140:143], v[220:223], v[104:107]
	v_mfma_f32_16x16x32_bf16 v[100:103], v[132:135], v[228:231], v[100:103]
	v_mfma_f32_16x16x32_bf16 v[96:99], v[140:143], v[228:231], v[96:99]
	v_mfma_f32_16x16x32_bf16 v[60:63], v[144:147], v[200:203], v[60:63]
	v_mfma_f32_16x16x32_bf16 v[56:59], v[152:155], v[200:203], v[56:59]
	v_mfma_f32_16x16x32_bf16 v[52:55], v[144:147], v[208:211], v[52:55]
	v_mfma_f32_16x16x32_bf16 v[48:51], v[152:155], v[208:211], v[48:51]
	v_mfma_f32_16x16x32_bf16 v[44:47], v[144:147], v[216:219], v[44:47]
	v_mfma_f32_16x16x32_bf16 v[40:43], v[152:155], v[216:219], v[40:43]
	v_mfma_f32_16x16x32_bf16 v[36:39], v[144:147], v[224:227], v[36:39]
	v_mfma_f32_16x16x32_bf16 v[32:35], v[152:155], v[224:227], v[32:35]
	v_mfma_f32_16x16x32_bf16 v[60:63], v[148:151], v[204:207], v[60:63]
	v_mfma_f32_16x16x32_bf16 v[56:59], v[196:199], v[204:207], v[56:59]
	v_mfma_f32_16x16x32_bf16 v[52:55], v[148:151], v[212:215], v[52:55]
	v_mfma_f32_16x16x32_bf16 v[48:51], v[196:199], v[212:215], v[48:51]
	v_mfma_f32_16x16x32_bf16 v[44:47], v[148:151], v[220:223], v[44:47]
	v_mfma_f32_16x16x32_bf16 v[40:43], v[196:199], v[220:223], v[40:43]
	v_mfma_f32_16x16x32_bf16 v[36:39], v[148:151], v[228:231], v[36:39]
	v_mfma_f32_16x16x32_bf16 v[32:35], v[196:199], v[228:231], v[32:35]
	s_barrier
	s_add_i32 s70, s67, s19
	v_lshl_add_u64 v[180:181], s[52:53], 0, v[158:159]
	s_mov_b32 m0, s70
	ds_read_b128 v[200:203], v191 offset:16384
	ds_read_b128 v[204:207], v191 offset:17408
	ds_read_b128 v[208:211], v191 offset:18432
	ds_read_b128 v[212:215], v191 offset:19456
	ds_read_b128 v[216:219], v191 offset:20480
	ds_read_b128 v[220:223], v191 offset:21504
	ds_read_b128 v[224:227], v191 offset:22528
	ds_read_b128 v[228:231], v191 offset:23552
	global_load_lds_dwordx4 v[180:181], off
	s_add_i32 m0, s70, 0x2000
	s_add_u32 s70, s52, 0x40000
	v_lshl_add_u64 v[184:185], s[52:53], 0, v[162:163]
	s_addc_u32 s71, s53, 0
	s_add_i32 s72, s68, s19
	global_load_lds_dwordx4 v[184:185], off
	v_lshl_add_u64 v[188:189], s[70:71], 0, v[158:159]
	s_mov_b32 m0, s72
	v_lshl_add_u64 v[192:193], s[54:55], 0, v[160:161]
	global_load_lds_dwordx4 v[188:189], off
	v_lshl_add_u64 v[188:189], s[70:71], 0, v[162:163]
	s_add_i32 m0, s72, 0x2000
	s_nop 0
	global_load_lds_dwordx4 v[188:189], off
	v_lshl_add_u64 v[188:189], s[54:55], 0, v[156:157]
	s_mov_b32 m0, s33
	s_nop 0
	global_load_lds_dwordx4 v[188:189], off
	s_mov_b32 m0, s41
	s_nop 0
	global_load_lds_dwordx4 v[192:193], off
	s_waitcnt vmcnt(8)
	s_waitcnt lgkmcnt(0)
	s_barrier
; #define PG8_STAGE(bufoff, gbase, voff) do { _Pragma("unroll") for (int _i = 0; _i < 2; ++_i) \
;         __builtin_amdgcn_global_load_lds((const unsigned*)((const char*)(gbase) + (voff)[_i]), (PG8_LAS unsigned*)(lds + (bufoff) + ldsw + _i * 8192), 16, 0, 0); } while (0)
; #define PG8_LDA(dst, b, h) do { _Pragma("unroll") for (int m = 0; m < 4; ++m) _Pragma("unroll") for (int k = 0; k < 2; ++k) dst[m][k] = *(const PG8_LAS bf16x8*)(lds + PG8_SA(b, h) + aoff + m * 2048 + k * 1024); } while (0)
; #define PG8_LDB(dst, b, h) do { _Pragma("unroll") for (int n = 0; n < 2; ++n) _Pragma("unroll") for (int k = 0; k < 2; ++k) dst[n][k] = *(const PG8_LAS bf16x8*)(lds + PG8_SB(b, h) + boff + n * 2048 + k * 1024); } while (0)
; #define PG8_MMA(ai, bj, At, Bt) do { __builtin_amdgcn_s_setprio(1); _Pragma("unroll") for (int m = 0; m < 4; ++m) _Pragma("unroll") for (int n = 0; n < 2; ++n) _Pragma("unroll") for (int k = 0; k < 2; ++k) \
;         acc[ai][bj][m][n] = __builtin_amdgcn_mfma_f32_16x16x32_bf16(Bt[n][k], At[m][k], acc[ai][bj][m][n], 0, 0, 0); __builtin_amdgcn_s_setprio(0); } while (0)
; #define PG8_WAIT_V(n) asm volatile("s_waitcnt vmcnt(" #n ")" ::: "memory")
; #define PG8_WAIT_L(n) asm volatile("s_waitcnt lgkmcnt(" #n ")" ::: "memory")
; #define PG8_BAR __builtin_amdgcn_s_barrier()
; #define PG8_SCHED __builtin_amdgcn_sched_barrier(0)
; template <class Epi, class Sched, bool ALIGN_EPI = false, bool SP2 = false>
; __device__ __forceinline__ void gemm_phase(PG8_LAS unsigned char* lds, const Gemm g, const Sched& S, const Epi& E) {
;     ...
;             PG8_WAIT_V(8); PG8_WAIT_L(0); PG8_BAR; PG8_MMA(1, 0, At, B0); PG8_MMA(1, 1, At, B1); PG8_BAR; PG8_SCHED;
;             PG8_LDB(B0, 1, 0); PG8_LDB(B1, 1, 1); PG8_SCHED; PG8_LDA(At, 1, 0); PG8_STAGE(PG8_SA(0, 1), a2 + hstepA, voffA);
;             PG8_WAIT_V(8); PG8_WAIT_L(0); PG8_BAR; PG8_MMA(0, 0, At, B0); PG8_MMA(0, 1, At, B1); PG8_BAR; PG8_SCHED;
	s_waitcnt lgkmcnt(0)
	v_mfma_f32_16x16x32_bf16 v[92:95], v[128:131], v[200:203], v[92:95]
	v_mfma_f32_16x16x32_bf16 v[88:91], v[136:139], v[200:203], v[88:91]
	v_mfma_f32_16x16x32_bf16 v[84:87], v[128:131], v[208:211], v[84:87]
	v_mfma_f32_16x16x32_bf16 v[80:83], v[136:139], v[208:211], v[80:83]
	v_mfma_f32_16x16x32_bf16 v[76:79], v[128:131], v[216:219], v[76:79]
	v_mfma_f32_16x16x32_bf16 v[72:75], v[136:139], v[216:219], v[72:75]
	v_mfma_f32_16x16x32_bf16 v[68:71], v[128:131], v[224:227], v[68:71]
	v_mfma_f32_16x16x32_bf16 v[64:67], v[136:139], v[224:227], v[64:67]
	v_mfma_f32_16x16x32_bf16 v[92:95], v[132:135], v[204:207], v[92:95]
	v_mfma_f32_16x16x32_bf16 v[88:91], v[140:143], v[204:207], v[88:91]
	v_mfma_f32_16x16x32_bf16 v[84:87], v[132:135], v[212:215], v[84:87]
	v_mfma_f32_16x16x32_bf16 v[80:83], v[140:143], v[212:215], v[80:83]
	v_mfma_f32_16x16x32_bf16 v[76:79], v[132:135], v[220:223], v[76:79]
	v_mfma_f32_16x16x32_bf16 v[72:75], v[140:143], v[220:223], v[72:75]
	v_mfma_f32_16x16x32_bf16 v[68:71], v[132:135], v[228:231], v[68:71]
	v_mfma_f32_16x16x32_bf16 v[64:67], v[140:143], v[228:231], v[64:67]
	v_mfma_f32_16x16x32_bf16 v[28:31], v[144:147], v[200:203], v[28:31]
	v_mfma_f32_16x16x32_bf16 v[24:27], v[152:155], v[200:203], v[24:27]
	v_mfma_f32_16x16x32_bf16 v[20:23], v[144:147], v[208:211], v[20:23]
	v_mfma_f32_16x16x32_bf16 v[16:19], v[152:155], v[208:211], v[16:19]
	v_mfma_f32_16x16x32_bf16 v[12:15], v[144:147], v[216:219], v[12:15]
	v_mfma_f32_16x16x32_bf16 v[8:11], v[152:155], v[216:219], v[8:11]
	v_mfma_f32_16x16x32_bf16 v[4:7], v[144:147], v[224:227], v[4:7]
	v_mfma_f32_16x16x32_bf16 v[0:3], v[152:155], v[224:227], v[0:3]
	v_mfma_f32_16x16x32_bf16 v[28:31], v[148:151], v[204:207], v[28:31]
	v_mfma_f32_16x16x32_bf16 v[24:27], v[196:199], v[204:207], v[24:27]
	v_mfma_f32_16x16x32_bf16 v[20:23], v[148:151], v[212:215], v[20:23]
	v_mfma_f32_16x16x32_bf16 v[16:19], v[196:199], v[212:215], v[16:19]
	v_mfma_f32_16x16x32_bf16 v[12:15], v[148:151], v[220:223], v[12:15]
	v_mfma_f32_16x16x32_bf16 v[8:11], v[196:199], v[220:223], v[8:11]
	v_mfma_f32_16x16x32_bf16 v[4:7], v[148:151], v[228:231], v[4:7]
	v_mfma_f32_16x16x32_bf16 v[0:3], v[196:199], v[228:231], v[0:3]
	s_barrier
	s_add_i32 s70, 0, 0x18000
	s_add_i32 s71, 0, 0x1c000
	v_add_u32_e32 v140, s70, v179
	v_add_u32_e32 v165, s71, v179
	ds_read_b128 v[128:131], v140
	ds_read_b128 v[132:135], v140 offset:1024
	ds_read_b128 v[136:139], v140 offset:2048
	ds_read_b128 v[140:143], v140 offset:3072
	ds_read_b128 v[144:147], v165
	ds_read_b128 v[148:151], v165 offset:1024
	ds_read_b128 v[152:155], v165 offset:2048
	ds_read_b128 v[196:199], v165 offset:3072
	s_add_u32 s54, s54, 0x40000
	s_addc_u32 s55, s55, 0
	s_mov_b32 m0, s56
	v_lshl_add_u64 v[232:233], s[54:55], 0, v[156:157]
	ds_read_b128 v[200:203], v191 offset:32768
	ds_read_b128 v[204:207], v191 offset:33792
	ds_read_b128 v[208:211], v191 offset:34816
	ds_read_b128 v[212:215], v191 offset:35840
	ds_read_b128 v[216:219], v191 offset:36864
	ds_read_b128 v[220:223], v191 offset:37888
	ds_read_b128 v[224:227], v191 offset:38912
	ds_read_b128 v[228:231], v191 offset:39936
	global_load_lds_dwordx4 v[232:233], off
	v_lshl_add_u64 v[232:233], s[54:55], 0, v[160:161]
	s_mov_b32 m0, s57
	s_nop 0
	global_load_lds_dwordx4 v[232:233], off
	s_waitcnt vmcnt(8)
	s_waitcnt lgkmcnt(0)
	s_barrier
	s_waitcnt lgkmcnt(0)
	v_mfma_f32_16x16x32_bf16 v[124:127], v[128:131], v[200:203], v[124:127]
	v_mfma_f32_16x16x32_bf16 v[120:123], v[136:139], v[200:203], v[120:123]
	v_mfma_f32_16x16x32_bf16 v[116:119], v[128:131], v[208:211], v[116:119]
	v_mfma_f32_16x16x32_bf16 v[112:115], v[136:139], v[208:211], v[112:115]
	v_mfma_f32_16x16x32_bf16 v[108:111], v[128:131], v[216:219], v[108:111]
	v_mfma_f32_16x16x32_bf16 v[104:107], v[136:139], v[216:219], v[104:107]
	v_mfma_f32_16x16x32_bf16 v[100:103], v[128:131], v[224:227], v[100:103]
	v_mfma_f32_16x16x32_bf16 v[96:99], v[136:139], v[224:227], v[96:99]
	v_mfma_f32_16x16x32_bf16 v[124:127], v[132:135], v[204:207], v[124:127]
	v_mfma_f32_16x16x32_bf16 v[120:123], v[140:143], v[204:207], v[120:123]
	v_mfma_f32_16x16x32_bf16 v[116:119], v[132:135], v[212:215], v[116:119]
	v_mfma_f32_16x16x32_bf16 v[112:115], v[140:143], v[212:215], v[112:115]
	v_mfma_f32_16x16x32_bf16 v[108:111], v[132:135], v[220:223], v[108:111]
	v_mfma_f32_16x16x32_bf16 v[104:107], v[140:143], v[220:223], v[104:107]
	v_mfma_f32_16x16x32_bf16 v[100:103], v[132:135], v[228:231], v[100:103]
	v_mfma_f32_16x16x32_bf16 v[96:99], v[140:143], v[228:231], v[96:99]
	v_mfma_f32_16x16x32_bf16 v[60:63], v[144:147], v[200:203], v[60:63]
	v_mfma_f32_16x16x32_bf16 v[56:59], v[152:155], v[200:203], v[56:59]
	v_mfma_f32_16x16x32_bf16 v[52:55], v[144:147], v[208:211], v[52:55]
	v_mfma_f32_16x16x32_bf16 v[48:51], v[152:155], v[208:211], v[48:51]
	v_mfma_f32_16x16x32_bf16 v[44:47], v[144:147], v[216:219], v[44:47]
	v_mfma_f32_16x16x32_bf16 v[40:43], v[152:155], v[216:219], v[40:43]
	v_mfma_f32_16x16x32_bf16 v[36:39], v[144:147], v[224:227], v[36:39]
	v_mfma_f32_16x16x32_bf16 v[32:35], v[152:155], v[224:227], v[32:35]
	v_mfma_f32_16x16x32_bf16 v[60:63], v[148:151], v[204:207], v[60:63]
	v_mfma_f32_16x16x32_bf16 v[56:59], v[196:199], v[204:207], v[56:59]
	v_mfma_f32_16x16x32_bf16 v[52:55], v[148:151], v[212:215], v[52:55]
	v_mfma_f32_16x16x32_bf16 v[48:51], v[196:199], v[212:215], v[48:51]
	v_mfma_f32_16x16x32_bf16 v[44:47], v[148:151], v[220:223], v[44:47]
	v_mfma_f32_16x16x32_bf16 v[40:43], v[196:199], v[220:223], v[40:43]
	v_mfma_f32_16x16x32_bf16 v[36:39], v[148:151], v[228:231], v[36:39]
	v_mfma_f32_16x16x32_bf16 v[32:35], v[196:199], v[228:231], v[32:35]
	s_barrier
; #define PG8_STAGE(bufoff, gbase, voff) do { _Pragma("unroll") for (int _i = 0; _i < 2; ++_i) \
;         __builtin_amdgcn_global_load_lds((const unsigned*)((const char*)(gbase) + (voff)[_i]), (PG8_LAS unsigned*)(lds + (bufoff) + ldsw + _i * 8192), 16, 0, 0); } while (0)
; #define PG8_LDA(dst, b, h) do { _Pragma("unroll") for (int m = 0; m < 4; ++m) _Pragma("unroll") for (int k = 0; k < 2; ++k) dst[m][k] = *(const PG8_LAS bf16x8*)(lds + PG8_SA(b, h) + aoff + m * 2048 + k * 1024); } while (0)
; #define PG8_MMA(ai, bj, At, Bt) do { __builtin_amdgcn_s_setprio(1); _Pragma("unroll") for (int m = 0; m < 4; ++m) _Pragma("unroll") for (int n = 0; n < 2; ++n) _Pragma("unroll") for (int k = 0; k < 2; ++k) \
;         acc[ai][bj][m][n] = __builtin_amdgcn_mfma_f32_16x16x32_bf16(Bt[n][k], At[m][k], acc[ai][bj][m][n], 0, 0, 0); __builtin_amdgcn_s_setprio(0); } while (0)
; #define PG8_WAIT_V(n) asm volatile("s_waitcnt vmcnt(" #n ")" ::: "memory")
; #define PG8_WAIT_L(n) asm volatile("s_waitcnt lgkmcnt(" #n ")" ::: "memory")
; #define PG8_BAR __builtin_amdgcn_s_barrier()
; #define PG8_SCHED __builtin_amdgcn_sched_barrier(0)
; template <class Epi, class Sched, bool ALIGN_EPI = false, bool SP2 = false>
; __device__ __forceinline__ void gemm_phase(PG8_LAS unsigned char* lds, const Gemm g, const Sched& S, const Epi& E) {
;     ...
;         for (int t = 0; t < nt; t += 2) {
;     ...
;             PG8_LDA(At, 1, 1); PG8_STAGE(PG8_SB(1, 0), b3, voffB); PG8_STAGE(PG8_SB(1, 1), b3 + hstepB, voffB); PG8_STAGE(PG8_SA(1, 0), a3, voffA);
;             PG8_WAIT_V(8); PG8_WAIT_L(0); PG8_BAR; PG8_MMA(1, 0, At, B0); PG8_MMA(1, 1, At, B1); PG8_BAR; PG8_SCHED;
	s_add_i32 s54, s70, s19
	v_lshl_add_u64 v[180:181], v[180:181], 0, s[28:29]
	s_mov_b32 m0, s54
	ds_read_b128 v[200:203], v191 offset:49152
	ds_read_b128 v[204:207], v191 offset:50176
	ds_read_b128 v[208:211], v191 offset:51200
	ds_read_b128 v[212:215], v191 offset:52224
	ds_read_b128 v[216:219], v191 offset:53248
	ds_read_b128 v[220:223], v191 offset:54272
	ds_read_b128 v[224:227], v191 offset:55296
	ds_read_b128 v[228:231], v191 offset:56320
	global_load_lds_dwordx4 v[180:181], off
	s_add_i32 m0, s54, 0x2000
	s_add_u32 s52, s52, 0x40080
	v_lshl_add_u64 v[180:181], v[184:185], 0, s[28:29]
	s_addc_u32 s53, s53, 0
	s_add_i32 s54, s71, s19
	global_load_lds_dwordx4 v[180:181], off
	v_lshl_add_u64 v[180:181], s[52:53], 0, v[158:159]
	s_mov_b32 m0, s54
	s_nop 0
	global_load_lds_dwordx4 v[180:181], off
	v_lshl_add_u64 v[180:181], s[52:53], 0, v[162:163]
	s_add_i32 m0, s54, 0x2000
	s_nop 0
	global_load_lds_dwordx4 v[180:181], off
	v_lshl_add_u64 v[180:181], v[188:189], 0, s[28:29]
	s_mov_b32 m0, s62
	s_nop 0
	global_load_lds_dwordx4 v[180:181], off
	v_lshl_add_u64 v[180:181], v[192:193], 0, s[28:29]
	s_mov_b32 m0, s63
	s_nop 0
	global_load_lds_dwordx4 v[180:181], off
	s_waitcnt vmcnt(8)
	s_waitcnt lgkmcnt(0)
	s_barrier
	s_waitcnt lgkmcnt(0)
	v_mfma_f32_16x16x32_bf16 v[92:95], v[128:131], v[200:203], v[92:95]
	v_mfma_f32_16x16x32_bf16 v[88:91], v[136:139], v[200:203], v[88:91]
	v_mfma_f32_16x16x32_bf16 v[84:87], v[128:131], v[208:211], v[84:87]
	v_mfma_f32_16x16x32_bf16 v[80:83], v[136:139], v[208:211], v[80:83]
	v_mfma_f32_16x16x32_bf16 v[76:79], v[128:131], v[216:219], v[76:79]
	v_mfma_f32_16x16x32_bf16 v[72:75], v[136:139], v[216:219], v[72:75]
	v_mfma_f32_16x16x32_bf16 v[68:71], v[128:131], v[224:227], v[68:71]
	v_mfma_f32_16x16x32_bf16 v[64:67], v[136:139], v[224:227], v[64:67]
	v_mfma_f32_16x16x32_bf16 v[92:95], v[132:135], v[204:207], v[92:95]
	v_mfma_f32_16x16x32_bf16 v[88:91], v[140:143], v[204:207], v[88:91]
	v_mfma_f32_16x16x32_bf16 v[84:87], v[132:135], v[212:215], v[84:87]
	v_mfma_f32_16x16x32_bf16 v[80:83], v[140:143], v[212:215], v[80:83]
	v_mfma_f32_16x16x32_bf16 v[76:79], v[132:135], v[220:223], v[76:79]
	v_mfma_f32_16x16x32_bf16 v[72:75], v[140:143], v[220:223], v[72:75]
	v_mfma_f32_16x16x32_bf16 v[68:71], v[132:135], v[228:231], v[68:71]
	v_mfma_f32_16x16x32_bf16 v[64:67], v[140:143], v[228:231], v[64:67]
	v_mfma_f32_16x16x32_bf16 v[28:31], v[144:147], v[200:203], v[28:31]
	v_mfma_f32_16x16x32_bf16 v[24:27], v[152:155], v[200:203], v[24:27]
	v_mfma_f32_16x16x32_bf16 v[20:23], v[144:147], v[208:211], v[20:23]
	v_mfma_f32_16x16x32_bf16 v[16:19], v[152:155], v[208:211], v[16:19]
	v_mfma_f32_16x16x32_bf16 v[12:15], v[144:147], v[216:219], v[12:15]
	v_mfma_f32_16x16x32_bf16 v[8:11], v[152:155], v[216:219], v[8:11]
	v_mfma_f32_16x16x32_bf16 v[4:7], v[144:147], v[224:227], v[4:7]
	v_mfma_f32_16x16x32_bf16 v[0:3], v[152:155], v[224:227], v[0:3]
	v_mfma_f32_16x16x32_bf16 v[28:31], v[148:151], v[204:207], v[28:31]
	v_mfma_f32_16x16x32_bf16 v[24:27], v[196:199], v[204:207], v[24:27]
	v_mfma_f32_16x16x32_bf16 v[20:23], v[148:151], v[212:215], v[20:23]
	v_mfma_f32_16x16x32_bf16 v[16:19], v[196:199], v[212:215], v[16:19]
	v_mfma_f32_16x16x32_bf16 v[12:15], v[148:151], v[220:223], v[12:15]
	v_mfma_f32_16x16x32_bf16 v[8:11], v[196:199], v[220:223], v[8:11]
	v_mfma_f32_16x16x32_bf16 v[4:7], v[148:151], v[228:231], v[4:7]
	v_mfma_f32_16x16x32_bf16 v[0:3], v[196:199], v[228:231], v[0:3]
	s_barrier
	s_add_u32 s45, s45, 0x100
	s_addc_u32 s49, s49, 0
	s_add_u32 s50, s50, 0x100
	s_addc_u32 s51, s51, 0
	s_cmp_ge_i32 s69, s59
	s_mov_b32 s52, s69
	s_cbranch_scc0 .LBB0_1172

; #define PG8_STAGE(bufoff, gbase, voff) do { _Pragma("unroll") for (int _i = 0; _i < 2; ++_i) \
;         __builtin_amdgcn_global_load_lds((const unsigned*)((const char*)(gbase) + (voff)[_i]), (PG8_LAS unsigned*)(lds + (bufoff) + ldsw + _i * 8192), 16, 0, 0); } while (0)
; #define PG8_LDA(dst, b, h) do { _Pragma("unroll") for (int m = 0; m < 4; ++m) _Pragma("unroll") for (int k = 0; k < 2; ++k) dst[m][k] = *(const PG8_LAS bf16x8*)(lds + PG8_SA(b, h) + aoff + m * 2048 + k * 1024); } while (0)
; #define PG8_LDB(dst, b, h) do { _Pragma("unroll") for (int n = 0; n < 2; ++n) _Pragma("unroll") for (int k = 0; k < 2; ++k) dst[n][k] = *(const PG8_LAS bf16x8*)(lds + PG8_SB(b, h) + boff + n * 2048 + k * 1024); } while (0)
; #define PG8_MMA(ai, bj, At, Bt) do { __builtin_amdgcn_s_setprio(1); _Pragma("unroll") for (int m = 0; m < 4; ++m) _Pragma("unroll") for (int n = 0; n < 2; ++n) _Pragma("unroll") for (int k = 0; k < 2; ++k) \
;         acc[ai][bj][m][n] = __builtin_amdgcn_mfma_f32_16x16x32_bf16(Bt[n][k], At[m][k], acc[ai][bj][m][n], 0, 0, 0); __builtin_amdgcn_s_setprio(0); } while (0)
; #define PG8_WAIT_V(n) asm volatile("s_waitcnt vmcnt(" #n ")" ::: "memory")
; #define PG8_WAIT_L(n) asm volatile("s_waitcnt lgkmcnt(" #n ")" ::: "memory")
; #define PG8_BAR __builtin_amdgcn_s_barrier()
; #define PG8_SCHED __builtin_amdgcn_sched_barrier(0)
; template <class Epi, class Sched, bool ALIGN_EPI = false, bool SP2 = false>
; __device__ __forceinline__ void gemm_phase(PG8_LAS unsigned char* lds, const Gemm g, const Sched& S, const Epi& E) {
;     ...
;             PG8_LDB(B0, 0, 0); PG8_LDB(B1, 0, 1); PG8_SCHED; PG8_LDA(At, 0, 0); PG8_STAGE(PG8_SA(1, 1), a1 + hstepA, voffA);
;             PG8_WAIT_V(8); PG8_WAIT_L(0); PG8_BAR; PG8_MMA(0, 0, At, B0); PG8_MMA(0, 1, At, B1); PG8_BAR; PG8_SCHED;
;             PG8_LDA(At, 0, 1); PG8_STAGE(PG8_SB(0, 0), b2, voffB); PG8_STAGE(PG8_SB(0, 1), b2 + hstepB, voffB); PG8_STAGE(PG8_SA(0, 0), a2, voffA);
;             PG8_WAIT_V(8); PG8_WAIT_L(0); PG8_BAR; PG8_MMA(1, 0, At, B0); PG8_MMA(1, 1, At, B1); PG8_BAR; PG8_SCHED;
.LBB0_1257:
	ds_read_b128 v[112:115], v199
	ds_read_b128 v[116:119], v199 offset:1024
	ds_read_b128 v[128:131], v199 offset:2048
	ds_read_b128 v[132:135], v199 offset:3072
	ds_read_b128 v[136:139], v203
	ds_read_b128 v[148:151], v203 offset:1024
	ds_read_b128 v[152:155], v203 offset:2048
	ds_read_b128 v[156:159], v203 offset:3072
	s_add_i32 s68, s48, 2
	s_add_u32 s49, s46, 0xfffc0080
	s_addc_u32 s50, s47, -1
	s_cmp_eq_u32 s58, s48
	s_cselect_b32 s48, s65, s66
	s_cselect_b32 s51, s35, s50
	s_cselect_b32 s50, s37, s49
	s_cselect_b32 s49, s64, s67
	v_lshl_add_u64 v[176:177], s[46:47], 0, v[168:169]
	s_add_i32 m0, s20, 0xc000
	ds_read_b128 v[180:183], v217
	ds_read_b128 v[186:189], v217 offset:1024
	ds_read_b128 v[192:195], v217 offset:2048
	ds_read_b128 v[204:207], v217 offset:3072
	ds_read_b128 v[208:211], v217 offset:4096
	ds_read_b128 v[212:215], v217 offset:5120
	ds_read_b128 v[218:221], v217 offset:6144
	ds_read_b128 v[222:225], v217 offset:7168
	global_load_lds_dwordx4 v[176:177], off
	v_lshl_add_u64 v[176:177], s[46:47], 0, v[170:171]
	s_add_i32 m0, s20, 0xe000
	s_nop 0
	global_load_lds_dwordx4 v[176:177], off
	s_waitcnt vmcnt(8)
	s_waitcnt lgkmcnt(0)
	s_barrier
	s_waitcnt lgkmcnt(0)
	v_mfma_f32_16x16x32_bf16 v[140:143], v[112:115], v[180:183], v[140:143]
	v_mfma_f32_16x16x32_bf16 v[120:123], v[128:131], v[180:183], v[120:123]
	v_mfma_f32_16x16x32_bf16 v[104:107], v[112:115], v[192:195], v[104:107]
	v_mfma_f32_16x16x32_bf16 v[96:99], v[128:131], v[192:195], v[96:99]
	v_mfma_f32_16x16x32_bf16 v[88:91], v[112:115], v[208:211], v[88:91]
	v_mfma_f32_16x16x32_bf16 v[80:83], v[128:131], v[208:211], v[80:83]
	v_mfma_f32_16x16x32_bf16 v[72:75], v[112:115], v[218:221], v[72:75]
	v_mfma_f32_16x16x32_bf16 v[64:67], v[128:131], v[218:221], v[64:67]
	v_mfma_f32_16x16x32_bf16 v[140:143], v[116:119], v[186:189], v[140:143]
	v_mfma_f32_16x16x32_bf16 v[120:123], v[132:135], v[186:189], v[120:123]
	v_mfma_f32_16x16x32_bf16 v[104:107], v[116:119], v[204:207], v[104:107]
	v_mfma_f32_16x16x32_bf16 v[96:99], v[132:135], v[204:207], v[96:99]
	v_mfma_f32_16x16x32_bf16 v[88:91], v[116:119], v[212:215], v[88:91]
	v_mfma_f32_16x16x32_bf16 v[80:83], v[132:135], v[212:215], v[80:83]
	v_mfma_f32_16x16x32_bf16 v[72:75], v[116:119], v[222:225], v[72:75]
	v_mfma_f32_16x16x32_bf16 v[64:67], v[132:135], v[222:225], v[64:67]
	v_mfma_f32_16x16x32_bf16 v[144:147], v[136:139], v[180:183], v[144:147]
	v_mfma_f32_16x16x32_bf16 v[124:127], v[152:155], v[180:183], v[124:127]
	v_mfma_f32_16x16x32_bf16 v[108:111], v[136:139], v[192:195], v[108:111]
	v_mfma_f32_16x16x32_bf16 v[100:103], v[152:155], v[192:195], v[100:103]
	v_mfma_f32_16x16x32_bf16 v[92:95], v[136:139], v[208:211], v[92:95]
	v_mfma_f32_16x16x32_bf16 v[84:87], v[152:155], v[208:211], v[84:87]
	v_mfma_f32_16x16x32_bf16 v[76:79], v[136:139], v[218:221], v[76:79]
	v_mfma_f32_16x16x32_bf16 v[68:71], v[152:155], v[218:221], v[68:71]
	v_mfma_f32_16x16x32_bf16 v[144:147], v[148:151], v[186:189], v[144:147]
	v_mfma_f32_16x16x32_bf16 v[124:127], v[156:159], v[186:189], v[124:127]
	v_mfma_f32_16x16x32_bf16 v[108:111], v[148:151], v[204:207], v[108:111]
	v_mfma_f32_16x16x32_bf16 v[100:103], v[156:159], v[204:207], v[100:103]
	v_mfma_f32_16x16x32_bf16 v[92:95], v[148:151], v[212:215], v[92:95]
	v_mfma_f32_16x16x32_bf16 v[84:87], v[156:159], v[212:215], v[84:87]
	v_mfma_f32_16x16x32_bf16 v[76:79], v[148:151], v[222:225], v[76:79]
	v_mfma_f32_16x16x32_bf16 v[68:71], v[156:159], v[222:225], v[68:71]
	s_barrier
	s_add_i32 s69, s62, s17
	v_lshl_add_u64 v[176:177], s[48:49], 0, v[164:165]
	s_mov_b32 m0, s69
	ds_read_b128 v[180:183], v217 offset:16384
	ds_read_b128 v[186:189], v217 offset:17408
	ds_read_b128 v[192:195], v217 offset:18432
	ds_read_b128 v[204:207], v217 offset:19456
	ds_read_b128 v[208:211], v217 offset:20480
	ds_read_b128 v[212:215], v217 offset:21504
	ds_read_b128 v[218:221], v217 offset:22528
	ds_read_b128 v[222:225], v217 offset:23552
	global_load_lds_dwordx4 v[176:177], off
	s_add_i32 m0, s69, 0x2000
	s_add_u32 s70, s48, 0x40000
	v_lshl_add_u64 v[196:197], s[48:49], 0, v[160:161]
	s_addc_u32 s71, s49, 0
	s_add_i32 s69, s63, s17
	global_load_lds_dwordx4 v[196:197], off
	v_lshl_add_u64 v[200:201], s[70:71], 0, v[164:165]
	s_mov_b32 m0, s69
	v_lshl_add_u64 v[226:227], s[50:51], 0, v[162:163]
	global_load_lds_dwordx4 v[200:201], off
	v_lshl_add_u64 v[200:201], s[70:71], 0, v[160:161]
	s_add_i32 m0, s69, 0x2000
	s_nop 0
	global_load_lds_dwordx4 v[200:201], off
	v_lshl_add_u64 v[200:201], s[50:51], 0, v[166:167]
	s_mov_b32 m0, s20
	s_nop 0
	global_load_lds_dwordx4 v[200:201], off
	s_mov_b32 m0, s21
	s_nop 0
	global_load_lds_dwordx4 v[226:227], off
	s_waitcnt vmcnt(8)
	s_waitcnt lgkmcnt(0)
	s_barrier
; #define PG8_STAGE(bufoff, gbase, voff) do { _Pragma("unroll") for (int _i = 0; _i < 2; ++_i) \
;         __builtin_amdgcn_global_load_lds((const unsigned*)((const char*)(gbase) + (voff)[_i]), (PG8_LAS unsigned*)(lds + (bufoff) + ldsw + _i * 8192), 16, 0, 0); } while (0)
; #define PG8_LDA(dst, b, h) do { _Pragma("unroll") for (int m = 0; m < 4; ++m) _Pragma("unroll") for (int k = 0; k < 2; ++k) dst[m][k] = *(const PG8_LAS bf16x8*)(lds + PG8_SA(b, h) + aoff + m * 2048 + k * 1024); } while (0)
; #define PG8_LDB(dst, b, h) do { _Pragma("unroll") for (int n = 0; n < 2; ++n) _Pragma("unroll") for (int k = 0; k < 2; ++k) dst[n][k] = *(const PG8_LAS bf16x8*)(lds + PG8_SB(b, h) + boff + n * 2048 + k * 1024); } while (0)
; #define PG8_MMA(ai, bj, At, Bt) do { __builtin_amdgcn_s_setprio(1); _Pragma("unroll") for (int m = 0; m < 4; ++m) _Pragma("unroll") for (int n = 0; n < 2; ++n) _Pragma("unroll") for (int k = 0; k < 2; ++k) \
;         acc[ai][bj][m][n] = __builtin_amdgcn_mfma_f32_16x16x32_bf16(Bt[n][k], At[m][k], acc[ai][bj][m][n], 0, 0, 0); __builtin_amdgcn_s_setprio(0); } while (0)
; #define PG8_WAIT_V(n) asm volatile("s_waitcnt vmcnt(" #n ")" ::: "memory")
; #define PG8_WAIT_L(n) asm volatile("s_waitcnt lgkmcnt(" #n ")" ::: "memory")
; #define PG8_BAR __builtin_amdgcn_s_barrier()
; #define PG8_SCHED __builtin_amdgcn_sched_barrier(0)
; template <class Epi, class Sched, bool ALIGN_EPI = false, bool SP2 = false>
; __device__ __forceinline__ void gemm_phase(PG8_LAS unsigned char* lds, const Gemm g, const Sched& S, const Epi& E) {
;     ...
;             PG8_WAIT_V(8); PG8_WAIT_L(0); PG8_BAR; PG8_MMA(1, 0, At, B0); PG8_MMA(1, 1, At, B1); PG8_BAR; PG8_SCHED;
;             PG8_LDB(B0, 1, 0); PG8_LDB(B1, 1, 1); PG8_SCHED; PG8_LDA(At, 1, 0); PG8_STAGE(PG8_SA(0, 1), a2 + hstepA, voffA);
;             PG8_WAIT_V(8); PG8_WAIT_L(0); PG8_BAR; PG8_MMA(0, 0, At, B0); PG8_MMA(0, 1, At, B1); PG8_BAR; PG8_SCHED;
	s_waitcnt lgkmcnt(0)
	v_mfma_f32_16x16x32_bf16 v[56:59], v[112:115], v[180:183], v[56:59]
	v_mfma_f32_16x16x32_bf16 v[48:51], v[128:131], v[180:183], v[48:51]
	v_mfma_f32_16x16x32_bf16 v[40:43], v[112:115], v[192:195], v[40:43]
	v_mfma_f32_16x16x32_bf16 v[32:35], v[128:131], v[192:195], v[32:35]
	v_mfma_f32_16x16x32_bf16 v[24:27], v[112:115], v[208:211], v[24:27]
	v_mfma_f32_16x16x32_bf16 v[16:19], v[128:131], v[208:211], v[16:19]
	v_mfma_f32_16x16x32_bf16 v[8:11], v[112:115], v[218:221], v[8:11]
	v_mfma_f32_16x16x32_bf16 v[4:7], v[128:131], v[218:221], v[4:7]
	v_mfma_f32_16x16x32_bf16 v[56:59], v[116:119], v[186:189], v[56:59]
	v_mfma_f32_16x16x32_bf16 v[48:51], v[132:135], v[186:189], v[48:51]
	v_mfma_f32_16x16x32_bf16 v[40:43], v[116:119], v[204:207], v[40:43]
	v_mfma_f32_16x16x32_bf16 v[32:35], v[132:135], v[204:207], v[32:35]
	v_mfma_f32_16x16x32_bf16 v[24:27], v[116:119], v[212:215], v[24:27]
	v_mfma_f32_16x16x32_bf16 v[16:19], v[132:135], v[212:215], v[16:19]
	v_mfma_f32_16x16x32_bf16 v[8:11], v[116:119], v[222:225], v[8:11]
	v_mfma_f32_16x16x32_bf16 v[4:7], v[132:135], v[222:225], v[4:7]
	v_mfma_f32_16x16x32_bf16 v[60:63], v[136:139], v[180:183], v[60:63]
	v_mfma_f32_16x16x32_bf16 v[52:55], v[152:155], v[180:183], v[52:55]
	v_mfma_f32_16x16x32_bf16 v[44:47], v[136:139], v[192:195], v[44:47]
	v_mfma_f32_16x16x32_bf16 v[36:39], v[152:155], v[192:195], v[36:39]
	v_mfma_f32_16x16x32_bf16 v[28:31], v[136:139], v[208:211], v[28:31]
	v_mfma_f32_16x16x32_bf16 v[20:23], v[152:155], v[208:211], v[20:23]
	v_mfma_f32_16x16x32_bf16 v[12:15], v[136:139], v[218:221], v[12:15]
	v_mfma_f32_16x16x32_bf16 v[0:3], v[152:155], v[218:221], v[0:3]
	v_mfma_f32_16x16x32_bf16 v[60:63], v[148:151], v[186:189], v[60:63]
	v_mfma_f32_16x16x32_bf16 v[52:55], v[156:159], v[186:189], v[52:55]
	v_mfma_f32_16x16x32_bf16 v[44:47], v[148:151], v[204:207], v[44:47]
	v_mfma_f32_16x16x32_bf16 v[36:39], v[156:159], v[204:207], v[36:39]
	v_mfma_f32_16x16x32_bf16 v[28:31], v[148:151], v[212:215], v[28:31]
	v_mfma_f32_16x16x32_bf16 v[20:23], v[156:159], v[212:215], v[20:23]
	v_mfma_f32_16x16x32_bf16 v[12:15], v[148:151], v[222:225], v[12:15]
	v_mfma_f32_16x16x32_bf16 v[0:3], v[156:159], v[222:225], v[0:3]
	s_barrier
	s_add_i32 s69, 0, 0x18000
	s_add_i32 s70, 0, 0x1c000
	v_add_u32_e32 v132, s69, v191
	v_add_u32_e32 v156, s70, v191
	ds_read_b128 v[112:115], v132
	ds_read_b128 v[116:119], v132 offset:1024
	ds_read_b128 v[128:131], v132 offset:2048
	ds_read_b128 v[132:135], v132 offset:3072
	ds_read_b128 v[136:139], v156
	ds_read_b128 v[148:151], v156 offset:1024
	ds_read_b128 v[152:155], v156 offset:2048
	ds_read_b128 v[156:159], v156 offset:3072
	s_add_u32 s50, s50, 0x40000
	s_addc_u32 s51, s51, 0
	s_mov_b32 m0, s31
	v_lshl_add_u64 v[228:229], s[50:51], 0, v[166:167]
	ds_read_b128 v[180:183], v217 offset:32768
	ds_read_b128 v[186:189], v217 offset:33792
	ds_read_b128 v[192:195], v217 offset:34816
	ds_read_b128 v[204:207], v217 offset:35840
	ds_read_b128 v[208:211], v217 offset:36864
	ds_read_b128 v[212:215], v217 offset:37888
	ds_read_b128 v[218:221], v217 offset:38912
	ds_read_b128 v[222:225], v217 offset:39936
	global_load_lds_dwordx4 v[228:229], off
	v_lshl_add_u64 v[228:229], s[50:51], 0, v[162:163]
	s_mov_b32 m0, s33
	s_nop 0
	global_load_lds_dwordx4 v[228:229], off
	s_waitcnt vmcnt(8)
	s_waitcnt lgkmcnt(0)
	s_barrier
	s_waitcnt lgkmcnt(0)
	v_mfma_f32_16x16x32_bf16 v[140:143], v[112:115], v[180:183], v[140:143]
	v_mfma_f32_16x16x32_bf16 v[120:123], v[128:131], v[180:183], v[120:123]
	v_mfma_f32_16x16x32_bf16 v[104:107], v[112:115], v[192:195], v[104:107]
	v_mfma_f32_16x16x32_bf16 v[96:99], v[128:131], v[192:195], v[96:99]
	v_mfma_f32_16x16x32_bf16 v[88:91], v[112:115], v[208:211], v[88:91]
	v_mfma_f32_16x16x32_bf16 v[80:83], v[128:131], v[208:211], v[80:83]
	v_mfma_f32_16x16x32_bf16 v[72:75], v[112:115], v[218:221], v[72:75]
	v_mfma_f32_16x16x32_bf16 v[64:67], v[128:131], v[218:221], v[64:67]
	v_mfma_f32_16x16x32_bf16 v[140:143], v[116:119], v[186:189], v[140:143]
	v_mfma_f32_16x16x32_bf16 v[120:123], v[132:135], v[186:189], v[120:123]
	v_mfma_f32_16x16x32_bf16 v[104:107], v[116:119], v[204:207], v[104:107]
	v_mfma_f32_16x16x32_bf16 v[96:99], v[132:135], v[204:207], v[96:99]
	v_mfma_f32_16x16x32_bf16 v[88:91], v[116:119], v[212:215], v[88:91]
	v_mfma_f32_16x16x32_bf16 v[80:83], v[132:135], v[212:215], v[80:83]
	v_mfma_f32_16x16x32_bf16 v[72:75], v[116:119], v[222:225], v[72:75]
	v_mfma_f32_16x16x32_bf16 v[64:67], v[132:135], v[222:225], v[64:67]
	v_mfma_f32_16x16x32_bf16 v[144:147], v[136:139], v[180:183], v[144:147]
	v_mfma_f32_16x16x32_bf16 v[124:127], v[152:155], v[180:183], v[124:127]
	v_mfma_f32_16x16x32_bf16 v[108:111], v[136:139], v[192:195], v[108:111]
	v_mfma_f32_16x16x32_bf16 v[100:103], v[152:155], v[192:195], v[100:103]
	v_mfma_f32_16x16x32_bf16 v[92:95], v[136:139], v[208:211], v[92:95]
	v_mfma_f32_16x16x32_bf16 v[84:87], v[152:155], v[208:211], v[84:87]
	v_mfma_f32_16x16x32_bf16 v[76:79], v[136:139], v[218:221], v[76:79]
	v_mfma_f32_16x16x32_bf16 v[68:71], v[152:155], v[218:221], v[68:71]
	v_mfma_f32_16x16x32_bf16 v[144:147], v[148:151], v[186:189], v[144:147]
	v_mfma_f32_16x16x32_bf16 v[124:127], v[156:159], v[186:189], v[124:127]
	v_mfma_f32_16x16x32_bf16 v[108:111], v[148:151], v[204:207], v[108:111]
	v_mfma_f32_16x16x32_bf16 v[100:103], v[156:159], v[204:207], v[100:103]
	v_mfma_f32_16x16x32_bf16 v[92:95], v[148:151], v[212:215], v[92:95]
	v_mfma_f32_16x16x32_bf16 v[84:87], v[156:159], v[212:215], v[84:87]
	v_mfma_f32_16x16x32_bf16 v[76:79], v[148:151], v[222:225], v[76:79]
	v_mfma_f32_16x16x32_bf16 v[68:71], v[156:159], v[222:225], v[68:71]
	s_barrier
; #define PG8_STAGE(bufoff, gbase, voff) do { _Pragma("unroll") for (int _i = 0; _i < 2; ++_i) \
;         __builtin_amdgcn_global_load_lds((const unsigned*)((const char*)(gbase) + (voff)[_i]), (PG8_LAS unsigned*)(lds + (bufoff) + ldsw + _i * 8192), 16, 0, 0); } while (0)
; #define PG8_LDA(dst, b, h) do { _Pragma("unroll") for (int m = 0; m < 4; ++m) _Pragma("unroll") for (int k = 0; k < 2; ++k) dst[m][k] = *(const PG8_LAS bf16x8*)(lds + PG8_SA(b, h) + aoff + m * 2048 + k * 1024); } while (0)
; #define PG8_MMA(ai, bj, At, Bt) do { __builtin_amdgcn_s_setprio(1); _Pragma("unroll") for (int m = 0; m < 4; ++m) _Pragma("unroll") for (int n = 0; n < 2; ++n) _Pragma("unroll") for (int k = 0; k < 2; ++k) \
;         acc[ai][bj][m][n] = __builtin_amdgcn_mfma_f32_16x16x32_bf16(Bt[n][k], At[m][k], acc[ai][bj][m][n], 0, 0, 0); __builtin_amdgcn_s_setprio(0); } while (0)
; #define PG8_WAIT_V(n) asm volatile("s_waitcnt vmcnt(" #n ")" ::: "memory")
; #define PG8_WAIT_L(n) asm volatile("s_waitcnt lgkmcnt(" #n ")" ::: "memory")
; #define PG8_BAR __builtin_amdgcn_s_barrier()
; #define PG8_SCHED __builtin_amdgcn_sched_barrier(0)
; template <class Epi, class Sched, bool ALIGN_EPI = false, bool SP2 = false>
; __device__ __forceinline__ void gemm_phase(PG8_LAS unsigned char* lds, const Gemm g, const Sched& S, const Epi& E) {
;     ...
;         for (int t = 0; t < nt; t += 2) {
;             const bool last = (t == nt - 2);
;             const char* a1 = cA + (long)(t + 1) * kstepA;
;             const char* a2 = last ? nA : cA + (long)(t + 2) * kstepA; const char* b2 = last ? nB : cB + (long)(t + 2) * kstep;
;             const char* a3 = a2 + kstepA; const char* b3 = b2 + kstep;
;             if (last && has_next) S.a_ready(nxt);
;     ...
;             PG8_LDA(At, 1, 1); PG8_STAGE(PG8_SB(1, 0), b3, voffB); PG8_STAGE(PG8_SB(1, 1), b3 + hstepB, voffB); PG8_STAGE(PG8_SA(1, 0), a3, voffA);
;             PG8_WAIT_V(8); PG8_WAIT_L(0); PG8_BAR; PG8_MMA(1, 0, At, B0); PG8_MMA(1, 1, At, B1); PG8_BAR; PG8_SCHED;
	s_add_i32 s50, s69, s17
	v_lshl_add_u64 v[176:177], v[176:177], 0, s[24:25]
	s_mov_b32 m0, s50
	ds_read_b128 v[180:183], v217 offset:49152
	ds_read_b128 v[186:189], v217 offset:50176
	ds_read_b128 v[192:195], v217 offset:51200
	ds_read_b128 v[204:207], v217 offset:52224
	ds_read_b128 v[208:211], v217 offset:53248
	ds_read_b128 v[212:215], v217 offset:54272
	ds_read_b128 v[218:221], v217 offset:55296
	ds_read_b128 v[222:225], v217 offset:56320
	global_load_lds_dwordx4 v[176:177], off
	s_add_i32 m0, s50, 0x2000
	s_add_u32 s48, s48, 0x40080
	v_lshl_add_u64 v[176:177], v[196:197], 0, s[24:25]
	s_addc_u32 s49, s49, 0
	s_add_i32 s50, s70, s17
	global_load_lds_dwordx4 v[176:177], off
	v_lshl_add_u64 v[176:177], s[48:49], 0, v[164:165]
	s_mov_b32 m0, s50
	s_nop 0
	global_load_lds_dwordx4 v[176:177], off
	v_lshl_add_u64 v[176:177], s[48:49], 0, v[160:161]
	s_add_i32 m0, s50, 0x2000
	s_nop 0
	global_load_lds_dwordx4 v[176:177], off
	v_lshl_add_u64 v[176:177], v[200:201], 0, s[24:25]
	s_mov_b32 m0, s56
	s_nop 0
	global_load_lds_dwordx4 v[176:177], off
	v_lshl_add_u64 v[176:177], v[226:227], 0, s[24:25]
	s_mov_b32 m0, s57
	s_nop 0
	global_load_lds_dwordx4 v[176:177], off
	s_waitcnt vmcnt(8)
	s_waitcnt lgkmcnt(0)
	s_barrier
	s_waitcnt lgkmcnt(0)
	v_mfma_f32_16x16x32_bf16 v[56:59], v[112:115], v[180:183], v[56:59]
	v_mfma_f32_16x16x32_bf16 v[48:51], v[128:131], v[180:183], v[48:51]
	v_mfma_f32_16x16x32_bf16 v[40:43], v[112:115], v[192:195], v[40:43]
	v_mfma_f32_16x16x32_bf16 v[32:35], v[128:131], v[192:195], v[32:35]
	v_mfma_f32_16x16x32_bf16 v[24:27], v[112:115], v[208:211], v[24:27]
	v_mfma_f32_16x16x32_bf16 v[16:19], v[128:131], v[208:211], v[16:19]
	v_mfma_f32_16x16x32_bf16 v[8:11], v[112:115], v[218:221], v[8:11]
	v_mfma_f32_16x16x32_bf16 v[4:7], v[128:131], v[218:221], v[4:7]
	v_mfma_f32_16x16x32_bf16 v[56:59], v[116:119], v[186:189], v[56:59]
	v_mfma_f32_16x16x32_bf16 v[48:51], v[132:135], v[186:189], v[48:51]
	v_mfma_f32_16x16x32_bf16 v[40:43], v[116:119], v[204:207], v[40:43]
	v_mfma_f32_16x16x32_bf16 v[32:35], v[132:135], v[204:207], v[32:35]
	v_mfma_f32_16x16x32_bf16 v[24:27], v[116:119], v[212:215], v[24:27]
	v_mfma_f32_16x16x32_bf16 v[16:19], v[132:135], v[212:215], v[16:19]
	v_mfma_f32_16x16x32_bf16 v[8:11], v[116:119], v[222:225], v[8:11]
	v_mfma_f32_16x16x32_bf16 v[4:7], v[132:135], v[222:225], v[4:7]
	v_mfma_f32_16x16x32_bf16 v[60:63], v[136:139], v[180:183], v[60:63]
	v_mfma_f32_16x16x32_bf16 v[52:55], v[152:155], v[180:183], v[52:55]
	v_mfma_f32_16x16x32_bf16 v[44:47], v[136:139], v[192:195], v[44:47]
	v_mfma_f32_16x16x32_bf16 v[36:39], v[152:155], v[192:195], v[36:39]
	v_mfma_f32_16x16x32_bf16 v[28:31], v[136:139], v[208:211], v[28:31]
	v_mfma_f32_16x16x32_bf16 v[20:23], v[152:155], v[208:211], v[20:23]
	v_mfma_f32_16x16x32_bf16 v[12:15], v[136:139], v[218:221], v[12:15]
	v_mfma_f32_16x16x32_bf16 v[0:3], v[152:155], v[218:221], v[0:3]
	v_mfma_f32_16x16x32_bf16 v[60:63], v[148:151], v[186:189], v[60:63]
	v_mfma_f32_16x16x32_bf16 v[52:55], v[156:159], v[186:189], v[52:55]
	v_mfma_f32_16x16x32_bf16 v[44:47], v[148:151], v[204:207], v[44:47]
	v_mfma_f32_16x16x32_bf16 v[36:39], v[156:159], v[204:207], v[36:39]
	v_mfma_f32_16x16x32_bf16 v[28:31], v[148:151], v[212:215], v[28:31]
	v_mfma_f32_16x16x32_bf16 v[20:23], v[156:159], v[212:215], v[20:23]
	v_mfma_f32_16x16x32_bf16 v[12:15], v[148:151], v[222:225], v[12:15]
	v_mfma_f32_16x16x32_bf16 v[0:3], v[156:159], v[222:225], v[0:3]
	s_barrier
	s_add_u32 s46, s46, 0x100
	s_addc_u32 s47, s47, 0
	s_add_u32 s66, s66, 0x100
	s_addc_u32 s67, s67, 0
	s_cmp_ge_i32 s68, s53
	s_mov_b32 s48, s68
	s_cbranch_scc0 .LBB0_1257

; #define PG8_STAGE(bufoff, gbase, voff) do { _Pragma("unroll") for (int _i = 0; _i < 2; ++_i) \
;         __builtin_amdgcn_global_load_lds((const unsigned*)((const char*)(gbase) + (voff)[_i]), (PG8_LAS unsigned*)(lds + (bufoff) + ldsw + _i * 8192), 16, 0, 0); } while (0)
; #define PG8_LDA(dst, b, h) do { _Pragma("unroll") for (int m = 0; m < 4; ++m) _Pragma("unroll") for (int k = 0; k < 2; ++k) dst[m][k] = *(const PG8_LAS bf16x8*)(lds + PG8_SA(b, h) + aoff + m * 2048 + k * 1024); } while (0)
; #define PG8_LDB(dst, b, h) do { _Pragma("unroll") for (int n = 0; n < 2; ++n) _Pragma("unroll") for (int k = 0; k < 2; ++k) dst[n][k] = *(const PG8_LAS bf16x8*)(lds + PG8_SB(b, h) + boff + n * 2048 + k * 1024); } while (0)
; #define PG8_MMA(ai, bj, At, Bt) do { __builtin_amdgcn_s_setprio(1); _Pragma("unroll") for (int m = 0; m < 4; ++m) _Pragma("unroll") for (int n = 0; n < 2; ++n) _Pragma("unroll") for (int k = 0; k < 2; ++k) \
;         acc[ai][bj][m][n] = __builtin_amdgcn_mfma_f32_16x16x32_bf16(Bt[n][k], At[m][k], acc[ai][bj][m][n], 0, 0, 0); __builtin_amdgcn_s_setprio(0); } while (0)
; #define PG8_WAIT_V(n) asm volatile("s_waitcnt vmcnt(" #n ")" ::: "memory")
; #define PG8_WAIT_L(n) asm volatile("s_waitcnt lgkmcnt(" #n ")" ::: "memory")
; #define PG8_BAR __builtin_amdgcn_s_barrier()
; #define PG8_SCHED __builtin_amdgcn_sched_barrier(0)
; template <class Epi, class Sched, bool ALIGN_EPI = false, bool SP2 = false>
; __device__ __forceinline__ void gemm_phase(PG8_LAS unsigned char* lds, const Gemm g, const Sched& S, const Epi& E) {
;     ...
;             PG8_LDB(B0, 0, 0); PG8_LDB(B1, 0, 1); PG8_SCHED; PG8_LDA(At, 0, 0); PG8_STAGE(PG8_SA(1, 1), a1 + hstepA, voffA);
;             PG8_WAIT_V(8); PG8_WAIT_L(0); PG8_BAR; PG8_MMA(0, 0, At, B0); PG8_MMA(0, 1, At, B1); PG8_BAR; PG8_SCHED;
;             PG8_LDA(At, 0, 1); PG8_STAGE(PG8_SB(0, 0), b2, voffB); PG8_STAGE(PG8_SB(0, 1), b2 + hstepB, voffB); PG8_STAGE(PG8_SA(0, 0), a2, voffA);
;             PG8_WAIT_V(8); PG8_WAIT_L(0); PG8_BAR; PG8_MMA(1, 0, At, B0); PG8_MMA(1, 1, At, B1); PG8_BAR; PG8_SCHED;
.LBB0_1333:
	ds_read_b128 v[144:147], v155
	ds_read_b128 v[148:151], v155 offset:1024
	ds_read_b128 v[158:161], v155 offset:2048
	ds_read_b128 v[162:165], v155 offset:3072
	ds_read_b128 v[166:169], v156
	ds_read_b128 v[170:173], v156 offset:1024
	ds_read_b128 v[174:177], v156 offset:2048
	ds_read_b128 v[178:181], v156 offset:3072
	s_add_i32 s66, s48, 2
	s_add_u32 s49, s46, 0xffff0080
	s_addc_u32 s50, s47, -1
	s_cmp_eq_u32 s59, s48
	s_cselect_b32 s48, s63, s64
	s_cselect_b32 s51, s9, s50
	s_cselect_b32 s50, s37, s49
	s_cselect_b32 s49, s41, s65
	v_lshl_add_u64 v[214:215], s[46:47], 0, v[136:137]
	s_add_i32 m0, s20, 0xc000
	ds_read_b128 v[182:185], v157
	ds_read_b128 v[186:189], v157 offset:1024
	ds_read_b128 v[190:193], v157 offset:2048
	ds_read_b128 v[194:197], v157 offset:3072
	ds_read_b128 v[198:201], v157 offset:4096
	ds_read_b128 v[202:205], v157 offset:5120
	ds_read_b128 v[206:209], v157 offset:6144
	ds_read_b128 v[210:213], v157 offset:7168
	global_load_lds_dwordx4 v[214:215], off
	v_lshl_add_u64 v[214:215], s[46:47], 0, v[138:139]
	s_add_i32 m0, s20, 0xe000
	s_nop 0
	global_load_lds_dwordx4 v[214:215], off
	s_waitcnt vmcnt(8)
	s_waitcnt lgkmcnt(0)
	s_barrier
	s_waitcnt lgkmcnt(0)
	v_mfma_f32_16x16x32_bf16 v[124:127], v[144:147], v[182:185], v[124:127]
	v_mfma_f32_16x16x32_bf16 v[120:123], v[158:161], v[182:185], v[120:123]
	v_mfma_f32_16x16x32_bf16 v[116:119], v[144:147], v[190:193], v[116:119]
	v_mfma_f32_16x16x32_bf16 v[112:115], v[158:161], v[190:193], v[112:115]
	v_mfma_f32_16x16x32_bf16 v[104:107], v[144:147], v[198:201], v[104:107]
	v_mfma_f32_16x16x32_bf16 v[96:99], v[158:161], v[198:201], v[96:99]
	v_mfma_f32_16x16x32_bf16 v[88:91], v[144:147], v[206:209], v[88:91]
	v_mfma_f32_16x16x32_bf16 v[80:83], v[158:161], v[206:209], v[80:83]
	v_mfma_f32_16x16x32_bf16 v[124:127], v[148:151], v[186:189], v[124:127]
	v_mfma_f32_16x16x32_bf16 v[120:123], v[162:165], v[186:189], v[120:123]
	v_mfma_f32_16x16x32_bf16 v[116:119], v[148:151], v[194:197], v[116:119]
	v_mfma_f32_16x16x32_bf16 v[112:115], v[162:165], v[194:197], v[112:115]
	v_mfma_f32_16x16x32_bf16 v[104:107], v[148:151], v[202:205], v[104:107]
	v_mfma_f32_16x16x32_bf16 v[96:99], v[162:165], v[202:205], v[96:99]
	v_mfma_f32_16x16x32_bf16 v[88:91], v[148:151], v[210:213], v[88:91]
	v_mfma_f32_16x16x32_bf16 v[80:83], v[162:165], v[210:213], v[80:83]
	v_mfma_f32_16x16x32_bf16 v[108:111], v[166:169], v[182:185], v[108:111]
	v_mfma_f32_16x16x32_bf16 v[100:103], v[174:177], v[182:185], v[100:103]
	v_mfma_f32_16x16x32_bf16 v[92:95], v[166:169], v[190:193], v[92:95]
	v_mfma_f32_16x16x32_bf16 v[84:87], v[174:177], v[190:193], v[84:87]
	v_mfma_f32_16x16x32_bf16 v[76:79], v[166:169], v[198:201], v[76:79]
	v_mfma_f32_16x16x32_bf16 v[72:75], v[174:177], v[198:201], v[72:75]
	v_mfma_f32_16x16x32_bf16 v[68:71], v[166:169], v[206:209], v[68:71]
	v_mfma_f32_16x16x32_bf16 v[64:67], v[174:177], v[206:209], v[64:67]
	v_mfma_f32_16x16x32_bf16 v[108:111], v[170:173], v[186:189], v[108:111]
	v_mfma_f32_16x16x32_bf16 v[100:103], v[178:181], v[186:189], v[100:103]
	v_mfma_f32_16x16x32_bf16 v[92:95], v[170:173], v[194:197], v[92:95]
	v_mfma_f32_16x16x32_bf16 v[84:87], v[178:181], v[194:197], v[84:87]
	v_mfma_f32_16x16x32_bf16 v[76:79], v[170:173], v[202:205], v[76:79]
	v_mfma_f32_16x16x32_bf16 v[72:75], v[178:181], v[202:205], v[72:75]
	v_mfma_f32_16x16x32_bf16 v[68:71], v[170:173], v[210:213], v[68:71]
	v_mfma_f32_16x16x32_bf16 v[64:67], v[178:181], v[210:213], v[64:67]
	s_barrier
	s_add_i32 s67, s61, s19
	v_lshl_add_u64 v[214:215], s[48:49], 0, v[130:131]
	s_mov_b32 m0, s67
	ds_read_b128 v[182:185], v157 offset:16384
	ds_read_b128 v[186:189], v157 offset:17408
	ds_read_b128 v[190:193], v157 offset:18432
	ds_read_b128 v[194:197], v157 offset:19456
	ds_read_b128 v[198:201], v157 offset:20480
	ds_read_b128 v[202:205], v157 offset:21504
	ds_read_b128 v[206:209], v157 offset:22528
	ds_read_b128 v[210:213], v157 offset:23552
	global_load_lds_dwordx4 v[214:215], off
	s_add_i32 m0, s67, 0x2000
	s_add_u32 s68, s48, 0x10000
	v_lshl_add_u64 v[216:217], s[48:49], 0, v[134:135]
	s_addc_u32 s69, s49, 0
	s_add_i32 s67, s62, s19
	global_load_lds_dwordx4 v[216:217], off
	v_lshl_add_u64 v[218:219], s[68:69], 0, v[130:131]
	s_mov_b32 m0, s67
	v_lshl_add_u64 v[220:221], s[50:51], 0, v[132:133]
	global_load_lds_dwordx4 v[218:219], off
	v_lshl_add_u64 v[218:219], s[68:69], 0, v[134:135]
	s_add_i32 m0, s67, 0x2000
	s_nop 0
	global_load_lds_dwordx4 v[218:219], off
	v_lshl_add_u64 v[218:219], s[50:51], 0, v[128:129]
	s_mov_b32 m0, s20
	s_nop 0
	global_load_lds_dwordx4 v[218:219], off
	s_mov_b32 m0, s21
	s_nop 0
	global_load_lds_dwordx4 v[220:221], off
	s_waitcnt vmcnt(8)
	s_waitcnt lgkmcnt(0)
	s_barrier
; #define PG8_STAGE(bufoff, gbase, voff) do { _Pragma("unroll") for (int _i = 0; _i < 2; ++_i) \
;         __builtin_amdgcn_global_load_lds((const unsigned*)((const char*)(gbase) + (voff)[_i]), (PG8_LAS unsigned*)(lds + (bufoff) + ldsw + _i * 8192), 16, 0, 0); } while (0)
; #define PG8_LDA(dst, b, h) do { _Pragma("unroll") for (int m = 0; m < 4; ++m) _Pragma("unroll") for (int k = 0; k < 2; ++k) dst[m][k] = *(const PG8_LAS bf16x8*)(lds + PG8_SA(b, h) + aoff + m * 2048 + k * 1024); } while (0)
; #define PG8_LDB(dst, b, h) do { _Pragma("unroll") for (int n = 0; n < 2; ++n) _Pragma("unroll") for (int k = 0; k < 2; ++k) dst[n][k] = *(const PG8_LAS bf16x8*)(lds + PG8_SB(b, h) + boff + n * 2048 + k * 1024); } while (0)
; #define PG8_MMA(ai, bj, At, Bt) do { __builtin_amdgcn_s_setprio(1); _Pragma("unroll") for (int m = 0; m < 4; ++m) _Pragma("unroll") for (int n = 0; n < 2; ++n) _Pragma("unroll") for (int k = 0; k < 2; ++k) \
;         acc[ai][bj][m][n] = __builtin_amdgcn_mfma_f32_16x16x32_bf16(Bt[n][k], At[m][k], acc[ai][bj][m][n], 0, 0, 0); __builtin_amdgcn_s_setprio(0); } while (0)
; #define PG8_WAIT_V(n) asm volatile("s_waitcnt vmcnt(" #n ")" ::: "memory")
; #define PG8_WAIT_L(n) asm volatile("s_waitcnt lgkmcnt(" #n ")" ::: "memory")
; #define PG8_BAR __builtin_amdgcn_s_barrier()
; #define PG8_SCHED __builtin_amdgcn_sched_barrier(0)
; template <class Epi, class Sched, bool ALIGN_EPI = false, bool SP2 = false>
; __device__ __forceinline__ void gemm_phase(PG8_LAS unsigned char* lds, const Gemm g, const Sched& S, const Epi& E) {
;     ...
;             PG8_WAIT_V(8); PG8_WAIT_L(0); PG8_BAR; PG8_MMA(1, 0, At, B0); PG8_MMA(1, 1, At, B1); PG8_BAR; PG8_SCHED;
;             PG8_LDB(B0, 1, 0); PG8_LDB(B1, 1, 1); PG8_SCHED; PG8_LDA(At, 1, 0); PG8_STAGE(PG8_SA(0, 1), a2 + hstepA, voffA);
;             PG8_WAIT_V(8); PG8_WAIT_L(0); PG8_BAR; PG8_MMA(0, 0, At, B0); PG8_MMA(0, 1, At, B1); PG8_BAR; PG8_SCHED;
	s_waitcnt lgkmcnt(0)
	v_mfma_f32_16x16x32_bf16 v[60:63], v[144:147], v[182:185], v[60:63]
	v_mfma_f32_16x16x32_bf16 v[56:59], v[158:161], v[182:185], v[56:59]
	v_mfma_f32_16x16x32_bf16 v[52:55], v[144:147], v[190:193], v[52:55]
	v_mfma_f32_16x16x32_bf16 v[48:51], v[158:161], v[190:193], v[48:51]
	v_mfma_f32_16x16x32_bf16 v[40:43], v[144:147], v[198:201], v[40:43]
	v_mfma_f32_16x16x32_bf16 v[32:35], v[158:161], v[198:201], v[32:35]
	v_mfma_f32_16x16x32_bf16 v[24:27], v[144:147], v[206:209], v[24:27]
	v_mfma_f32_16x16x32_bf16 v[16:19], v[158:161], v[206:209], v[16:19]
	v_mfma_f32_16x16x32_bf16 v[60:63], v[148:151], v[186:189], v[60:63]
	v_mfma_f32_16x16x32_bf16 v[56:59], v[162:165], v[186:189], v[56:59]
	v_mfma_f32_16x16x32_bf16 v[52:55], v[148:151], v[194:197], v[52:55]
	v_mfma_f32_16x16x32_bf16 v[48:51], v[162:165], v[194:197], v[48:51]
	v_mfma_f32_16x16x32_bf16 v[40:43], v[148:151], v[202:205], v[40:43]
	v_mfma_f32_16x16x32_bf16 v[32:35], v[162:165], v[202:205], v[32:35]
	v_mfma_f32_16x16x32_bf16 v[24:27], v[148:151], v[210:213], v[24:27]
	v_mfma_f32_16x16x32_bf16 v[16:19], v[162:165], v[210:213], v[16:19]
	v_mfma_f32_16x16x32_bf16 v[44:47], v[166:169], v[182:185], v[44:47]
	v_mfma_f32_16x16x32_bf16 v[36:39], v[174:177], v[182:185], v[36:39]
	v_mfma_f32_16x16x32_bf16 v[28:31], v[166:169], v[190:193], v[28:31]
	v_mfma_f32_16x16x32_bf16 v[20:23], v[174:177], v[190:193], v[20:23]
	v_mfma_f32_16x16x32_bf16 v[12:15], v[166:169], v[198:201], v[12:15]
	v_mfma_f32_16x16x32_bf16 v[8:11], v[174:177], v[198:201], v[8:11]
	v_mfma_f32_16x16x32_bf16 v[4:7], v[166:169], v[206:209], v[4:7]
	v_mfma_f32_16x16x32_bf16 v[0:3], v[174:177], v[206:209], v[0:3]
	v_mfma_f32_16x16x32_bf16 v[44:47], v[170:173], v[186:189], v[44:47]
	v_mfma_f32_16x16x32_bf16 v[36:39], v[178:181], v[186:189], v[36:39]
	v_mfma_f32_16x16x32_bf16 v[28:31], v[170:173], v[194:197], v[28:31]
	v_mfma_f32_16x16x32_bf16 v[20:23], v[178:181], v[194:197], v[20:23]
	v_mfma_f32_16x16x32_bf16 v[12:15], v[170:173], v[202:205], v[12:15]
	v_mfma_f32_16x16x32_bf16 v[8:11], v[178:181], v[202:205], v[8:11]
	v_mfma_f32_16x16x32_bf16 v[4:7], v[170:173], v[210:213], v[4:7]
	v_mfma_f32_16x16x32_bf16 v[0:3], v[178:181], v[210:213], v[0:3]
	s_barrier
	s_add_i32 s67, 0, 0x18000
	s_add_i32 s68, 0, 0x1c000
	v_add_u32_e32 v162, s67, v154
	v_add_u32_e32 v178, s68, v154
	ds_read_b128 v[144:147], v162
	ds_read_b128 v[148:151], v162 offset:1024
	ds_read_b128 v[158:161], v162 offset:2048
	ds_read_b128 v[162:165], v162 offset:3072
	ds_read_b128 v[166:169], v178
	ds_read_b128 v[170:173], v178 offset:1024
	ds_read_b128 v[174:177], v178 offset:2048
	ds_read_b128 v[178:181], v178 offset:3072
	s_add_u32 s50, s50, 0x10000
	s_addc_u32 s51, s51, 0
	s_mov_b32 m0, s33
	v_lshl_add_u64 v[222:223], s[50:51], 0, v[128:129]
	ds_read_b128 v[182:185], v157 offset:32768
	ds_read_b128 v[186:189], v157 offset:33792
	ds_read_b128 v[190:193], v157 offset:34816
	ds_read_b128 v[194:197], v157 offset:35840
	ds_read_b128 v[198:201], v157 offset:36864
	ds_read_b128 v[202:205], v157 offset:37888
	ds_read_b128 v[206:209], v157 offset:38912
	ds_read_b128 v[210:213], v157 offset:39936
	global_load_lds_dwordx4 v[222:223], off
	v_lshl_add_u64 v[222:223], s[50:51], 0, v[132:133]
	s_mov_b32 m0, s35
	s_nop 0
	global_load_lds_dwordx4 v[222:223], off
	s_waitcnt vmcnt(8)
	s_waitcnt lgkmcnt(0)
	s_barrier
	s_waitcnt lgkmcnt(0)
	v_mfma_f32_16x16x32_bf16 v[124:127], v[144:147], v[182:185], v[124:127]
	v_mfma_f32_16x16x32_bf16 v[120:123], v[158:161], v[182:185], v[120:123]
	v_mfma_f32_16x16x32_bf16 v[116:119], v[144:147], v[190:193], v[116:119]
	v_mfma_f32_16x16x32_bf16 v[112:115], v[158:161], v[190:193], v[112:115]
	v_mfma_f32_16x16x32_bf16 v[104:107], v[144:147], v[198:201], v[104:107]
	v_mfma_f32_16x16x32_bf16 v[96:99], v[158:161], v[198:201], v[96:99]
	v_mfma_f32_16x16x32_bf16 v[88:91], v[144:147], v[206:209], v[88:91]
	v_mfma_f32_16x16x32_bf16 v[80:83], v[158:161], v[206:209], v[80:83]
	v_mfma_f32_16x16x32_bf16 v[124:127], v[148:151], v[186:189], v[124:127]
	v_mfma_f32_16x16x32_bf16 v[120:123], v[162:165], v[186:189], v[120:123]
	v_mfma_f32_16x16x32_bf16 v[116:119], v[148:151], v[194:197], v[116:119]
	v_mfma_f32_16x16x32_bf16 v[112:115], v[162:165], v[194:197], v[112:115]
	v_mfma_f32_16x16x32_bf16 v[104:107], v[148:151], v[202:205], v[104:107]
	v_mfma_f32_16x16x32_bf16 v[96:99], v[162:165], v[202:205], v[96:99]
	v_mfma_f32_16x16x32_bf16 v[88:91], v[148:151], v[210:213], v[88:91]
	v_mfma_f32_16x16x32_bf16 v[80:83], v[162:165], v[210:213], v[80:83]
	v_mfma_f32_16x16x32_bf16 v[108:111], v[166:169], v[182:185], v[108:111]
	v_mfma_f32_16x16x32_bf16 v[100:103], v[174:177], v[182:185], v[100:103]
	v_mfma_f32_16x16x32_bf16 v[92:95], v[166:169], v[190:193], v[92:95]
	v_mfma_f32_16x16x32_bf16 v[84:87], v[174:177], v[190:193], v[84:87]
	v_mfma_f32_16x16x32_bf16 v[76:79], v[166:169], v[198:201], v[76:79]
	v_mfma_f32_16x16x32_bf16 v[72:75], v[174:177], v[198:201], v[72:75]
	v_mfma_f32_16x16x32_bf16 v[68:71], v[166:169], v[206:209], v[68:71]
	v_mfma_f32_16x16x32_bf16 v[64:67], v[174:177], v[206:209], v[64:67]
	v_mfma_f32_16x16x32_bf16 v[108:111], v[170:173], v[186:189], v[108:111]
	v_mfma_f32_16x16x32_bf16 v[100:103], v[178:181], v[186:189], v[100:103]
	v_mfma_f32_16x16x32_bf16 v[92:95], v[170:173], v[194:197], v[92:95]
	v_mfma_f32_16x16x32_bf16 v[84:87], v[178:181], v[194:197], v[84:87]
	v_mfma_f32_16x16x32_bf16 v[76:79], v[170:173], v[202:205], v[76:79]
	v_mfma_f32_16x16x32_bf16 v[72:75], v[178:181], v[202:205], v[72:75]
	v_mfma_f32_16x16x32_bf16 v[68:71], v[170:173], v[210:213], v[68:71]
	v_mfma_f32_16x16x32_bf16 v[64:67], v[178:181], v[210:213], v[64:67]
	s_barrier
; #define PG8_STAGE(bufoff, gbase, voff) do { _Pragma("unroll") for (int _i = 0; _i < 2; ++_i) \
;         __builtin_amdgcn_global_load_lds((const unsigned*)((const char*)(gbase) + (voff)[_i]), (PG8_LAS unsigned*)(lds + (bufoff) + ldsw + _i * 8192), 16, 0, 0); } while (0)
; #define PG8_LDA(dst, b, h) do { _Pragma("unroll") for (int m = 0; m < 4; ++m) _Pragma("unroll") for (int k = 0; k < 2; ++k) dst[m][k] = *(const PG8_LAS bf16x8*)(lds + PG8_SA(b, h) + aoff + m * 2048 + k * 1024); } while (0)
; #define PG8_MMA(ai, bj, At, Bt) do { __builtin_amdgcn_s_setprio(1); _Pragma("unroll") for (int m = 0; m < 4; ++m) _Pragma("unroll") for (int n = 0; n < 2; ++n) _Pragma("unroll") for (int k = 0; k < 2; ++k) \
;         acc[ai][bj][m][n] = __builtin_amdgcn_mfma_f32_16x16x32_bf16(Bt[n][k], At[m][k], acc[ai][bj][m][n], 0, 0, 0); __builtin_amdgcn_s_setprio(0); } while (0)
; #define PG8_WAIT_V(n) asm volatile("s_waitcnt vmcnt(" #n ")" ::: "memory")
; #define PG8_WAIT_L(n) asm volatile("s_waitcnt lgkmcnt(" #n ")" ::: "memory")
; #define PG8_BAR __builtin_amdgcn_s_barrier()
; #define PG8_SCHED __builtin_amdgcn_sched_barrier(0)
;     __device__ __forceinline__ void operator()(const f32x4 (&acc)[2][2][4][2], const Unit& u, int wr, int wc, int fr_in, int fq_in) const {
;     ...
;             for (int m = 0; m < 4; ++m) { bf16_t* rowp = base + (size_t)(row0 + ai * HALF + m * 16) * ldc + col0;
; #pragma unroll
;                 for (int bj = 0; bj < 2; ++bj) { f32x4 v0 = acc[ai][bj][m][0] + bv[bj][0], v1 = acc[ai][bj][m][1] + bv[bj][1];
; template <class Epi, class Sched, bool ALIGN_EPI = false, bool SP2 = false>
; __device__ __forceinline__ void gemm_phase(PG8_LAS unsigned char* lds, const Gemm g, const Sched& S, const Epi& E) {
;     ...
;             PG8_LDA(At, 1, 1); PG8_STAGE(PG8_SB(1, 0), b3, voffB); PG8_STAGE(PG8_SB(1, 1), b3 + hstepB, voffB); PG8_STAGE(PG8_SA(1, 0), a3, voffA);
;             PG8_WAIT_V(8); PG8_WAIT_L(0); PG8_BAR; PG8_MMA(1, 0, At, B0); PG8_MMA(1, 1, At, B1); PG8_BAR; PG8_SCHED;
	s_add_i32 s50, s67, s19
	v_lshl_add_u64 v[214:215], v[214:215], 0, s[24:25]
	s_mov_b32 m0, s50
	ds_read_b128 v[182:185], v157 offset:49152
	ds_read_b128 v[186:189], v157 offset:50176
	ds_read_b128 v[190:193], v157 offset:51200
	ds_read_b128 v[194:197], v157 offset:52224
	ds_read_b128 v[198:201], v157 offset:53248
	ds_read_b128 v[202:205], v157 offset:54272
	ds_read_b128 v[206:209], v157 offset:55296
	ds_read_b128 v[210:213], v157 offset:56320
	global_load_lds_dwordx4 v[214:215], off
	s_add_i32 m0, s50, 0x2000
	s_add_u32 s48, s48, 0x10080
	v_lshl_add_u64 v[214:215], v[216:217], 0, s[24:25]
	s_addc_u32 s49, s49, 0
	s_add_i32 s50, s68, s19
	global_load_lds_dwordx4 v[214:215], off
	v_lshl_add_u64 v[214:215], s[48:49], 0, v[130:131]
	s_mov_b32 m0, s50
	s_nop 0
	global_load_lds_dwordx4 v[214:215], off
	v_lshl_add_u64 v[214:215], s[48:49], 0, v[134:135]
	s_add_i32 m0, s50, 0x2000
	s_nop 0
	global_load_lds_dwordx4 v[214:215], off
	v_lshl_add_u64 v[214:215], v[218:219], 0, s[24:25]
	s_mov_b32 m0, s57
	s_nop 0
	global_load_lds_dwordx4 v[214:215], off
	v_lshl_add_u64 v[214:215], v[220:221], 0, s[24:25]
	s_mov_b32 m0, s58
	s_nop 0
	global_load_lds_dwordx4 v[214:215], off
	s_waitcnt vmcnt(8)
	s_waitcnt lgkmcnt(0)
	s_barrier
	s_waitcnt lgkmcnt(0)
	v_mfma_f32_16x16x32_bf16 v[60:63], v[144:147], v[182:185], v[60:63]
	v_mfma_f32_16x16x32_bf16 v[56:59], v[158:161], v[182:185], v[56:59]
	v_mfma_f32_16x16x32_bf16 v[52:55], v[144:147], v[190:193], v[52:55]
	v_mfma_f32_16x16x32_bf16 v[48:51], v[158:161], v[190:193], v[48:51]
	v_mfma_f32_16x16x32_bf16 v[40:43], v[144:147], v[198:201], v[40:43]
	v_mfma_f32_16x16x32_bf16 v[32:35], v[158:161], v[198:201], v[32:35]
	v_mfma_f32_16x16x32_bf16 v[24:27], v[144:147], v[206:209], v[24:27]
	v_mfma_f32_16x16x32_bf16 v[16:19], v[158:161], v[206:209], v[16:19]
	v_mfma_f32_16x16x32_bf16 v[60:63], v[148:151], v[186:189], v[60:63]
	v_mfma_f32_16x16x32_bf16 v[56:59], v[162:165], v[186:189], v[56:59]
	v_mfma_f32_16x16x32_bf16 v[52:55], v[148:151], v[194:197], v[52:55]
	v_mfma_f32_16x16x32_bf16 v[48:51], v[162:165], v[194:197], v[48:51]
	v_mfma_f32_16x16x32_bf16 v[40:43], v[148:151], v[202:205], v[40:43]
	v_mfma_f32_16x16x32_bf16 v[32:35], v[162:165], v[202:205], v[32:35]
	v_mfma_f32_16x16x32_bf16 v[24:27], v[148:151], v[210:213], v[24:27]
	v_mfma_f32_16x16x32_bf16 v[16:19], v[162:165], v[210:213], v[16:19]
	v_mfma_f32_16x16x32_bf16 v[44:47], v[166:169], v[182:185], v[44:47]
	v_mfma_f32_16x16x32_bf16 v[36:39], v[174:177], v[182:185], v[36:39]
	v_mfma_f32_16x16x32_bf16 v[28:31], v[166:169], v[190:193], v[28:31]
	v_mfma_f32_16x16x32_bf16 v[20:23], v[174:177], v[190:193], v[20:23]
	v_mfma_f32_16x16x32_bf16 v[12:15], v[166:169], v[198:201], v[12:15]
	v_mfma_f32_16x16x32_bf16 v[8:11], v[174:177], v[198:201], v[8:11]
	v_mfma_f32_16x16x32_bf16 v[4:7], v[166:169], v[206:209], v[4:7]
	v_mfma_f32_16x16x32_bf16 v[0:3], v[174:177], v[206:209], v[0:3]
	v_mfma_f32_16x16x32_bf16 v[44:47], v[170:173], v[186:189], v[44:47]
	v_mfma_f32_16x16x32_bf16 v[36:39], v[178:181], v[186:189], v[36:39]
	v_mfma_f32_16x16x32_bf16 v[28:31], v[170:173], v[194:197], v[28:31]
	v_mfma_f32_16x16x32_bf16 v[20:23], v[178:181], v[194:197], v[20:23]
	v_mfma_f32_16x16x32_bf16 v[12:15], v[170:173], v[202:205], v[12:15]
	v_mfma_f32_16x16x32_bf16 v[8:11], v[178:181], v[202:205], v[8:11]
	v_mfma_f32_16x16x32_bf16 v[4:7], v[170:173], v[210:213], v[4:7]
	v_mfma_f32_16x16x32_bf16 v[0:3], v[178:181], v[210:213], v[0:3]
	s_barrier
	s_add_u32 s46, s46, 0x100
	s_addc_u32 s47, s47, 0
	s_add_u32 s64, s64, 0x100
	s_addc_u32 s65, s65, 0
	s_cmp_ge_i32 s66, s53
	s_mov_b32 s48, s66
	s_cbranch_scc0 .LBB0_1333
	v_pk_add_f32 v[126:127], v[126:127], 0 op_sel_hi:[1,0]
	v_pk_add_f32 v[124:125], v[124:125], 0 op_sel_hi:[1,0]
	v_pk_add_f32 v[122:123], v[122:123], 0 op_sel_hi:[1,0]
	v_pk_add_f32 v[120:121], v[120:121], 0 op_sel_hi:[1,0]
	v_pk_add_f32 v[144:145], v[110:111], 0 op_sel_hi:[1,0]
	v_pk_add_f32 v[146:147], v[108:109], 0 op_sel_hi:[1,0]
	v_pk_add_f32 v[148:149], v[102:103], 0 op_sel_hi:[1,0]
	v_pk_add_f32 v[150:151], v[100:101], 0 op_sel_hi:[1,0]
	v_pk_add_f32 v[100:101], v[118:119], 0 op_sel_hi:[1,0]
	v_pk_add_f32 v[102:103], v[116:117], 0 op_sel_hi:[1,0]
	v_pk_add_f32 v[108:109], v[114:115], 0 op_sel_hi:[1,0]
	v_pk_add_f32 v[110:111], v[112:113], 0 op_sel_hi:[1,0]
	v_pk_add_f32 v[112:113], v[94:95], 0 op_sel_hi:[1,0]
	v_pk_add_f32 v[114:115], v[92:93], 0 op_sel_hi:[1,0]
	v_pk_add_f32 v[116:117], v[86:87], 0 op_sel_hi:[1,0]
	v_pk_add_f32 v[118:119], v[84:85], 0 op_sel_hi:[1,0]
	v_pk_add_f32 v[84:85], v[106:107], 0 op_sel_hi:[1,0]
	v_pk_add_f32 v[86:87], v[104:105], 0 op_sel_hi:[1,0]
	v_pk_add_f32 v[92:93], v[98:99], 0 op_sel_hi:[1,0]
	v_pk_add_f32 v[94:95], v[96:97], 0 op_sel_hi:[1,0]
	v_pk_add_f32 v[96:97], v[78:79], 0 op_sel_hi:[1,0]
	v_pk_add_f32 v[98:99], v[76:77], 0 op_sel_hi:[1,0]
	v_pk_add_f32 v[104:105], v[74:75], 0 op_sel_hi:[1,0]
	v_pk_add_f32 v[106:107], v[72:73], 0 op_sel_hi:[1,0]
	v_pk_add_f32 v[72:73], v[90:91], 0 op_sel_hi:[1,0]
	v_pk_add_f32 v[74:75], v[88:89], 0 op_sel_hi:[1,0]
	v_pk_add_f32 v[76:77], v[82:83], 0 op_sel_hi:[1,0]
	v_pk_add_f32 v[78:79], v[80:81], 0 op_sel_hi:[1,0]
	v_pk_add_f32 v[70:71], v[70:71], 0 op_sel_hi:[1,0]
	v_pk_add_f32 v[68:69], v[68:69], 0 op_sel_hi:[1,0]
	v_pk_add_f32 v[66:67], v[66:67], 0 op_sel_hi:[1,0]
	v_pk_add_f32 v[64:65], v[64:65], 0 op_sel_hi:[1,0]
	v_pk_add_f32 v[62:63], v[62:63], 0 op_sel_hi:[1,0]
	v_pk_add_f32 v[60:61], v[60:61], 0 op_sel_hi:[1,0]
	v_pk_add_f32 v[58:59], v[58:59], 0 op_sel_hi:[1,0]
	v_pk_add_f32 v[56:57], v[56:57], 0 op_sel_hi:[1,0]
	v_pk_add_f32 v[80:81], v[46:47], 0 op_sel_hi:[1,0]
	v_pk_add_f32 v[82:83], v[44:45], 0 op_sel_hi:[1,0]
	v_pk_add_f32 v[88:89], v[38:39], 0 op_sel_hi:[1,0]
	v_pk_add_f32 v[90:91], v[36:37], 0 op_sel_hi:[1,0]
	v_pk_add_f32 v[36:37], v[54:55], 0 op_sel_hi:[1,0]
	v_pk_add_f32 v[38:39], v[52:53], 0 op_sel_hi:[1,0]
	v_pk_add_f32 v[44:45], v[50:51], 0 op_sel_hi:[1,0]
	v_pk_add_f32 v[46:47], v[48:49], 0 op_sel_hi:[1,0]
	v_pk_add_f32 v[48:49], v[30:31], 0 op_sel_hi:[1,0]
	v_pk_add_f32 v[50:51], v[28:29], 0 op_sel_hi:[1,0]
	v_pk_add_f32 v[52:53], v[22:23], 0 op_sel_hi:[1,0]
	v_pk_add_f32 v[54:55], v[20:21], 0 op_sel_hi:[1,0]
	v_pk_add_f32 v[20:21], v[42:43], 0 op_sel_hi:[1,0]
	v_pk_add_f32 v[22:23], v[40:41], 0 op_sel_hi:[1,0]
	v_pk_add_f32 v[28:29], v[34:35], 0 op_sel_hi:[1,0]
	v_pk_add_f32 v[30:31], v[32:33], 0 op_sel_hi:[1,0]
	v_pk_add_f32 v[32:33], v[14:15], 0 op_sel_hi:[1,0]
	v_pk_add_f32 v[34:35], v[12:13], 0 op_sel_hi:[1,0]
	v_pk_add_f32 v[40:41], v[10:11], 0 op_sel_hi:[1,0]
	v_pk_add_f32 v[42:43], v[8:9], 0 op_sel_hi:[1,0]
	v_pk_add_f32 v[8:9], v[26:27], 0 op_sel_hi:[1,0]
	v_pk_add_f32 v[10:11], v[24:25], 0 op_sel_hi:[1,0]
	v_pk_add_f32 v[12:13], v[18:19], 0 op_sel_hi:[1,0]
	v_pk_add_f32 v[14:15], v[16:17], 0 op_sel_hi:[1,0]
	v_pk_add_f32 v[6:7], v[6:7], 0 op_sel_hi:[1,0]
	v_pk_add_f32 v[4:5], v[4:5], 0 op_sel_hi:[1,0]
	v_pk_add_f32 v[2:3], v[2:3], 0 op_sel_hi:[1,0]
	v_pk_add_f32 v[0:1], v[0:1], 0 op_sel_hi:[1,0]

; #define PG8_STAGE(bufoff, gbase, voff) do { _Pragma("unroll") for (int _i = 0; _i < 2; ++_i) \
;         __builtin_amdgcn_global_load_lds((const unsigned*)((const char*)(gbase) + (voff)[_i]), (PG8_LAS unsigned*)(lds + (bufoff) + ldsw + _i * 8192), 16, 0, 0); } while (0)
; #define PG8_LDA(dst, b, h) do { _Pragma("unroll") for (int m = 0; m < 4; ++m) _Pragma("unroll") for (int k = 0; k < 2; ++k) dst[m][k] = *(const PG8_LAS bf16x8*)(lds + PG8_SA(b, h) + aoff + m * 2048 + k * 1024); } while (0)
; #define PG8_LDB(dst, b, h) do { _Pragma("unroll") for (int n = 0; n < 2; ++n) _Pragma("unroll") for (int k = 0; k < 2; ++k) dst[n][k] = *(const PG8_LAS bf16x8*)(lds + PG8_SB(b, h) + boff + n * 2048 + k * 1024); } while (0)
; #define PG8_MMA(ai, bj, At, Bt) do { __builtin_amdgcn_s_setprio(1); _Pragma("unroll") for (int m = 0; m < 4; ++m) _Pragma("unroll") for (int n = 0; n < 2; ++n) _Pragma("unroll") for (int k = 0; k < 2; ++k) \
;         acc[ai][bj][m][n] = __builtin_amdgcn_mfma_f32_16x16x32_bf16(Bt[n][k], At[m][k], acc[ai][bj][m][n], 0, 0, 0); __builtin_amdgcn_s_setprio(0); } while (0)
; #define PG8_WAIT_V(n) asm volatile("s_waitcnt vmcnt(" #n ")" ::: "memory")
; #define PG8_WAIT_L(n) asm volatile("s_waitcnt lgkmcnt(" #n ")" ::: "memory")
; #define PG8_BAR __builtin_amdgcn_s_barrier()
; #define PG8_SCHED __builtin_amdgcn_sched_barrier(0)
; template <class Epi, class Sched, bool ALIGN_EPI = false, bool SP2 = false>
; __device__ __forceinline__ void gemm_phase(PG8_LAS unsigned char* lds, const Gemm g, const Sched& S, const Epi& E) {
;     ...
;             PG8_LDB(B0, 0, 0); PG8_LDB(B1, 0, 1); PG8_SCHED; PG8_LDA(At, 0, 0); PG8_STAGE(PG8_SA(1, 1), a1 + hstepA, voffA);
;             PG8_WAIT_V(8); PG8_WAIT_L(0); PG8_BAR; PG8_MMA(0, 0, At, B0); PG8_MMA(0, 1, At, B1); PG8_BAR; PG8_SCHED;
;             PG8_LDA(At, 0, 1); PG8_STAGE(PG8_SB(0, 0), b2, voffB); PG8_STAGE(PG8_SB(0, 1), b2 + hstepB, voffB); PG8_STAGE(PG8_SA(0, 0), a2, voffA);
;             PG8_WAIT_V(8); PG8_WAIT_L(0); PG8_BAR; PG8_MMA(1, 0, At, B0); PG8_MMA(1, 1, At, B1); PG8_BAR; PG8_SCHED;
.LBB0_1362:
	ds_read_b128 v[128:131], v183
	ds_read_b128 v[132:135], v183 offset:1024
	ds_read_b128 v[136:139], v183 offset:2048
	ds_read_b128 v[140:143], v183 offset:3072
	ds_read_b128 v[144:147], v187
	ds_read_b128 v[148:151], v187 offset:1024
	ds_read_b128 v[152:155], v187 offset:2048
	ds_read_b128 v[196:199], v187 offset:3072
	s_add_i32 s69, s50, 2
	s_add_u32 s51, s48, 0x3fc000
	s_addc_u32 s52, s49, 0
	s_cmp_eq_u32 s64, s50
	s_cselect_b32 s54, s9, s51
	s_cselect_b32 s55, s8, s52
	s_cselect_b32 s53, s11, s47
	s_cselect_b32 s52, s41, s43
	s_add_u32 s50, s54, 0x400000
	s_addc_u32 s51, s55, 0
	v_lshl_add_u64 v[180:181], s[48:49], 0, v[166:167]
	s_add_i32 m0, s19, 0xc000
	ds_read_b128 v[200:203], v191
	ds_read_b128 v[204:207], v191 offset:1024
	ds_read_b128 v[208:211], v191 offset:2048
	ds_read_b128 v[212:215], v191 offset:3072
	ds_read_b128 v[216:219], v191 offset:4096
	ds_read_b128 v[220:223], v191 offset:5120
	ds_read_b128 v[224:227], v191 offset:6144
	ds_read_b128 v[228:231], v191 offset:7168
	global_load_lds_dwordx4 v[180:181], off
	v_lshl_add_u64 v[180:181], s[48:49], 0, v[168:169]
	s_add_i32 m0, s19, 0xe000
	s_nop 0
	global_load_lds_dwordx4 v[180:181], off
	s_waitcnt vmcnt(8)
	s_waitcnt lgkmcnt(0)
	s_barrier
	s_waitcnt lgkmcnt(0)
	v_mfma_f32_16x16x32_bf16 v[124:127], v[128:131], v[200:203], v[124:127]
	v_mfma_f32_16x16x32_bf16 v[120:123], v[136:139], v[200:203], v[120:123]
	v_mfma_f32_16x16x32_bf16 v[116:119], v[128:131], v[208:211], v[116:119]
	v_mfma_f32_16x16x32_bf16 v[112:115], v[136:139], v[208:211], v[112:115]
	v_mfma_f32_16x16x32_bf16 v[108:111], v[128:131], v[216:219], v[108:111]
	v_mfma_f32_16x16x32_bf16 v[104:107], v[136:139], v[216:219], v[104:107]
	v_mfma_f32_16x16x32_bf16 v[100:103], v[128:131], v[224:227], v[100:103]
	v_mfma_f32_16x16x32_bf16 v[96:99], v[136:139], v[224:227], v[96:99]
	v_mfma_f32_16x16x32_bf16 v[124:127], v[132:135], v[204:207], v[124:127]
	v_mfma_f32_16x16x32_bf16 v[120:123], v[140:143], v[204:207], v[120:123]
	v_mfma_f32_16x16x32_bf16 v[116:119], v[132:135], v[212:215], v[116:119]
	v_mfma_f32_16x16x32_bf16 v[112:115], v[140:143], v[212:215], v[112:115]
	v_mfma_f32_16x16x32_bf16 v[108:111], v[132:135], v[220:223], v[108:111]
	v_mfma_f32_16x16x32_bf16 v[104:107], v[140:143], v[220:223], v[104:107]
	v_mfma_f32_16x16x32_bf16 v[100:103], v[132:135], v[228:231], v[100:103]
	v_mfma_f32_16x16x32_bf16 v[96:99], v[140:143], v[228:231], v[96:99]
	v_mfma_f32_16x16x32_bf16 v[60:63], v[144:147], v[200:203], v[60:63]
	v_mfma_f32_16x16x32_bf16 v[56:59], v[152:155], v[200:203], v[56:59]
	v_mfma_f32_16x16x32_bf16 v[52:55], v[144:147], v[208:211], v[52:55]
	v_mfma_f32_16x16x32_bf16 v[48:51], v[152:155], v[208:211], v[48:51]
	v_mfma_f32_16x16x32_bf16 v[44:47], v[144:147], v[216:219], v[44:47]
	v_mfma_f32_16x16x32_bf16 v[40:43], v[152:155], v[216:219], v[40:43]
	v_mfma_f32_16x16x32_bf16 v[36:39], v[144:147], v[224:227], v[36:39]
	v_mfma_f32_16x16x32_bf16 v[32:35], v[152:155], v[224:227], v[32:35]
	v_mfma_f32_16x16x32_bf16 v[60:63], v[148:151], v[204:207], v[60:63]
	v_mfma_f32_16x16x32_bf16 v[56:59], v[196:199], v[204:207], v[56:59]
	v_mfma_f32_16x16x32_bf16 v[52:55], v[148:151], v[212:215], v[52:55]
	v_mfma_f32_16x16x32_bf16 v[48:51], v[196:199], v[212:215], v[48:51]
	v_mfma_f32_16x16x32_bf16 v[44:47], v[148:151], v[220:223], v[44:47]
	v_mfma_f32_16x16x32_bf16 v[40:43], v[196:199], v[220:223], v[40:43]
	v_mfma_f32_16x16x32_bf16 v[36:39], v[148:151], v[228:231], v[36:39]
	v_mfma_f32_16x16x32_bf16 v[32:35], v[196:199], v[228:231], v[32:35]
	s_barrier
	s_add_i32 s70, s67, s16
	v_lshl_add_u64 v[180:181], s[52:53], 0, v[158:159]
	s_mov_b32 m0, s70
	ds_read_b128 v[200:203], v191 offset:16384
	ds_read_b128 v[204:207], v191 offset:17408
	ds_read_b128 v[208:211], v191 offset:18432
	ds_read_b128 v[212:215], v191 offset:19456
	ds_read_b128 v[216:219], v191 offset:20480
	ds_read_b128 v[220:223], v191 offset:21504
	ds_read_b128 v[224:227], v191 offset:22528
	ds_read_b128 v[228:231], v191 offset:23552
	global_load_lds_dwordx4 v[180:181], off
	s_add_i32 m0, s70, 0x2000
	s_add_u32 s70, s52, 0x4000
	v_lshl_add_u64 v[180:181], s[52:53], 0, v[162:163]
	s_addc_u32 s71, s53, 0
	s_add_i32 s72, s68, s16
	global_load_lds_dwordx4 v[180:181], off
	v_lshl_add_u64 v[180:181], s[70:71], 0, v[158:159]
	s_mov_b32 m0, s72
	s_nop 0
	global_load_lds_dwordx4 v[180:181], off
	v_lshl_add_u64 v[180:181], s[70:71], 0, v[162:163]
	s_add_i32 m0, s72, 0x2000
	s_nop 0
	global_load_lds_dwordx4 v[180:181], off
	v_lshl_add_u64 v[180:181], s[54:55], 0, v[156:157]
	s_mov_b32 m0, s19
	s_nop 0
	global_load_lds_dwordx4 v[180:181], off
	v_lshl_add_u64 v[180:181], s[54:55], 0, v[160:161]
	s_mov_b32 m0, s33
	s_nop 0
	global_load_lds_dwordx4 v[180:181], off
	s_waitcnt vmcnt(8)
	s_waitcnt lgkmcnt(0)
	s_barrier
; #define PG8_STAGE(bufoff, gbase, voff) do { _Pragma("unroll") for (int _i = 0; _i < 2; ++_i) \
;         __builtin_amdgcn_global_load_lds((const unsigned*)((const char*)(gbase) + (voff)[_i]), (PG8_LAS unsigned*)(lds + (bufoff) + ldsw + _i * 8192), 16, 0, 0); } while (0)
; #define PG8_LDA(dst, b, h) do { _Pragma("unroll") for (int m = 0; m < 4; ++m) _Pragma("unroll") for (int k = 0; k < 2; ++k) dst[m][k] = *(const PG8_LAS bf16x8*)(lds + PG8_SA(b, h) + aoff + m * 2048 + k * 1024); } while (0)
; #define PG8_LDB(dst, b, h) do { _Pragma("unroll") for (int n = 0; n < 2; ++n) _Pragma("unroll") for (int k = 0; k < 2; ++k) dst[n][k] = *(const PG8_LAS bf16x8*)(lds + PG8_SB(b, h) + boff + n * 2048 + k * 1024); } while (0)
; #define PG8_MMA(ai, bj, At, Bt) do { __builtin_amdgcn_s_setprio(1); _Pragma("unroll") for (int m = 0; m < 4; ++m) _Pragma("unroll") for (int n = 0; n < 2; ++n) _Pragma("unroll") for (int k = 0; k < 2; ++k) \
;         acc[ai][bj][m][n] = __builtin_amdgcn_mfma_f32_16x16x32_bf16(Bt[n][k], At[m][k], acc[ai][bj][m][n], 0, 0, 0); __builtin_amdgcn_s_setprio(0); } while (0)
; #define PG8_WAIT_V(n) asm volatile("s_waitcnt vmcnt(" #n ")" ::: "memory")
; #define PG8_WAIT_L(n) asm volatile("s_waitcnt lgkmcnt(" #n ")" ::: "memory")
; #define PG8_BAR __builtin_amdgcn_s_barrier()
; #define PG8_SCHED __builtin_amdgcn_sched_barrier(0)
; template <class Epi, class Sched, bool ALIGN_EPI = false, bool SP2 = false>
; __device__ __forceinline__ void gemm_phase(PG8_LAS unsigned char* lds, const Gemm g, const Sched& S, const Epi& E) {
;     ...
;             PG8_WAIT_V(8); PG8_WAIT_L(0); PG8_BAR; PG8_MMA(1, 0, At, B0); PG8_MMA(1, 1, At, B1); PG8_BAR; PG8_SCHED;
;             PG8_LDB(B0, 1, 0); PG8_LDB(B1, 1, 1); PG8_SCHED; PG8_LDA(At, 1, 0); PG8_STAGE(PG8_SA(0, 1), a2 + hstepA, voffA);
;             PG8_WAIT_V(8); PG8_WAIT_L(0); PG8_BAR; PG8_MMA(0, 0, At, B0); PG8_MMA(0, 1, At, B1); PG8_BAR; PG8_SCHED;
	s_waitcnt lgkmcnt(0)
	v_mfma_f32_16x16x32_bf16 v[92:95], v[128:131], v[200:203], v[92:95]
	v_mfma_f32_16x16x32_bf16 v[88:91], v[136:139], v[200:203], v[88:91]
	v_mfma_f32_16x16x32_bf16 v[84:87], v[128:131], v[208:211], v[84:87]
	v_mfma_f32_16x16x32_bf16 v[80:83], v[136:139], v[208:211], v[80:83]
	v_mfma_f32_16x16x32_bf16 v[76:79], v[128:131], v[216:219], v[76:79]
	v_mfma_f32_16x16x32_bf16 v[72:75], v[136:139], v[216:219], v[72:75]
	v_mfma_f32_16x16x32_bf16 v[68:71], v[128:131], v[224:227], v[68:71]
	v_mfma_f32_16x16x32_bf16 v[64:67], v[136:139], v[224:227], v[64:67]
	v_mfma_f32_16x16x32_bf16 v[92:95], v[132:135], v[204:207], v[92:95]
	v_mfma_f32_16x16x32_bf16 v[88:91], v[140:143], v[204:207], v[88:91]
	v_mfma_f32_16x16x32_bf16 v[84:87], v[132:135], v[212:215], v[84:87]
	v_mfma_f32_16x16x32_bf16 v[80:83], v[140:143], v[212:215], v[80:83]
	v_mfma_f32_16x16x32_bf16 v[76:79], v[132:135], v[220:223], v[76:79]
	v_mfma_f32_16x16x32_bf16 v[72:75], v[140:143], v[220:223], v[72:75]
	v_mfma_f32_16x16x32_bf16 v[68:71], v[132:135], v[228:231], v[68:71]
	v_mfma_f32_16x16x32_bf16 v[64:67], v[140:143], v[228:231], v[64:67]
	v_mfma_f32_16x16x32_bf16 v[28:31], v[144:147], v[200:203], v[28:31]
	v_mfma_f32_16x16x32_bf16 v[24:27], v[152:155], v[200:203], v[24:27]
	v_mfma_f32_16x16x32_bf16 v[20:23], v[144:147], v[208:211], v[20:23]
	v_mfma_f32_16x16x32_bf16 v[16:19], v[152:155], v[208:211], v[16:19]
	v_mfma_f32_16x16x32_bf16 v[12:15], v[144:147], v[216:219], v[12:15]
	v_mfma_f32_16x16x32_bf16 v[8:11], v[152:155], v[216:219], v[8:11]
	v_mfma_f32_16x16x32_bf16 v[4:7], v[144:147], v[224:227], v[4:7]
	v_mfma_f32_16x16x32_bf16 v[0:3], v[152:155], v[224:227], v[0:3]
	v_mfma_f32_16x16x32_bf16 v[28:31], v[148:151], v[204:207], v[28:31]
	v_mfma_f32_16x16x32_bf16 v[24:27], v[196:199], v[204:207], v[24:27]
	v_mfma_f32_16x16x32_bf16 v[20:23], v[148:151], v[212:215], v[20:23]
	v_mfma_f32_16x16x32_bf16 v[16:19], v[196:199], v[212:215], v[16:19]
	v_mfma_f32_16x16x32_bf16 v[12:15], v[148:151], v[220:223], v[12:15]
	v_mfma_f32_16x16x32_bf16 v[8:11], v[196:199], v[220:223], v[8:11]
	v_mfma_f32_16x16x32_bf16 v[4:7], v[148:151], v[228:231], v[4:7]
	v_mfma_f32_16x16x32_bf16 v[0:3], v[196:199], v[228:231], v[0:3]
	s_barrier
	s_add_i32 s70, 0, 0x18000
	s_add_i32 s71, 0, 0x1c000
	v_add_u32_e32 v140, s70, v179
	v_add_u32_e32 v165, s71, v179
	ds_read_b128 v[128:131], v140
	ds_read_b128 v[132:135], v140 offset:1024
	ds_read_b128 v[136:139], v140 offset:2048
	ds_read_b128 v[140:143], v140 offset:3072
	ds_read_b128 v[144:147], v165
	ds_read_b128 v[148:151], v165 offset:1024
	ds_read_b128 v[152:155], v165 offset:2048
	ds_read_b128 v[196:199], v165 offset:3072
	s_add_u32 s54, s54, 0x4000
	s_addc_u32 s55, s55, 0
	s_mov_b32 m0, s35
	v_lshl_add_u64 v[180:181], s[54:55], 0, v[156:157]
	ds_read_b128 v[200:203], v191 offset:32768
	ds_read_b128 v[204:207], v191 offset:33792
	ds_read_b128 v[208:211], v191 offset:34816
	ds_read_b128 v[212:215], v191 offset:35840
	ds_read_b128 v[216:219], v191 offset:36864
	ds_read_b128 v[220:223], v191 offset:37888
	ds_read_b128 v[224:227], v191 offset:38912
	ds_read_b128 v[228:231], v191 offset:39936
	global_load_lds_dwordx4 v[180:181], off
	v_lshl_add_u64 v[180:181], s[54:55], 0, v[160:161]
	s_mov_b32 m0, s57
	s_nop 0
	global_load_lds_dwordx4 v[180:181], off
	s_waitcnt vmcnt(8)
	s_waitcnt lgkmcnt(0)
	s_barrier
	s_waitcnt lgkmcnt(0)
	v_mfma_f32_16x16x32_bf16 v[124:127], v[128:131], v[200:203], v[124:127]
	v_mfma_f32_16x16x32_bf16 v[120:123], v[136:139], v[200:203], v[120:123]
	v_mfma_f32_16x16x32_bf16 v[116:119], v[128:131], v[208:211], v[116:119]
	v_mfma_f32_16x16x32_bf16 v[112:115], v[136:139], v[208:211], v[112:115]
	v_mfma_f32_16x16x32_bf16 v[108:111], v[128:131], v[216:219], v[108:111]
	v_mfma_f32_16x16x32_bf16 v[104:107], v[136:139], v[216:219], v[104:107]
	v_mfma_f32_16x16x32_bf16 v[100:103], v[128:131], v[224:227], v[100:103]
	v_mfma_f32_16x16x32_bf16 v[96:99], v[136:139], v[224:227], v[96:99]
	v_mfma_f32_16x16x32_bf16 v[124:127], v[132:135], v[204:207], v[124:127]
	v_mfma_f32_16x16x32_bf16 v[120:123], v[140:143], v[204:207], v[120:123]
	v_mfma_f32_16x16x32_bf16 v[116:119], v[132:135], v[212:215], v[116:119]
	v_mfma_f32_16x16x32_bf16 v[112:115], v[140:143], v[212:215], v[112:115]
	v_mfma_f32_16x16x32_bf16 v[108:111], v[132:135], v[220:223], v[108:111]
	v_mfma_f32_16x16x32_bf16 v[104:107], v[140:143], v[220:223], v[104:107]
	v_mfma_f32_16x16x32_bf16 v[100:103], v[132:135], v[228:231], v[100:103]
	v_mfma_f32_16x16x32_bf16 v[96:99], v[140:143], v[228:231], v[96:99]
	v_mfma_f32_16x16x32_bf16 v[60:63], v[144:147], v[200:203], v[60:63]
	v_mfma_f32_16x16x32_bf16 v[56:59], v[152:155], v[200:203], v[56:59]
	v_mfma_f32_16x16x32_bf16 v[52:55], v[144:147], v[208:211], v[52:55]
	v_mfma_f32_16x16x32_bf16 v[48:51], v[152:155], v[208:211], v[48:51]
	v_mfma_f32_16x16x32_bf16 v[44:47], v[144:147], v[216:219], v[44:47]
	v_mfma_f32_16x16x32_bf16 v[40:43], v[152:155], v[216:219], v[40:43]
	v_mfma_f32_16x16x32_bf16 v[36:39], v[144:147], v[224:227], v[36:39]
	v_mfma_f32_16x16x32_bf16 v[32:35], v[152:155], v[224:227], v[32:35]
	v_mfma_f32_16x16x32_bf16 v[60:63], v[148:151], v[204:207], v[60:63]
	v_mfma_f32_16x16x32_bf16 v[56:59], v[196:199], v[204:207], v[56:59]
	v_mfma_f32_16x16x32_bf16 v[52:55], v[148:151], v[212:215], v[52:55]
	v_mfma_f32_16x16x32_bf16 v[48:51], v[196:199], v[212:215], v[48:51]
	v_mfma_f32_16x16x32_bf16 v[44:47], v[148:151], v[220:223], v[44:47]
	v_mfma_f32_16x16x32_bf16 v[40:43], v[196:199], v[220:223], v[40:43]
	v_mfma_f32_16x16x32_bf16 v[36:39], v[148:151], v[228:231], v[36:39]
	v_mfma_f32_16x16x32_bf16 v[32:35], v[196:199], v[228:231], v[32:35]
	s_barrier
; #define PG8_STAGE(bufoff, gbase, voff) do { _Pragma("unroll") for (int _i = 0; _i < 2; ++_i) \
;         __builtin_amdgcn_global_load_lds((const unsigned*)((const char*)(gbase) + (voff)[_i]), (PG8_LAS unsigned*)(lds + (bufoff) + ldsw + _i * 8192), 16, 0, 0); } while (0)
; #define PG8_LDA(dst, b, h) do { _Pragma("unroll") for (int m = 0; m < 4; ++m) _Pragma("unroll") for (int k = 0; k < 2; ++k) dst[m][k] = *(const PG8_LAS bf16x8*)(lds + PG8_SA(b, h) + aoff + m * 2048 + k * 1024); } while (0)
; #define PG8_MMA(ai, bj, At, Bt) do { __builtin_amdgcn_s_setprio(1); _Pragma("unroll") for (int m = 0; m < 4; ++m) _Pragma("unroll") for (int n = 0; n < 2; ++n) _Pragma("unroll") for (int k = 0; k < 2; ++k) \
;         acc[ai][bj][m][n] = __builtin_amdgcn_mfma_f32_16x16x32_bf16(Bt[n][k], At[m][k], acc[ai][bj][m][n], 0, 0, 0); __builtin_amdgcn_s_setprio(0); } while (0)
; #define PG8_WAIT_V(n) asm volatile("s_waitcnt vmcnt(" #n ")" ::: "memory")
; #define PG8_WAIT_L(n) asm volatile("s_waitcnt lgkmcnt(" #n ")" ::: "memory")
; #define PG8_BAR __builtin_amdgcn_s_barrier()
; #define PG8_SCHED __builtin_amdgcn_sched_barrier(0)
; template <class Epi, class Sched, bool ALIGN_EPI = false, bool SP2 = false>
; __device__ __forceinline__ void gemm_phase(PG8_LAS unsigned char* lds, const Gemm g, const Sched& S, const Epi& E) {
;     ...
;         for (int t = 0; t < nt; t += 2) {
;             const bool last = (t == nt - 2);
;             const char* a1 = cA + (long)(t + 1) * kstepA;
;             const char* a2 = last ? nA : cA + (long)(t + 2) * kstepA; const char* b2 = last ? nB : cB + (long)(t + 2) * kstep;
;             const char* a3 = a2 + kstepA; const char* b3 = b2 + kstep;
;             if (last && has_next) S.a_ready(nxt);
;     ...
;             PG8_LDA(At, 1, 1); PG8_STAGE(PG8_SB(1, 0), b3, voffB); PG8_STAGE(PG8_SB(1, 1), b3 + hstepB, voffB); PG8_STAGE(PG8_SA(1, 0), a3, voffA);
;             PG8_WAIT_V(8); PG8_WAIT_L(0); PG8_BAR; PG8_MMA(1, 0, At, B0); PG8_MMA(1, 1, At, B1); PG8_BAR; PG8_SCHED;
	s_add_u32 s54, s52, 0x20000
	s_addc_u32 s55, s53, 0
	s_add_i32 s70, s70, s16
	v_lshl_add_u64 v[180:181], s[54:55], 0, v[158:159]
	s_mov_b32 m0, s70
	ds_read_b128 v[200:203], v191 offset:49152
	ds_read_b128 v[204:207], v191 offset:50176
	ds_read_b128 v[208:211], v191 offset:51200
	ds_read_b128 v[212:215], v191 offset:52224
	ds_read_b128 v[216:219], v191 offset:53248
	ds_read_b128 v[220:223], v191 offset:54272
	ds_read_b128 v[224:227], v191 offset:55296
	ds_read_b128 v[228:231], v191 offset:56320
	global_load_lds_dwordx4 v[180:181], off
	s_add_i32 m0, s70, 0x2000
	s_add_u32 s52, s52, 0x24000
	v_lshl_add_u64 v[180:181], s[54:55], 0, v[162:163]
	s_addc_u32 s53, s53, 0
	s_add_i32 s54, s71, s16
	global_load_lds_dwordx4 v[180:181], off
	v_lshl_add_u64 v[180:181], s[52:53], 0, v[158:159]
	s_mov_b32 m0, s54
	s_nop 0
	global_load_lds_dwordx4 v[180:181], off
	v_lshl_add_u64 v[180:181], s[52:53], 0, v[162:163]
	s_add_i32 m0, s54, 0x2000
	s_nop 0
	global_load_lds_dwordx4 v[180:181], off
	v_lshl_add_u64 v[180:181], s[50:51], 0, v[156:157]
	s_mov_b32 m0, s62
	s_nop 0
	global_load_lds_dwordx4 v[180:181], off
	v_lshl_add_u64 v[180:181], s[50:51], 0, v[160:161]
	s_mov_b32 m0, s63
	s_nop 0
	global_load_lds_dwordx4 v[180:181], off
	s_waitcnt vmcnt(8)
	s_waitcnt lgkmcnt(0)
	s_barrier
	s_waitcnt lgkmcnt(0)
	v_mfma_f32_16x16x32_bf16 v[92:95], v[128:131], v[200:203], v[92:95]
	v_mfma_f32_16x16x32_bf16 v[88:91], v[136:139], v[200:203], v[88:91]
	v_mfma_f32_16x16x32_bf16 v[84:87], v[128:131], v[208:211], v[84:87]
	v_mfma_f32_16x16x32_bf16 v[80:83], v[136:139], v[208:211], v[80:83]
	v_mfma_f32_16x16x32_bf16 v[76:79], v[128:131], v[216:219], v[76:79]
	v_mfma_f32_16x16x32_bf16 v[72:75], v[136:139], v[216:219], v[72:75]
	v_mfma_f32_16x16x32_bf16 v[68:71], v[128:131], v[224:227], v[68:71]
	v_mfma_f32_16x16x32_bf16 v[64:67], v[136:139], v[224:227], v[64:67]
	v_mfma_f32_16x16x32_bf16 v[92:95], v[132:135], v[204:207], v[92:95]
	v_mfma_f32_16x16x32_bf16 v[88:91], v[140:143], v[204:207], v[88:91]
	v_mfma_f32_16x16x32_bf16 v[84:87], v[132:135], v[212:215], v[84:87]
	v_mfma_f32_16x16x32_bf16 v[80:83], v[140:143], v[212:215], v[80:83]
	v_mfma_f32_16x16x32_bf16 v[76:79], v[132:135], v[220:223], v[76:79]
	v_mfma_f32_16x16x32_bf16 v[72:75], v[140:143], v[220:223], v[72:75]
	v_mfma_f32_16x16x32_bf16 v[68:71], v[132:135], v[228:231], v[68:71]
	v_mfma_f32_16x16x32_bf16 v[64:67], v[140:143], v[228:231], v[64:67]
	v_mfma_f32_16x16x32_bf16 v[28:31], v[144:147], v[200:203], v[28:31]
	v_mfma_f32_16x16x32_bf16 v[24:27], v[152:155], v[200:203], v[24:27]
	v_mfma_f32_16x16x32_bf16 v[20:23], v[144:147], v[208:211], v[20:23]
	v_mfma_f32_16x16x32_bf16 v[16:19], v[152:155], v[208:211], v[16:19]
	v_mfma_f32_16x16x32_bf16 v[12:15], v[144:147], v[216:219], v[12:15]
	v_mfma_f32_16x16x32_bf16 v[8:11], v[152:155], v[216:219], v[8:11]
	v_mfma_f32_16x16x32_bf16 v[4:7], v[144:147], v[224:227], v[4:7]
	v_mfma_f32_16x16x32_bf16 v[0:3], v[152:155], v[224:227], v[0:3]
	v_mfma_f32_16x16x32_bf16 v[28:31], v[148:151], v[204:207], v[28:31]
	v_mfma_f32_16x16x32_bf16 v[24:27], v[196:199], v[204:207], v[24:27]
	v_mfma_f32_16x16x32_bf16 v[20:23], v[148:151], v[212:215], v[20:23]
	v_mfma_f32_16x16x32_bf16 v[16:19], v[196:199], v[212:215], v[16:19]
	v_mfma_f32_16x16x32_bf16 v[12:15], v[148:151], v[220:223], v[12:15]
	v_mfma_f32_16x16x32_bf16 v[8:11], v[196:199], v[220:223], v[8:11]
	v_mfma_f32_16x16x32_bf16 v[4:7], v[148:151], v[228:231], v[4:7]
	v_mfma_f32_16x16x32_bf16 v[0:3], v[196:199], v[228:231], v[0:3]
	s_barrier
	s_add_u32 s43, s43, 0x40000
	s_addc_u32 s47, s47, 0
	s_add_u32 s48, s48, 0x800000
	s_addc_u32 s49, s49, 0
	s_cmp_ge_i32 s69, s59
	s_mov_b32 s50, s69
	s_cbranch_scc0 .LBB0_1362

; #define PG8_STAGE(bufoff, gbase, voff) do { _Pragma("unroll") for (int _i = 0; _i < 2; ++_i) \
;         __builtin_amdgcn_global_load_lds((const unsigned*)((const char*)(gbase) + (voff)[_i]), (PG8_LAS unsigned*)(lds + (bufoff) + ldsw + _i * 8192), 16, 0, 0); } while (0)
; #define PG8_LDA(dst, b, h) do { _Pragma("unroll") for (int m = 0; m < 4; ++m) _Pragma("unroll") for (int k = 0; k < 2; ++k) dst[m][k] = *(const PG8_LAS bf16x8*)(lds + PG8_SA(b, h) + aoff + m * 2048 + k * 1024); } while (0)
; #define PG8_LDB(dst, b, h) do { _Pragma("unroll") for (int n = 0; n < 2; ++n) _Pragma("unroll") for (int k = 0; k < 2; ++k) dst[n][k] = *(const PG8_LAS bf16x8*)(lds + PG8_SB(b, h) + boff + n * 2048 + k * 1024); } while (0)
; #define PG8_MMA(ai, bj, At, Bt) do { __builtin_amdgcn_s_setprio(1); _Pragma("unroll") for (int m = 0; m < 4; ++m) _Pragma("unroll") for (int n = 0; n < 2; ++n) _Pragma("unroll") for (int k = 0; k < 2; ++k) \
;         acc[ai][bj][m][n] = __builtin_amdgcn_mfma_f32_16x16x32_bf16(Bt[n][k], At[m][k], acc[ai][bj][m][n], 0, 0, 0); __builtin_amdgcn_s_setprio(0); } while (0)
; #define PG8_WAIT_V(n) asm volatile("s_waitcnt vmcnt(" #n ")" ::: "memory")
; #define PG8_WAIT_L(n) asm volatile("s_waitcnt lgkmcnt(" #n ")" ::: "memory")
; #define PG8_BAR __builtin_amdgcn_s_barrier()
; #define PG8_SCHED __builtin_amdgcn_sched_barrier(0)
; template <class Epi, class Sched, bool ALIGN_EPI = false, bool SP2 = false>
; __device__ __forceinline__ void gemm_phase(PG8_LAS unsigned char* lds, const Gemm g, const Sched& S, const Epi& E) {
;     ...
;             PG8_LDB(B0, 0, 0); PG8_LDB(B1, 0, 1); PG8_SCHED; PG8_LDA(At, 0, 0); PG8_STAGE(PG8_SA(1, 1), a1 + hstepA, voffA);
;             PG8_WAIT_V(8); PG8_WAIT_L(0); PG8_BAR; PG8_MMA(0, 0, At, B0); PG8_MMA(0, 1, At, B1); PG8_BAR; PG8_SCHED;
;             PG8_LDA(At, 0, 1); PG8_STAGE(PG8_SB(0, 0), b2, voffB); PG8_STAGE(PG8_SB(0, 1), b2 + hstepB, voffB); PG8_STAGE(PG8_SA(0, 0), a2, voffA);
;             PG8_WAIT_V(8); PG8_WAIT_L(0); PG8_BAR; PG8_MMA(1, 0, At, B0); PG8_MMA(1, 1, At, B1); PG8_BAR; PG8_SCHED;
.LBB0_1455:
	ds_read_b128 v[104:107], v199
	ds_read_b128 v[108:111], v199 offset:1024
	ds_read_b128 v[112:115], v199 offset:2048
	ds_read_b128 v[116:119], v199 offset:3072
	ds_read_b128 v[120:123], v203
	ds_read_b128 v[124:127], v203 offset:1024
	ds_read_b128 v[136:139], v203 offset:2048
	ds_read_b128 v[140:143], v203 offset:3072
	s_add_i32 s21, s20, 2
	s_add_u32 s22, s12, 0xfffc0080
	s_addc_u32 s23, s13, -1
	s_cmp_eq_u32 s72, s20
	s_cselect_b32 s25, s14, s23
	s_cselect_b32 s24, s15, s22
	s_cselect_b32 s23, s16, s19
	s_cselect_b32 s22, s17, s18
	v_lshl_add_u64 v[184:185], s[12:13], 0, v[180:181]
	s_add_i32 m0, s34, 0xc000
	ds_read_b128 v[160:163], v207
	ds_read_b128 v[164:167], v207 offset:1024
	ds_read_b128 v[168:171], v207 offset:2048
	ds_read_b128 v[208:211], v207 offset:3072
	ds_read_b128 v[212:215], v207 offset:4096
	ds_read_b128 v[216:219], v207 offset:5120
	ds_read_b128 v[220:223], v207 offset:6144
	ds_read_b128 v[224:227], v207 offset:7168
	global_load_lds_dwordx4 v[184:185], off
	v_lshl_add_u64 v[184:185], s[12:13], 0, v[182:183]
	s_add_i32 m0, s34, 0xe000
	s_nop 0
	global_load_lds_dwordx4 v[184:185], off
	s_waitcnt vmcnt(8)
	s_waitcnt lgkmcnt(0)
	s_barrier
	s_waitcnt lgkmcnt(0)
	v_mfma_f32_16x16x32_bf16 v[156:159], v[104:107], v[160:163], v[156:159]
	v_mfma_f32_16x16x32_bf16 v[152:155], v[112:115], v[160:163], v[152:155]
	v_mfma_f32_16x16x32_bf16 v[148:151], v[104:107], v[168:171], v[148:151]
	v_mfma_f32_16x16x32_bf16 v[144:147], v[112:115], v[168:171], v[144:147]
	v_mfma_f32_16x16x32_bf16 v[132:135], v[104:107], v[212:215], v[132:135]
	v_mfma_f32_16x16x32_bf16 v[128:131], v[112:115], v[212:215], v[128:131]
	v_mfma_f32_16x16x32_bf16 v[100:103], v[104:107], v[220:223], v[100:103]
	v_mfma_f32_16x16x32_bf16 v[96:99], v[112:115], v[220:223], v[96:99]
	v_mfma_f32_16x16x32_bf16 v[156:159], v[108:111], v[164:167], v[156:159]
	v_mfma_f32_16x16x32_bf16 v[152:155], v[116:119], v[164:167], v[152:155]
	v_mfma_f32_16x16x32_bf16 v[148:151], v[108:111], v[208:211], v[148:151]
	v_mfma_f32_16x16x32_bf16 v[144:147], v[116:119], v[208:211], v[144:147]
	v_mfma_f32_16x16x32_bf16 v[132:135], v[108:111], v[216:219], v[132:135]
	v_mfma_f32_16x16x32_bf16 v[128:131], v[116:119], v[216:219], v[128:131]
	v_mfma_f32_16x16x32_bf16 v[100:103], v[108:111], v[224:227], v[100:103]
	v_mfma_f32_16x16x32_bf16 v[96:99], v[116:119], v[224:227], v[96:99]
	v_mfma_f32_16x16x32_bf16 v[60:63], v[120:123], v[160:163], v[60:63]
	v_mfma_f32_16x16x32_bf16 v[56:59], v[136:139], v[160:163], v[56:59]
	v_mfma_f32_16x16x32_bf16 v[52:55], v[120:123], v[168:171], v[52:55]
	v_mfma_f32_16x16x32_bf16 v[48:51], v[136:139], v[168:171], v[48:51]
	v_mfma_f32_16x16x32_bf16 v[44:47], v[120:123], v[212:215], v[44:47]
	v_mfma_f32_16x16x32_bf16 v[40:43], v[136:139], v[212:215], v[40:43]
	v_mfma_f32_16x16x32_bf16 v[36:39], v[120:123], v[220:223], v[36:39]
	v_mfma_f32_16x16x32_bf16 v[32:35], v[136:139], v[220:223], v[32:35]
	v_mfma_f32_16x16x32_bf16 v[60:63], v[124:127], v[164:167], v[60:63]
	v_mfma_f32_16x16x32_bf16 v[56:59], v[140:143], v[164:167], v[56:59]
	v_mfma_f32_16x16x32_bf16 v[52:55], v[124:127], v[208:211], v[52:55]
	v_mfma_f32_16x16x32_bf16 v[48:51], v[140:143], v[208:211], v[48:51]
	v_mfma_f32_16x16x32_bf16 v[44:47], v[124:127], v[216:219], v[44:47]
	v_mfma_f32_16x16x32_bf16 v[40:43], v[140:143], v[216:219], v[40:43]
	v_mfma_f32_16x16x32_bf16 v[36:39], v[124:127], v[224:227], v[36:39]
	v_mfma_f32_16x16x32_bf16 v[32:35], v[140:143], v[224:227], v[32:35]
	s_barrier
	s_add_i32 s20, s76, s31
	v_lshl_add_u64 v[184:185], s[22:23], 0, v[174:175]
	s_mov_b32 m0, s20
	ds_read_b128 v[160:163], v207 offset:16384
	ds_read_b128 v[164:167], v207 offset:17408
	ds_read_b128 v[168:171], v207 offset:18432
	ds_read_b128 v[208:211], v207 offset:19456
	ds_read_b128 v[212:215], v207 offset:20480
	ds_read_b128 v[216:219], v207 offset:21504
	ds_read_b128 v[220:223], v207 offset:22528
	ds_read_b128 v[224:227], v207 offset:23552
	global_load_lds_dwordx4 v[184:185], off
	s_add_i32 m0, s20, 0x2000
	s_add_u32 s70, s22, 0x40000
	v_lshl_add_u64 v[188:189], s[22:23], 0, v[178:179]
	s_addc_u32 s71, s23, 0
	s_add_i32 s20, s77, s31
	global_load_lds_dwordx4 v[188:189], off
	v_lshl_add_u64 v[192:193], s[70:71], 0, v[174:175]
	s_mov_b32 m0, s20
	v_lshl_add_u64 v[196:197], s[24:25], 0, v[176:177]
	global_load_lds_dwordx4 v[192:193], off
	v_lshl_add_u64 v[192:193], s[70:71], 0, v[178:179]
	s_add_i32 m0, s20, 0x2000
	s_nop 0
	global_load_lds_dwordx4 v[192:193], off
	v_lshl_add_u64 v[192:193], s[24:25], 0, v[172:173]
	s_mov_b32 m0, s34
	s_nop 0
	global_load_lds_dwordx4 v[192:193], off
	s_mov_b32 m0, s35
	s_nop 0
	global_load_lds_dwordx4 v[196:197], off
	s_waitcnt vmcnt(8)
	s_waitcnt lgkmcnt(0)
	s_barrier
; #define PG8_STAGE(bufoff, gbase, voff) do { _Pragma("unroll") for (int _i = 0; _i < 2; ++_i) \
;         __builtin_amdgcn_global_load_lds((const unsigned*)((const char*)(gbase) + (voff)[_i]), (PG8_LAS unsigned*)(lds + (bufoff) + ldsw + _i * 8192), 16, 0, 0); } while (0)
; #define PG8_LDA(dst, b, h) do { _Pragma("unroll") for (int m = 0; m < 4; ++m) _Pragma("unroll") for (int k = 0; k < 2; ++k) dst[m][k] = *(const PG8_LAS bf16x8*)(lds + PG8_SA(b, h) + aoff + m * 2048 + k * 1024); } while (0)
; #define PG8_LDB(dst, b, h) do { _Pragma("unroll") for (int n = 0; n < 2; ++n) _Pragma("unroll") for (int k = 0; k < 2; ++k) dst[n][k] = *(const PG8_LAS bf16x8*)(lds + PG8_SB(b, h) + boff + n * 2048 + k * 1024); } while (0)
; #define PG8_MMA(ai, bj, At, Bt) do { __builtin_amdgcn_s_setprio(1); _Pragma("unroll") for (int m = 0; m < 4; ++m) _Pragma("unroll") for (int n = 0; n < 2; ++n) _Pragma("unroll") for (int k = 0; k < 2; ++k) \
;         acc[ai][bj][m][n] = __builtin_amdgcn_mfma_f32_16x16x32_bf16(Bt[n][k], At[m][k], acc[ai][bj][m][n], 0, 0, 0); __builtin_amdgcn_s_setprio(0); } while (0)
; #define PG8_WAIT_V(n) asm volatile("s_waitcnt vmcnt(" #n ")" ::: "memory")
; #define PG8_WAIT_L(n) asm volatile("s_waitcnt lgkmcnt(" #n ")" ::: "memory")
; #define PG8_BAR __builtin_amdgcn_s_barrier()
; #define PG8_SCHED __builtin_amdgcn_sched_barrier(0)
; template <class Epi, class Sched, bool ALIGN_EPI = false, bool SP2 = false>
; __device__ __forceinline__ void gemm_phase(PG8_LAS unsigned char* lds, const Gemm g, const Sched& S, const Epi& E) {
;     ...
;             PG8_WAIT_V(8); PG8_WAIT_L(0); PG8_BAR; PG8_MMA(1, 0, At, B0); PG8_MMA(1, 1, At, B1); PG8_BAR; PG8_SCHED;
;             PG8_LDB(B0, 1, 0); PG8_LDB(B1, 1, 1); PG8_SCHED; PG8_LDA(At, 1, 0); PG8_STAGE(PG8_SA(0, 1), a2 + hstepA, voffA);
;             PG8_WAIT_V(8); PG8_WAIT_L(0); PG8_BAR; PG8_MMA(0, 0, At, B0); PG8_MMA(0, 1, At, B1); PG8_BAR; PG8_SCHED;
	s_waitcnt lgkmcnt(0)
	v_mfma_f32_16x16x32_bf16 v[92:95], v[104:107], v[160:163], v[92:95]
	v_mfma_f32_16x16x32_bf16 v[88:91], v[112:115], v[160:163], v[88:91]
	v_mfma_f32_16x16x32_bf16 v[84:87], v[104:107], v[168:171], v[84:87]
	v_mfma_f32_16x16x32_bf16 v[80:83], v[112:115], v[168:171], v[80:83]
	v_mfma_f32_16x16x32_bf16 v[76:79], v[104:107], v[212:215], v[76:79]
	v_mfma_f32_16x16x32_bf16 v[72:75], v[112:115], v[212:215], v[72:75]
	v_mfma_f32_16x16x32_bf16 v[68:71], v[104:107], v[220:223], v[68:71]
	v_mfma_f32_16x16x32_bf16 v[64:67], v[112:115], v[220:223], v[64:67]
	v_mfma_f32_16x16x32_bf16 v[92:95], v[108:111], v[164:167], v[92:95]
	v_mfma_f32_16x16x32_bf16 v[88:91], v[116:119], v[164:167], v[88:91]
	v_mfma_f32_16x16x32_bf16 v[84:87], v[108:111], v[208:211], v[84:87]
	v_mfma_f32_16x16x32_bf16 v[80:83], v[116:119], v[208:211], v[80:83]
	v_mfma_f32_16x16x32_bf16 v[76:79], v[108:111], v[216:219], v[76:79]
	v_mfma_f32_16x16x32_bf16 v[72:75], v[116:119], v[216:219], v[72:75]
	v_mfma_f32_16x16x32_bf16 v[68:71], v[108:111], v[224:227], v[68:71]
	v_mfma_f32_16x16x32_bf16 v[64:67], v[116:119], v[224:227], v[64:67]
	v_mfma_f32_16x16x32_bf16 v[28:31], v[120:123], v[160:163], v[28:31]
	v_mfma_f32_16x16x32_bf16 v[24:27], v[136:139], v[160:163], v[24:27]
	v_mfma_f32_16x16x32_bf16 v[20:23], v[120:123], v[168:171], v[20:23]
	v_mfma_f32_16x16x32_bf16 v[16:19], v[136:139], v[168:171], v[16:19]
	v_mfma_f32_16x16x32_bf16 v[12:15], v[120:123], v[212:215], v[12:15]
	v_mfma_f32_16x16x32_bf16 v[8:11], v[136:139], v[212:215], v[8:11]
	v_mfma_f32_16x16x32_bf16 v[4:7], v[120:123], v[220:223], v[4:7]
	v_mfma_f32_16x16x32_bf16 v[0:3], v[136:139], v[220:223], v[0:3]
	v_mfma_f32_16x16x32_bf16 v[28:31], v[124:127], v[164:167], v[28:31]
	v_mfma_f32_16x16x32_bf16 v[24:27], v[140:143], v[164:167], v[24:27]
	v_mfma_f32_16x16x32_bf16 v[20:23], v[124:127], v[208:211], v[20:23]
	v_mfma_f32_16x16x32_bf16 v[16:19], v[140:143], v[208:211], v[16:19]
	v_mfma_f32_16x16x32_bf16 v[12:15], v[124:127], v[216:219], v[12:15]
	v_mfma_f32_16x16x32_bf16 v[8:11], v[140:143], v[216:219], v[8:11]
	v_mfma_f32_16x16x32_bf16 v[4:7], v[124:127], v[224:227], v[4:7]
	v_mfma_f32_16x16x32_bf16 v[0:3], v[140:143], v[224:227], v[0:3]
	s_barrier
	s_add_i32 s20, 0, 0x18000
	s_add_i32 s33, 0, 0x1c000
	v_add_u32_e32 v116, s20, v195
	v_add_u32_e32 v140, s33, v195
	ds_read_b128 v[104:107], v116
	ds_read_b128 v[108:111], v116 offset:1024
	ds_read_b128 v[112:115], v116 offset:2048
	ds_read_b128 v[116:119], v116 offset:3072
	ds_read_b128 v[120:123], v140
	ds_read_b128 v[124:127], v140 offset:1024
	ds_read_b128 v[136:139], v140 offset:2048
	ds_read_b128 v[140:143], v140 offset:3072
	s_add_u32 s24, s24, 0x40000
	s_addc_u32 s25, s25, 0
	s_mov_b32 m0, s36
	v_lshl_add_u64 v[200:201], s[24:25], 0, v[172:173]
	ds_read_b128 v[160:163], v207 offset:32768
	ds_read_b128 v[164:167], v207 offset:33792
	ds_read_b128 v[168:171], v207 offset:34816
	ds_read_b128 v[208:211], v207 offset:35840
	ds_read_b128 v[212:215], v207 offset:36864
	ds_read_b128 v[216:219], v207 offset:37888
	ds_read_b128 v[220:223], v207 offset:38912
	ds_read_b128 v[224:227], v207 offset:39936
	global_load_lds_dwordx4 v[200:201], off
	v_lshl_add_u64 v[200:201], s[24:25], 0, v[176:177]
	s_mov_b32 m0, s37
	s_nop 0
	global_load_lds_dwordx4 v[200:201], off
	s_waitcnt vmcnt(8)
	s_waitcnt lgkmcnt(0)
	s_barrier
	s_waitcnt lgkmcnt(0)
	v_mfma_f32_16x16x32_bf16 v[156:159], v[104:107], v[160:163], v[156:159]
	v_mfma_f32_16x16x32_bf16 v[152:155], v[112:115], v[160:163], v[152:155]
	v_mfma_f32_16x16x32_bf16 v[148:151], v[104:107], v[168:171], v[148:151]
	v_mfma_f32_16x16x32_bf16 v[144:147], v[112:115], v[168:171], v[144:147]
	v_mfma_f32_16x16x32_bf16 v[132:135], v[104:107], v[212:215], v[132:135]
	v_mfma_f32_16x16x32_bf16 v[128:131], v[112:115], v[212:215], v[128:131]
	v_mfma_f32_16x16x32_bf16 v[100:103], v[104:107], v[220:223], v[100:103]
	v_mfma_f32_16x16x32_bf16 v[96:99], v[112:115], v[220:223], v[96:99]
	v_mfma_f32_16x16x32_bf16 v[156:159], v[108:111], v[164:167], v[156:159]
	v_mfma_f32_16x16x32_bf16 v[152:155], v[116:119], v[164:167], v[152:155]
	v_mfma_f32_16x16x32_bf16 v[148:151], v[108:111], v[208:211], v[148:151]
	v_mfma_f32_16x16x32_bf16 v[144:147], v[116:119], v[208:211], v[144:147]
	v_mfma_f32_16x16x32_bf16 v[132:135], v[108:111], v[216:219], v[132:135]
	v_mfma_f32_16x16x32_bf16 v[128:131], v[116:119], v[216:219], v[128:131]
	v_mfma_f32_16x16x32_bf16 v[100:103], v[108:111], v[224:227], v[100:103]
	v_mfma_f32_16x16x32_bf16 v[96:99], v[116:119], v[224:227], v[96:99]
	v_mfma_f32_16x16x32_bf16 v[60:63], v[120:123], v[160:163], v[60:63]
	v_mfma_f32_16x16x32_bf16 v[56:59], v[136:139], v[160:163], v[56:59]
	v_mfma_f32_16x16x32_bf16 v[52:55], v[120:123], v[168:171], v[52:55]
	v_mfma_f32_16x16x32_bf16 v[48:51], v[136:139], v[168:171], v[48:51]
	v_mfma_f32_16x16x32_bf16 v[44:47], v[120:123], v[212:215], v[44:47]
	v_mfma_f32_16x16x32_bf16 v[40:43], v[136:139], v[212:215], v[40:43]
	v_mfma_f32_16x16x32_bf16 v[36:39], v[120:123], v[220:223], v[36:39]
	v_mfma_f32_16x16x32_bf16 v[32:35], v[136:139], v[220:223], v[32:35]
	v_mfma_f32_16x16x32_bf16 v[60:63], v[124:127], v[164:167], v[60:63]
	v_mfma_f32_16x16x32_bf16 v[56:59], v[140:143], v[164:167], v[56:59]
	v_mfma_f32_16x16x32_bf16 v[52:55], v[124:127], v[208:211], v[52:55]
	v_mfma_f32_16x16x32_bf16 v[48:51], v[140:143], v[208:211], v[48:51]
	v_mfma_f32_16x16x32_bf16 v[44:47], v[124:127], v[216:219], v[44:47]
	v_mfma_f32_16x16x32_bf16 v[40:43], v[140:143], v[216:219], v[40:43]
	v_mfma_f32_16x16x32_bf16 v[36:39], v[124:127], v[224:227], v[36:39]
	v_mfma_f32_16x16x32_bf16 v[32:35], v[140:143], v[224:227], v[32:35]
	s_barrier
; #define PG8_STAGE(bufoff, gbase, voff) do { _Pragma("unroll") for (int _i = 0; _i < 2; ++_i) \
;         __builtin_amdgcn_global_load_lds((const unsigned*)((const char*)(gbase) + (voff)[_i]), (PG8_LAS unsigned*)(lds + (bufoff) + ldsw + _i * 8192), 16, 0, 0); } while (0)
; #define PG8_LDA(dst, b, h) do { _Pragma("unroll") for (int m = 0; m < 4; ++m) _Pragma("unroll") for (int k = 0; k < 2; ++k) dst[m][k] = *(const PG8_LAS bf16x8*)(lds + PG8_SA(b, h) + aoff + m * 2048 + k * 1024); } while (0)
; #define PG8_MMA(ai, bj, At, Bt) do { __builtin_amdgcn_s_setprio(1); _Pragma("unroll") for (int m = 0; m < 4; ++m) _Pragma("unroll") for (int n = 0; n < 2; ++n) _Pragma("unroll") for (int k = 0; k < 2; ++k) \
;         acc[ai][bj][m][n] = __builtin_amdgcn_mfma_f32_16x16x32_bf16(Bt[n][k], At[m][k], acc[ai][bj][m][n], 0, 0, 0); __builtin_amdgcn_s_setprio(0); } while (0)
; #define PG8_WAIT_V(n) asm volatile("s_waitcnt vmcnt(" #n ")" ::: "memory")
; #define PG8_WAIT_L(n) asm volatile("s_waitcnt lgkmcnt(" #n ")" ::: "memory")
; #define PG8_BAR __builtin_amdgcn_s_barrier()
; #define PG8_SCHED __builtin_amdgcn_sched_barrier(0)
; template <class Epi, class Sched, bool ALIGN_EPI = false, bool SP2 = false>
; __device__ __forceinline__ void gemm_phase(PG8_LAS unsigned char* lds, const Gemm g, const Sched& S, const Epi& E) {
;     ...
;         for (int t = 0; t < nt; t += 2) {
;             const bool last = (t == nt - 2);
;             const char* a1 = cA + (long)(t + 1) * kstepA;
;             const char* a2 = last ? nA : cA + (long)(t + 2) * kstepA; const char* b2 = last ? nB : cB + (long)(t + 2) * kstep;
;             const char* a3 = a2 + kstepA; const char* b3 = b2 + kstep;
;             if (last && has_next) S.a_ready(nxt);
;     ...
;             PG8_LDA(At, 1, 1); PG8_STAGE(PG8_SB(1, 0), b3, voffB); PG8_STAGE(PG8_SB(1, 1), b3 + hstepB, voffB); PG8_STAGE(PG8_SA(1, 0), a3, voffA);
;             PG8_WAIT_V(8); PG8_WAIT_L(0); PG8_BAR; PG8_MMA(1, 0, At, B0); PG8_MMA(1, 1, At, B1); PG8_BAR; PG8_SCHED;
	s_add_i32 s20, s20, s31
	v_lshl_add_u64 v[184:185], v[184:185], 0, s[52:53]
	s_mov_b32 m0, s20
	ds_read_b128 v[160:163], v207 offset:49152
	ds_read_b128 v[164:167], v207 offset:50176
	ds_read_b128 v[168:171], v207 offset:51200
	ds_read_b128 v[208:211], v207 offset:52224
	ds_read_b128 v[212:215], v207 offset:53248
	ds_read_b128 v[216:219], v207 offset:54272
	ds_read_b128 v[220:223], v207 offset:55296
	ds_read_b128 v[224:227], v207 offset:56320
	global_load_lds_dwordx4 v[184:185], off
	s_add_i32 m0, s20, 0x2000
	s_add_u32 s22, s22, 0x40080
	v_lshl_add_u64 v[184:185], v[188:189], 0, s[52:53]
	s_addc_u32 s23, s23, 0
	s_add_i32 s20, s33, s31
	global_load_lds_dwordx4 v[184:185], off
	v_lshl_add_u64 v[184:185], s[22:23], 0, v[174:175]
	s_mov_b32 m0, s20
	s_nop 0
	global_load_lds_dwordx4 v[184:185], off
	v_lshl_add_u64 v[184:185], s[22:23], 0, v[178:179]
	s_add_i32 m0, s20, 0x2000
	s_nop 0
	global_load_lds_dwordx4 v[184:185], off
	v_lshl_add_u64 v[184:185], v[192:193], 0, s[52:53]
	s_mov_b32 m0, s68
	s_nop 0
	global_load_lds_dwordx4 v[184:185], off
	v_lshl_add_u64 v[184:185], v[196:197], 0, s[52:53]
	s_mov_b32 m0, s69
	s_nop 0
	global_load_lds_dwordx4 v[184:185], off
	s_waitcnt vmcnt(8)
	s_waitcnt lgkmcnt(0)
	s_barrier
	s_waitcnt lgkmcnt(0)
	v_mfma_f32_16x16x32_bf16 v[92:95], v[104:107], v[160:163], v[92:95]
	v_mfma_f32_16x16x32_bf16 v[88:91], v[112:115], v[160:163], v[88:91]
	v_mfma_f32_16x16x32_bf16 v[84:87], v[104:107], v[168:171], v[84:87]
	v_mfma_f32_16x16x32_bf16 v[80:83], v[112:115], v[168:171], v[80:83]
	v_mfma_f32_16x16x32_bf16 v[76:79], v[104:107], v[212:215], v[76:79]
	v_mfma_f32_16x16x32_bf16 v[72:75], v[112:115], v[212:215], v[72:75]
	v_mfma_f32_16x16x32_bf16 v[68:71], v[104:107], v[220:223], v[68:71]
	v_mfma_f32_16x16x32_bf16 v[64:67], v[112:115], v[220:223], v[64:67]
	v_mfma_f32_16x16x32_bf16 v[92:95], v[108:111], v[164:167], v[92:95]
	v_mfma_f32_16x16x32_bf16 v[88:91], v[116:119], v[164:167], v[88:91]
	v_mfma_f32_16x16x32_bf16 v[84:87], v[108:111], v[208:211], v[84:87]
	v_mfma_f32_16x16x32_bf16 v[80:83], v[116:119], v[208:211], v[80:83]
	v_mfma_f32_16x16x32_bf16 v[76:79], v[108:111], v[216:219], v[76:79]
	v_mfma_f32_16x16x32_bf16 v[72:75], v[116:119], v[216:219], v[72:75]
	v_mfma_f32_16x16x32_bf16 v[68:71], v[108:111], v[224:227], v[68:71]
	v_mfma_f32_16x16x32_bf16 v[64:67], v[116:119], v[224:227], v[64:67]
	v_mfma_f32_16x16x32_bf16 v[28:31], v[120:123], v[160:163], v[28:31]
	v_mfma_f32_16x16x32_bf16 v[24:27], v[136:139], v[160:163], v[24:27]
	v_mfma_f32_16x16x32_bf16 v[20:23], v[120:123], v[168:171], v[20:23]
	v_mfma_f32_16x16x32_bf16 v[16:19], v[136:139], v[168:171], v[16:19]
	v_mfma_f32_16x16x32_bf16 v[12:15], v[120:123], v[212:215], v[12:15]
	v_mfma_f32_16x16x32_bf16 v[8:11], v[136:139], v[212:215], v[8:11]
	v_mfma_f32_16x16x32_bf16 v[4:7], v[120:123], v[220:223], v[4:7]
	v_mfma_f32_16x16x32_bf16 v[0:3], v[136:139], v[220:223], v[0:3]
	v_mfma_f32_16x16x32_bf16 v[28:31], v[124:127], v[164:167], v[28:31]
	v_mfma_f32_16x16x32_bf16 v[24:27], v[140:143], v[164:167], v[24:27]
	v_mfma_f32_16x16x32_bf16 v[20:23], v[124:127], v[208:211], v[20:23]
	v_mfma_f32_16x16x32_bf16 v[16:19], v[140:143], v[208:211], v[16:19]
	v_mfma_f32_16x16x32_bf16 v[12:15], v[124:127], v[216:219], v[12:15]
	v_mfma_f32_16x16x32_bf16 v[8:11], v[140:143], v[216:219], v[8:11]
	v_mfma_f32_16x16x32_bf16 v[4:7], v[124:127], v[224:227], v[4:7]
	v_mfma_f32_16x16x32_bf16 v[0:3], v[140:143], v[224:227], v[0:3]
	s_barrier
	s_add_u32 s12, s12, 0x100
	s_addc_u32 s13, s13, 0
	s_add_u32 s18, s18, 0x100
	s_addc_u32 s19, s19, 0
	s_cmp_ge_i32 s21, s27
	s_mov_b32 s20, s21
	s_cbranch_scc0 .LBB0_1455

; #define PG8_STAGE(bufoff, gbase, voff) do { _Pragma("unroll") for (int _i = 0; _i < 2; ++_i) \
;         __builtin_amdgcn_global_load_lds((const unsigned*)((const char*)(gbase) + (voff)[_i]), (PG8_LAS unsigned*)(lds + (bufoff) + ldsw + _i * 8192), 16, 0, 0); } while (0)
; #define PG8_LDA(dst, b, h) do { _Pragma("unroll") for (int m = 0; m < 4; ++m) _Pragma("unroll") for (int k = 0; k < 2; ++k) dst[m][k] = *(const PG8_LAS bf16x8*)(lds + PG8_SA(b, h) + aoff + m * 2048 + k * 1024); } while (0)
; #define PG8_LDB(dst, b, h) do { _Pragma("unroll") for (int n = 0; n < 2; ++n) _Pragma("unroll") for (int k = 0; k < 2; ++k) dst[n][k] = *(const PG8_LAS bf16x8*)(lds + PG8_SB(b, h) + boff + n * 2048 + k * 1024); } while (0)
; #define PG8_MMA(ai, bj, At, Bt) do { __builtin_amdgcn_s_setprio(1); _Pragma("unroll") for (int m = 0; m < 4; ++m) _Pragma("unroll") for (int n = 0; n < 2; ++n) _Pragma("unroll") for (int k = 0; k < 2; ++k) \
;         acc[ai][bj][m][n] = __builtin_amdgcn_mfma_f32_16x16x32_bf16(Bt[n][k], At[m][k], acc[ai][bj][m][n], 0, 0, 0); __builtin_amdgcn_s_setprio(0); } while (0)
; #define PG8_WAIT_V(n) asm volatile("s_waitcnt vmcnt(" #n ")" ::: "memory")
; #define PG8_WAIT_L(n) asm volatile("s_waitcnt lgkmcnt(" #n ")" ::: "memory")
; #define PG8_BAR __builtin_amdgcn_s_barrier()
; #define PG8_SCHED __builtin_amdgcn_sched_barrier(0)
; template <class Epi, class Sched, bool ALIGN_EPI = false, bool SP2 = false>
; __device__ __forceinline__ void gemm_phase(PG8_LAS unsigned char* lds, const Gemm g, const Sched& S, const Epi& E) {
;     ...
;             PG8_LDB(B0, 0, 0); PG8_LDB(B1, 0, 1); PG8_SCHED; PG8_LDA(At, 0, 0); PG8_STAGE(PG8_SA(1, 1), a1 + hstepA, voffA);
;             PG8_WAIT_V(8); PG8_WAIT_L(0); PG8_BAR; PG8_MMA(0, 0, At, B0); PG8_MMA(0, 1, At, B1); PG8_BAR; PG8_SCHED;
;             PG8_LDA(At, 0, 1); PG8_STAGE(PG8_SB(0, 0), b2, voffB); PG8_STAGE(PG8_SB(0, 1), b2 + hstepB, voffB); PG8_STAGE(PG8_SA(0, 0), a2, voffA);
;             PG8_WAIT_V(8); PG8_WAIT_L(0); PG8_BAR; PG8_MMA(1, 0, At, B0); PG8_MMA(1, 1, At, B1); PG8_BAR; PG8_SCHED;
.LBB0_1523:
	ds_read_b128 v[152:155], v149
	ds_read_b128 v[156:159], v149 offset:1024
	ds_read_b128 v[160:163], v149 offset:2048
	ds_read_b128 v[164:167], v149 offset:3072
	ds_read_b128 v[168:171], v150
	ds_read_b128 v[172:175], v150 offset:1024
	ds_read_b128 v[176:179], v150 offset:2048
	ds_read_b128 v[180:183], v150 offset:3072
	s_add_i32 s60, s36, 2
	s_add_u32 s37, s34, 0xfffc0080
	s_addc_u32 s42, s35, -1
	s_cmp_eq_u32 s50, s36
	s_cselect_b32 s36, s57, s58
	s_cselect_b32 s43, s23, s42
	s_cselect_b32 s42, s25, s37
	s_cselect_b32 s37, s56, s59
	v_lshl_add_u64 v[144:145], s[34:35], 0, v[136:137]
	s_add_i32 m0, s20, 0xc000
	ds_read_b128 v[184:187], v151
	ds_read_b128 v[188:191], v151 offset:1024
	ds_read_b128 v[192:195], v151 offset:2048
	ds_read_b128 v[196:199], v151 offset:3072
	ds_read_b128 v[200:203], v151 offset:4096
	ds_read_b128 v[204:207], v151 offset:5120
	ds_read_b128 v[208:211], v151 offset:6144
	ds_read_b128 v[212:215], v151 offset:7168
	global_load_lds_dwordx4 v[144:145], off
	v_lshl_add_u64 v[144:145], s[34:35], 0, v[138:139]
	s_add_i32 m0, s20, 0xe000
	s_nop 0
	global_load_lds_dwordx4 v[144:145], off
	s_waitcnt vmcnt(8)
	s_waitcnt lgkmcnt(0)
	s_barrier
	s_waitcnt lgkmcnt(0)
	v_mfma_f32_16x16x32_bf16 v[120:123], v[152:155], v[184:187], v[120:123]
	v_mfma_f32_16x16x32_bf16 v[116:119], v[160:163], v[184:187], v[116:119]
	v_mfma_f32_16x16x32_bf16 v[108:111], v[152:155], v[192:195], v[108:111]
	v_mfma_f32_16x16x32_bf16 v[100:103], v[160:163], v[192:195], v[100:103]
	v_mfma_f32_16x16x32_bf16 v[92:95], v[152:155], v[200:203], v[92:95]
	v_mfma_f32_16x16x32_bf16 v[84:87], v[160:163], v[200:203], v[84:87]
	v_mfma_f32_16x16x32_bf16 v[76:79], v[152:155], v[208:211], v[76:79]
	v_mfma_f32_16x16x32_bf16 v[68:71], v[160:163], v[208:211], v[68:71]
	v_mfma_f32_16x16x32_bf16 v[120:123], v[156:159], v[188:191], v[120:123]
	v_mfma_f32_16x16x32_bf16 v[116:119], v[164:167], v[188:191], v[116:119]
	v_mfma_f32_16x16x32_bf16 v[108:111], v[156:159], v[196:199], v[108:111]
	v_mfma_f32_16x16x32_bf16 v[100:103], v[164:167], v[196:199], v[100:103]
	v_mfma_f32_16x16x32_bf16 v[92:95], v[156:159], v[204:207], v[92:95]
	v_mfma_f32_16x16x32_bf16 v[84:87], v[164:167], v[204:207], v[84:87]
	v_mfma_f32_16x16x32_bf16 v[76:79], v[156:159], v[212:215], v[76:79]
	v_mfma_f32_16x16x32_bf16 v[68:71], v[164:167], v[212:215], v[68:71]
	v_mfma_f32_16x16x32_bf16 v[124:127], v[168:171], v[184:187], v[124:127]
	v_mfma_f32_16x16x32_bf16 v[112:115], v[176:179], v[184:187], v[112:115]
	v_mfma_f32_16x16x32_bf16 v[104:107], v[168:171], v[192:195], v[104:107]
	v_mfma_f32_16x16x32_bf16 v[96:99], v[176:179], v[192:195], v[96:99]
	v_mfma_f32_16x16x32_bf16 v[88:91], v[168:171], v[200:203], v[88:91]
	v_mfma_f32_16x16x32_bf16 v[80:83], v[176:179], v[200:203], v[80:83]
	v_mfma_f32_16x16x32_bf16 v[72:75], v[168:171], v[208:211], v[72:75]
	v_mfma_f32_16x16x32_bf16 v[64:67], v[176:179], v[208:211], v[64:67]
	v_mfma_f32_16x16x32_bf16 v[124:127], v[172:175], v[188:191], v[124:127]
	v_mfma_f32_16x16x32_bf16 v[112:115], v[180:183], v[188:191], v[112:115]
	v_mfma_f32_16x16x32_bf16 v[104:107], v[172:175], v[196:199], v[104:107]
	v_mfma_f32_16x16x32_bf16 v[96:99], v[180:183], v[196:199], v[96:99]
	v_mfma_f32_16x16x32_bf16 v[88:91], v[172:175], v[204:207], v[88:91]
	v_mfma_f32_16x16x32_bf16 v[80:83], v[180:183], v[204:207], v[80:83]
	v_mfma_f32_16x16x32_bf16 v[72:75], v[172:175], v[212:215], v[72:75]
	v_mfma_f32_16x16x32_bf16 v[64:67], v[180:183], v[212:215], v[64:67]
	s_barrier
	s_add_i32 s61, s54, s17
	v_lshl_add_u64 v[144:145], s[36:37], 0, v[132:133]
	s_mov_b32 m0, s61
	ds_read_b128 v[184:187], v151 offset:16384
	ds_read_b128 v[188:191], v151 offset:17408
	ds_read_b128 v[192:195], v151 offset:18432
	ds_read_b128 v[196:199], v151 offset:19456
	ds_read_b128 v[200:203], v151 offset:20480
	ds_read_b128 v[204:207], v151 offset:21504
	ds_read_b128 v[208:211], v151 offset:22528
	ds_read_b128 v[212:215], v151 offset:23552
	global_load_lds_dwordx4 v[144:145], off
	s_add_i32 m0, s61, 0x2000
	s_add_u32 s62, s36, 0x40000
	v_lshl_add_u64 v[216:217], s[36:37], 0, v[128:129]
	s_addc_u32 s63, s37, 0
	s_add_i32 s61, s55, s17
	global_load_lds_dwordx4 v[216:217], off
	v_lshl_add_u64 v[218:219], s[62:63], 0, v[132:133]
	s_mov_b32 m0, s61
	v_lshl_add_u64 v[220:221], s[42:43], 0, v[130:131]
	global_load_lds_dwordx4 v[218:219], off
	v_lshl_add_u64 v[218:219], s[62:63], 0, v[128:129]
	s_add_i32 m0, s61, 0x2000
	s_nop 0
	global_load_lds_dwordx4 v[218:219], off
	v_lshl_add_u64 v[218:219], s[42:43], 0, v[134:135]
	s_mov_b32 m0, s20
	s_nop 0
	global_load_lds_dwordx4 v[218:219], off
	s_mov_b32 m0, s21
	s_nop 0
	global_load_lds_dwordx4 v[220:221], off
	s_waitcnt vmcnt(8)
	s_waitcnt lgkmcnt(0)
	s_barrier
; #define PG8_STAGE(bufoff, gbase, voff) do { _Pragma("unroll") for (int _i = 0; _i < 2; ++_i) \
;         __builtin_amdgcn_global_load_lds((const unsigned*)((const char*)(gbase) + (voff)[_i]), (PG8_LAS unsigned*)(lds + (bufoff) + ldsw + _i * 8192), 16, 0, 0); } while (0)
; #define PG8_LDA(dst, b, h) do { _Pragma("unroll") for (int m = 0; m < 4; ++m) _Pragma("unroll") for (int k = 0; k < 2; ++k) dst[m][k] = *(const PG8_LAS bf16x8*)(lds + PG8_SA(b, h) + aoff + m * 2048 + k * 1024); } while (0)
; #define PG8_LDB(dst, b, h) do { _Pragma("unroll") for (int n = 0; n < 2; ++n) _Pragma("unroll") for (int k = 0; k < 2; ++k) dst[n][k] = *(const PG8_LAS bf16x8*)(lds + PG8_SB(b, h) + boff + n * 2048 + k * 1024); } while (0)
; #define PG8_MMA(ai, bj, At, Bt) do { __builtin_amdgcn_s_setprio(1); _Pragma("unroll") for (int m = 0; m < 4; ++m) _Pragma("unroll") for (int n = 0; n < 2; ++n) _Pragma("unroll") for (int k = 0; k < 2; ++k) \
;         acc[ai][bj][m][n] = __builtin_amdgcn_mfma_f32_16x16x32_bf16(Bt[n][k], At[m][k], acc[ai][bj][m][n], 0, 0, 0); __builtin_amdgcn_s_setprio(0); } while (0)
; #define PG8_WAIT_V(n) asm volatile("s_waitcnt vmcnt(" #n ")" ::: "memory")
; #define PG8_WAIT_L(n) asm volatile("s_waitcnt lgkmcnt(" #n ")" ::: "memory")
; #define PG8_BAR __builtin_amdgcn_s_barrier()
; #define PG8_SCHED __builtin_amdgcn_sched_barrier(0)
; template <class Epi, class Sched, bool ALIGN_EPI = false, bool SP2 = false>
; __device__ __forceinline__ void gemm_phase(PG8_LAS unsigned char* lds, const Gemm g, const Sched& S, const Epi& E) {
;     ...
;             PG8_WAIT_V(8); PG8_WAIT_L(0); PG8_BAR; PG8_MMA(1, 0, At, B0); PG8_MMA(1, 1, At, B1); PG8_BAR; PG8_SCHED;
;             PG8_LDB(B0, 1, 0); PG8_LDB(B1, 1, 1); PG8_SCHED; PG8_LDA(At, 1, 0); PG8_STAGE(PG8_SA(0, 1), a2 + hstepA, voffA);
;             PG8_WAIT_V(8); PG8_WAIT_L(0); PG8_BAR; PG8_MMA(0, 0, At, B0); PG8_MMA(0, 1, At, B1); PG8_BAR; PG8_SCHED;
	s_waitcnt lgkmcnt(0)
	v_mfma_f32_16x16x32_bf16 v[60:63], v[152:155], v[184:187], v[60:63]
	v_mfma_f32_16x16x32_bf16 v[52:55], v[160:163], v[184:187], v[52:55]
	v_mfma_f32_16x16x32_bf16 v[44:47], v[152:155], v[192:195], v[44:47]
	v_mfma_f32_16x16x32_bf16 v[36:39], v[160:163], v[192:195], v[36:39]
	v_mfma_f32_16x16x32_bf16 v[28:31], v[152:155], v[200:203], v[28:31]
	v_mfma_f32_16x16x32_bf16 v[20:23], v[160:163], v[200:203], v[20:23]
	v_mfma_f32_16x16x32_bf16 v[12:15], v[152:155], v[208:211], v[12:15]
	v_mfma_f32_16x16x32_bf16 v[4:7], v[160:163], v[208:211], v[4:7]
	v_mfma_f32_16x16x32_bf16 v[60:63], v[156:159], v[188:191], v[60:63]
	v_mfma_f32_16x16x32_bf16 v[52:55], v[164:167], v[188:191], v[52:55]
	v_mfma_f32_16x16x32_bf16 v[44:47], v[156:159], v[196:199], v[44:47]
	v_mfma_f32_16x16x32_bf16 v[36:39], v[164:167], v[196:199], v[36:39]
	v_mfma_f32_16x16x32_bf16 v[28:31], v[156:159], v[204:207], v[28:31]
	v_mfma_f32_16x16x32_bf16 v[20:23], v[164:167], v[204:207], v[20:23]
	v_mfma_f32_16x16x32_bf16 v[12:15], v[156:159], v[212:215], v[12:15]
	v_mfma_f32_16x16x32_bf16 v[4:7], v[164:167], v[212:215], v[4:7]
	v_mfma_f32_16x16x32_bf16 v[56:59], v[168:171], v[184:187], v[56:59]
	v_mfma_f32_16x16x32_bf16 v[48:51], v[176:179], v[184:187], v[48:51]
	v_mfma_f32_16x16x32_bf16 v[40:43], v[168:171], v[192:195], v[40:43]
	v_mfma_f32_16x16x32_bf16 v[32:35], v[176:179], v[192:195], v[32:35]
	v_mfma_f32_16x16x32_bf16 v[24:27], v[168:171], v[200:203], v[24:27]
	v_mfma_f32_16x16x32_bf16 v[16:19], v[176:179], v[200:203], v[16:19]
	v_mfma_f32_16x16x32_bf16 v[8:11], v[168:171], v[208:211], v[8:11]
	v_mfma_f32_16x16x32_bf16 v[0:3], v[176:179], v[208:211], v[0:3]
	v_mfma_f32_16x16x32_bf16 v[56:59], v[172:175], v[188:191], v[56:59]
	v_mfma_f32_16x16x32_bf16 v[48:51], v[180:183], v[188:191], v[48:51]
	v_mfma_f32_16x16x32_bf16 v[40:43], v[172:175], v[196:199], v[40:43]
	v_mfma_f32_16x16x32_bf16 v[32:35], v[180:183], v[196:199], v[32:35]
	v_mfma_f32_16x16x32_bf16 v[24:27], v[172:175], v[204:207], v[24:27]
	v_mfma_f32_16x16x32_bf16 v[16:19], v[180:183], v[204:207], v[16:19]
	v_mfma_f32_16x16x32_bf16 v[8:11], v[172:175], v[212:215], v[8:11]
	v_mfma_f32_16x16x32_bf16 v[0:3], v[180:183], v[212:215], v[0:3]
	s_barrier
	s_add_i32 s61, 0, 0x18000
	s_add_i32 s62, 0, 0x1c000
	v_add_u32_e32 v164, s61, v148
	v_add_u32_e32 v180, s62, v148
	ds_read_b128 v[152:155], v164
	ds_read_b128 v[156:159], v164 offset:1024
	ds_read_b128 v[160:163], v164 offset:2048
	ds_read_b128 v[164:167], v164 offset:3072
	ds_read_b128 v[168:171], v180
	ds_read_b128 v[172:175], v180 offset:1024
	ds_read_b128 v[176:179], v180 offset:2048
	ds_read_b128 v[180:183], v180 offset:3072
	s_add_u32 s42, s42, 0x40000
	s_addc_u32 s43, s43, 0
	s_mov_b32 m0, s33
	v_lshl_add_u64 v[222:223], s[42:43], 0, v[134:135]
	ds_read_b128 v[184:187], v151 offset:32768
	ds_read_b128 v[188:191], v151 offset:33792
	ds_read_b128 v[192:195], v151 offset:34816
	ds_read_b128 v[196:199], v151 offset:35840
	ds_read_b128 v[200:203], v151 offset:36864
	ds_read_b128 v[204:207], v151 offset:37888
	ds_read_b128 v[208:211], v151 offset:38912
	ds_read_b128 v[212:215], v151 offset:39936
	global_load_lds_dwordx4 v[222:223], off
	v_lshl_add_u64 v[222:223], s[42:43], 0, v[130:131]
	s_mov_b32 m0, s44
	s_nop 0
	global_load_lds_dwordx4 v[222:223], off
	s_waitcnt vmcnt(8)
	s_waitcnt lgkmcnt(0)
	s_barrier
	s_waitcnt lgkmcnt(0)
	v_mfma_f32_16x16x32_bf16 v[120:123], v[152:155], v[184:187], v[120:123]
	v_mfma_f32_16x16x32_bf16 v[116:119], v[160:163], v[184:187], v[116:119]
	v_mfma_f32_16x16x32_bf16 v[108:111], v[152:155], v[192:195], v[108:111]
	v_mfma_f32_16x16x32_bf16 v[100:103], v[160:163], v[192:195], v[100:103]
	v_mfma_f32_16x16x32_bf16 v[92:95], v[152:155], v[200:203], v[92:95]
	v_mfma_f32_16x16x32_bf16 v[84:87], v[160:163], v[200:203], v[84:87]
	v_mfma_f32_16x16x32_bf16 v[76:79], v[152:155], v[208:211], v[76:79]
	v_mfma_f32_16x16x32_bf16 v[68:71], v[160:163], v[208:211], v[68:71]
	v_mfma_f32_16x16x32_bf16 v[120:123], v[156:159], v[188:191], v[120:123]
	v_mfma_f32_16x16x32_bf16 v[116:119], v[164:167], v[188:191], v[116:119]
	v_mfma_f32_16x16x32_bf16 v[108:111], v[156:159], v[196:199], v[108:111]
	v_mfma_f32_16x16x32_bf16 v[100:103], v[164:167], v[196:199], v[100:103]
	v_mfma_f32_16x16x32_bf16 v[92:95], v[156:159], v[204:207], v[92:95]
	v_mfma_f32_16x16x32_bf16 v[84:87], v[164:167], v[204:207], v[84:87]
	v_mfma_f32_16x16x32_bf16 v[76:79], v[156:159], v[212:215], v[76:79]
	v_mfma_f32_16x16x32_bf16 v[68:71], v[164:167], v[212:215], v[68:71]
	v_mfma_f32_16x16x32_bf16 v[124:127], v[168:171], v[184:187], v[124:127]
	v_mfma_f32_16x16x32_bf16 v[112:115], v[176:179], v[184:187], v[112:115]
	v_mfma_f32_16x16x32_bf16 v[104:107], v[168:171], v[192:195], v[104:107]
	v_mfma_f32_16x16x32_bf16 v[96:99], v[176:179], v[192:195], v[96:99]
	v_mfma_f32_16x16x32_bf16 v[88:91], v[168:171], v[200:203], v[88:91]
	v_mfma_f32_16x16x32_bf16 v[80:83], v[176:179], v[200:203], v[80:83]
	v_mfma_f32_16x16x32_bf16 v[72:75], v[168:171], v[208:211], v[72:75]
	v_mfma_f32_16x16x32_bf16 v[64:67], v[176:179], v[208:211], v[64:67]
	v_mfma_f32_16x16x32_bf16 v[124:127], v[172:175], v[188:191], v[124:127]
	v_mfma_f32_16x16x32_bf16 v[112:115], v[180:183], v[188:191], v[112:115]
	v_mfma_f32_16x16x32_bf16 v[104:107], v[172:175], v[196:199], v[104:107]
	v_mfma_f32_16x16x32_bf16 v[96:99], v[180:183], v[196:199], v[96:99]
	v_mfma_f32_16x16x32_bf16 v[88:91], v[172:175], v[204:207], v[88:91]
	v_mfma_f32_16x16x32_bf16 v[80:83], v[180:183], v[204:207], v[80:83]
	v_mfma_f32_16x16x32_bf16 v[72:75], v[172:175], v[212:215], v[72:75]
	v_mfma_f32_16x16x32_bf16 v[64:67], v[180:183], v[212:215], v[64:67]
	s_barrier
; #define PG8_STAGE(bufoff, gbase, voff) do { _Pragma("unroll") for (int _i = 0; _i < 2; ++_i) \
;         __builtin_amdgcn_global_load_lds((const unsigned*)((const char*)(gbase) + (voff)[_i]), (PG8_LAS unsigned*)(lds + (bufoff) + ldsw + _i * 8192), 16, 0, 0); } while (0)
; #define PG8_LDA(dst, b, h) do { _Pragma("unroll") for (int m = 0; m < 4; ++m) _Pragma("unroll") for (int k = 0; k < 2; ++k) dst[m][k] = *(const PG8_LAS bf16x8*)(lds + PG8_SA(b, h) + aoff + m * 2048 + k * 1024); } while (0)
; #define PG8_MMA(ai, bj, At, Bt) do { __builtin_amdgcn_s_setprio(1); _Pragma("unroll") for (int m = 0; m < 4; ++m) _Pragma("unroll") for (int n = 0; n < 2; ++n) _Pragma("unroll") for (int k = 0; k < 2; ++k) \
;         acc[ai][bj][m][n] = __builtin_amdgcn_mfma_f32_16x16x32_bf16(Bt[n][k], At[m][k], acc[ai][bj][m][n], 0, 0, 0); __builtin_amdgcn_s_setprio(0); } while (0)
; #define PG8_WAIT_V(n) asm volatile("s_waitcnt vmcnt(" #n ")" ::: "memory")
; #define PG8_WAIT_L(n) asm volatile("s_waitcnt lgkmcnt(" #n ")" ::: "memory")
; #define PG8_BAR __builtin_amdgcn_s_barrier()
; #define PG8_SCHED __builtin_amdgcn_sched_barrier(0)
; template <class Epi, class Sched, bool ALIGN_EPI = false, bool SP2 = false>
; __device__ __forceinline__ void gemm_phase(PG8_LAS unsigned char* lds, const Gemm g, const Sched& S, const Epi& E) {
;     ...
;         for (int t = 0; t < nt; t += 2) {
;             const bool last = (t == nt - 2);
;             const char* a1 = cA + (long)(t + 1) * kstepA;
;             const char* a2 = last ? nA : cA + (long)(t + 2) * kstepA; const char* b2 = last ? nB : cB + (long)(t + 2) * kstep;
;             const char* a3 = a2 + kstepA; const char* b3 = b2 + kstep;
;             if (last && has_next) S.a_ready(nxt);
;     ...
;             PG8_LDA(At, 1, 1); PG8_STAGE(PG8_SB(1, 0), b3, voffB); PG8_STAGE(PG8_SB(1, 1), b3 + hstepB, voffB); PG8_STAGE(PG8_SA(1, 0), a3, voffA);
;             PG8_WAIT_V(8); PG8_WAIT_L(0); PG8_BAR; PG8_MMA(1, 0, At, B0); PG8_MMA(1, 1, At, B1); PG8_BAR; PG8_SCHED;
	s_add_i32 s42, s61, s17
	v_lshl_add_u64 v[144:145], v[144:145], 0, s[10:11]
	s_mov_b32 m0, s42
	ds_read_b128 v[184:187], v151 offset:49152
	ds_read_b128 v[188:191], v151 offset:50176
	ds_read_b128 v[192:195], v151 offset:51200
	ds_read_b128 v[196:199], v151 offset:52224
	ds_read_b128 v[200:203], v151 offset:53248
	ds_read_b128 v[204:207], v151 offset:54272
	ds_read_b128 v[208:211], v151 offset:55296
	ds_read_b128 v[212:215], v151 offset:56320
	global_load_lds_dwordx4 v[144:145], off
	s_add_i32 m0, s42, 0x2000
	s_add_u32 s36, s36, 0x40080
	v_lshl_add_u64 v[144:145], v[216:217], 0, s[10:11]
	s_addc_u32 s37, s37, 0
	s_add_i32 s42, s62, s17
	global_load_lds_dwordx4 v[144:145], off
	v_lshl_add_u64 v[144:145], s[36:37], 0, v[132:133]
	s_mov_b32 m0, s42
	s_nop 0
	global_load_lds_dwordx4 v[144:145], off
	v_lshl_add_u64 v[144:145], s[36:37], 0, v[128:129]
	s_add_i32 m0, s42, 0x2000
	s_nop 0
	global_load_lds_dwordx4 v[144:145], off
	v_lshl_add_u64 v[144:145], v[218:219], 0, s[10:11]
	s_mov_b32 m0, s48
	s_nop 0
	global_load_lds_dwordx4 v[144:145], off
	v_lshl_add_u64 v[144:145], v[220:221], 0, s[10:11]
	s_mov_b32 m0, s49
	s_nop 0
	global_load_lds_dwordx4 v[144:145], off
	s_waitcnt vmcnt(8)
	s_waitcnt lgkmcnt(0)
	s_barrier
	s_waitcnt lgkmcnt(0)
	v_mfma_f32_16x16x32_bf16 v[60:63], v[152:155], v[184:187], v[60:63]
	v_mfma_f32_16x16x32_bf16 v[52:55], v[160:163], v[184:187], v[52:55]
	v_mfma_f32_16x16x32_bf16 v[44:47], v[152:155], v[192:195], v[44:47]
	v_mfma_f32_16x16x32_bf16 v[36:39], v[160:163], v[192:195], v[36:39]
	v_mfma_f32_16x16x32_bf16 v[28:31], v[152:155], v[200:203], v[28:31]
	v_mfma_f32_16x16x32_bf16 v[20:23], v[160:163], v[200:203], v[20:23]
	v_mfma_f32_16x16x32_bf16 v[12:15], v[152:155], v[208:211], v[12:15]
	v_mfma_f32_16x16x32_bf16 v[4:7], v[160:163], v[208:211], v[4:7]
	v_mfma_f32_16x16x32_bf16 v[60:63], v[156:159], v[188:191], v[60:63]
	v_mfma_f32_16x16x32_bf16 v[52:55], v[164:167], v[188:191], v[52:55]
	v_mfma_f32_16x16x32_bf16 v[44:47], v[156:159], v[196:199], v[44:47]
	v_mfma_f32_16x16x32_bf16 v[36:39], v[164:167], v[196:199], v[36:39]
	v_mfma_f32_16x16x32_bf16 v[28:31], v[156:159], v[204:207], v[28:31]
	v_mfma_f32_16x16x32_bf16 v[20:23], v[164:167], v[204:207], v[20:23]
	v_mfma_f32_16x16x32_bf16 v[12:15], v[156:159], v[212:215], v[12:15]
	v_mfma_f32_16x16x32_bf16 v[4:7], v[164:167], v[212:215], v[4:7]
	v_mfma_f32_16x16x32_bf16 v[56:59], v[168:171], v[184:187], v[56:59]
	v_mfma_f32_16x16x32_bf16 v[48:51], v[176:179], v[184:187], v[48:51]
	v_mfma_f32_16x16x32_bf16 v[40:43], v[168:171], v[192:195], v[40:43]
	v_mfma_f32_16x16x32_bf16 v[32:35], v[176:179], v[192:195], v[32:35]
	v_mfma_f32_16x16x32_bf16 v[24:27], v[168:171], v[200:203], v[24:27]
	v_mfma_f32_16x16x32_bf16 v[16:19], v[176:179], v[200:203], v[16:19]
	v_mfma_f32_16x16x32_bf16 v[8:11], v[168:171], v[208:211], v[8:11]
	v_mfma_f32_16x16x32_bf16 v[0:3], v[176:179], v[208:211], v[0:3]
	v_mfma_f32_16x16x32_bf16 v[56:59], v[172:175], v[188:191], v[56:59]
	v_mfma_f32_16x16x32_bf16 v[48:51], v[180:183], v[188:191], v[48:51]
	v_mfma_f32_16x16x32_bf16 v[40:43], v[172:175], v[196:199], v[40:43]
	v_mfma_f32_16x16x32_bf16 v[32:35], v[180:183], v[196:199], v[32:35]
	v_mfma_f32_16x16x32_bf16 v[24:27], v[172:175], v[204:207], v[24:27]
	v_mfma_f32_16x16x32_bf16 v[16:19], v[180:183], v[204:207], v[16:19]
	v_mfma_f32_16x16x32_bf16 v[8:11], v[172:175], v[212:215], v[8:11]
	v_mfma_f32_16x16x32_bf16 v[0:3], v[180:183], v[212:215], v[0:3]
	s_barrier
	s_add_u32 s34, s34, 0x100
	s_addc_u32 s35, s35, 0
	s_add_u32 s58, s58, 0x100
	s_addc_u32 s59, s59, 0
	s_cmp_ge_i32 s60, s46
	s_mov_b32 s36, s60
	s_cbranch_scc0 .LBB0_1523

; #define PG8_STAGE(bufoff, gbase, voff) do { _Pragma("unroll") for (int _i = 0; _i < 2; ++_i) \
;         __builtin_amdgcn_global_load_lds((const unsigned*)((const char*)(gbase) + (voff)[_i]), (PG8_LAS unsigned*)(lds + (bufoff) + ldsw + _i * 8192), 16, 0, 0); } while (0)
; #define PG8_LDA(dst, b, h) do { _Pragma("unroll") for (int m = 0; m < 4; ++m) _Pragma("unroll") for (int k = 0; k < 2; ++k) dst[m][k] = *(const PG8_LAS bf16x8*)(lds + PG8_SA(b, h) + aoff + m * 2048 + k * 1024); } while (0)
; #define PG8_LDB(dst, b, h) do { _Pragma("unroll") for (int n = 0; n < 2; ++n) _Pragma("unroll") for (int k = 0; k < 2; ++k) dst[n][k] = *(const PG8_LAS bf16x8*)(lds + PG8_SB(b, h) + boff + n * 2048 + k * 1024); } while (0)
; #define PG8_MMA(ai, bj, At, Bt) do { __builtin_amdgcn_s_setprio(1); _Pragma("unroll") for (int m = 0; m < 4; ++m) _Pragma("unroll") for (int n = 0; n < 2; ++n) _Pragma("unroll") for (int k = 0; k < 2; ++k) \
;         acc[ai][bj][m][n] = __builtin_amdgcn_mfma_f32_16x16x32_bf16(Bt[n][k], At[m][k], acc[ai][bj][m][n], 0, 0, 0); __builtin_amdgcn_s_setprio(0); } while (0)
; #define PG8_WAIT_V(n) asm volatile("s_waitcnt vmcnt(" #n ")" ::: "memory")
; #define PG8_WAIT_L(n) asm volatile("s_waitcnt lgkmcnt(" #n ")" ::: "memory")
; #define PG8_BAR __builtin_amdgcn_s_barrier()
; #define PG8_SCHED __builtin_amdgcn_sched_barrier(0)
; template <class Epi, class Sched, bool ALIGN_EPI = false, bool SP2 = false>
; __device__ __forceinline__ void gemm_phase(PG8_LAS unsigned char* lds, const Gemm g, const Sched& S, const Epi& E) {
;     ...
;             PG8_LDB(B0, 0, 0); PG8_LDB(B1, 0, 1); PG8_SCHED; PG8_LDA(At, 0, 0); PG8_STAGE(PG8_SA(1, 1), a1 + hstepA, voffA);
;             PG8_WAIT_V(8); PG8_WAIT_L(0); PG8_BAR; PG8_MMA(0, 0, At, B0); PG8_MMA(0, 1, At, B1); PG8_BAR; PG8_SCHED;
;             PG8_LDA(At, 0, 1); PG8_STAGE(PG8_SB(0, 0), b2, voffB); PG8_STAGE(PG8_SB(0, 1), b2 + hstepB, voffB); PG8_STAGE(PG8_SA(0, 0), a2, voffA);
;             PG8_WAIT_V(8); PG8_WAIT_L(0); PG8_BAR; PG8_MMA(1, 0, At, B0); PG8_MMA(1, 1, At, B1); PG8_BAR; PG8_SCHED;
.LBB0_1602:
	ds_read_b128 v[128:131], v185
	ds_read_b128 v[132:135], v185 offset:1024
	ds_read_b128 v[158:161], v185 offset:2048
	ds_read_b128 v[162:165], v185 offset:3072
	ds_read_b128 v[166:169], v186
	ds_read_b128 v[170:173], v186 offset:1024
	ds_read_b128 v[174:177], v186 offset:2048
	ds_read_b128 v[178:181], v186 offset:3072
	s_add_i32 s64, s44, 2
	s_add_u32 s45, s42, 0x3fc000
	s_addc_u32 s46, s43, 0
	s_cmp_eq_u32 s57, s44
	s_cselect_b32 s48, s8, s45
	s_cselect_b32 s49, s5, s46
	s_cselect_b32 s46, s29, s31
	s_cselect_b32 s47, s9, s41
	s_add_u32 s44, s48, 0x400000
	s_addc_u32 s45, s49, 0
	v_lshl_add_u64 v[182:183], s[42:43], 0, v[146:147]
	s_add_i32 m0, s20, 0xc000
	ds_read_b128 v[190:193], v187
	ds_read_b128 v[194:197], v187 offset:1024
	ds_read_b128 v[198:201], v187 offset:2048
	ds_read_b128 v[202:205], v187 offset:3072
	ds_read_b128 v[206:209], v187 offset:4096
	ds_read_b128 v[210:213], v187 offset:5120
	ds_read_b128 v[214:217], v187 offset:6144
	ds_read_b128 v[218:221], v187 offset:7168
	global_load_lds_dwordx4 v[182:183], off
	v_lshl_add_u64 v[182:183], s[42:43], 0, v[148:149]
	s_add_i32 m0, s20, 0xe000
	s_nop 0
	global_load_lds_dwordx4 v[182:183], off
	s_waitcnt vmcnt(8)
	s_waitcnt lgkmcnt(0)
	s_barrier
	s_waitcnt lgkmcnt(0)
	v_mfma_f32_16x16x32_bf16 v[124:127], v[128:131], v[190:193], v[124:127]
	v_mfma_f32_16x16x32_bf16 v[96:99], v[158:161], v[190:193], v[96:99]
	v_mfma_f32_16x16x32_bf16 v[120:123], v[128:131], v[198:201], v[120:123]
	v_mfma_f32_16x16x32_bf16 v[100:103], v[158:161], v[198:201], v[100:103]
	v_mfma_f32_16x16x32_bf16 v[116:119], v[128:131], v[206:209], v[116:119]
	v_mfma_f32_16x16x32_bf16 v[112:115], v[158:161], v[206:209], v[112:115]
	v_mfma_f32_16x16x32_bf16 v[108:111], v[128:131], v[214:217], v[108:111]
	v_mfma_f32_16x16x32_bf16 v[104:107], v[158:161], v[214:217], v[104:107]
	v_mfma_f32_16x16x32_bf16 v[124:127], v[132:135], v[194:197], v[124:127]
	v_mfma_f32_16x16x32_bf16 v[96:99], v[162:165], v[194:197], v[96:99]
	v_mfma_f32_16x16x32_bf16 v[120:123], v[132:135], v[202:205], v[120:123]
	v_mfma_f32_16x16x32_bf16 v[100:103], v[162:165], v[202:205], v[100:103]
	v_mfma_f32_16x16x32_bf16 v[116:119], v[132:135], v[210:213], v[116:119]
	v_mfma_f32_16x16x32_bf16 v[112:115], v[162:165], v[210:213], v[112:115]
	v_mfma_f32_16x16x32_bf16 v[108:111], v[132:135], v[218:221], v[108:111]
	v_mfma_f32_16x16x32_bf16 v[104:107], v[162:165], v[218:221], v[104:107]
	v_mfma_f32_16x16x32_bf16 v[60:63], v[166:169], v[190:193], v[60:63]
	v_mfma_f32_16x16x32_bf16 v[56:59], v[174:177], v[190:193], v[56:59]
	v_mfma_f32_16x16x32_bf16 v[52:55], v[166:169], v[198:201], v[52:55]
	v_mfma_f32_16x16x32_bf16 v[48:51], v[174:177], v[198:201], v[48:51]
	v_mfma_f32_16x16x32_bf16 v[44:47], v[166:169], v[206:209], v[44:47]
	v_mfma_f32_16x16x32_bf16 v[40:43], v[174:177], v[206:209], v[40:43]
	v_mfma_f32_16x16x32_bf16 v[36:39], v[166:169], v[214:217], v[36:39]
	v_mfma_f32_16x16x32_bf16 v[32:35], v[174:177], v[214:217], v[32:35]
	v_mfma_f32_16x16x32_bf16 v[60:63], v[170:173], v[194:197], v[60:63]
	v_mfma_f32_16x16x32_bf16 v[56:59], v[178:181], v[194:197], v[56:59]
	v_mfma_f32_16x16x32_bf16 v[52:55], v[170:173], v[202:205], v[52:55]
	v_mfma_f32_16x16x32_bf16 v[48:51], v[178:181], v[202:205], v[48:51]
	v_mfma_f32_16x16x32_bf16 v[44:47], v[170:173], v[210:213], v[44:47]
	v_mfma_f32_16x16x32_bf16 v[40:43], v[178:181], v[210:213], v[40:43]
	v_mfma_f32_16x16x32_bf16 v[36:39], v[170:173], v[218:221], v[36:39]
	v_mfma_f32_16x16x32_bf16 v[32:35], v[178:181], v[218:221], v[32:35]
	s_barrier
	s_add_i32 s65, s62, s19
	v_lshl_add_u64 v[182:183], s[46:47], 0, v[138:139]
	s_mov_b32 m0, s65
	ds_read_b128 v[190:193], v187 offset:16384
	ds_read_b128 v[194:197], v187 offset:17408
	ds_read_b128 v[198:201], v187 offset:18432
	ds_read_b128 v[202:205], v187 offset:19456
	ds_read_b128 v[206:209], v187 offset:20480
	ds_read_b128 v[210:213], v187 offset:21504
	ds_read_b128 v[214:217], v187 offset:22528
	ds_read_b128 v[218:221], v187 offset:23552
	global_load_lds_dwordx4 v[182:183], off
	s_add_i32 m0, s65, 0x2000
	s_add_u32 s66, s46, 0x4000
	v_lshl_add_u64 v[182:183], s[46:47], 0, v[142:143]
	s_addc_u32 s67, s47, 0
	s_add_i32 s65, s63, s19
	global_load_lds_dwordx4 v[182:183], off
	v_lshl_add_u64 v[182:183], s[66:67], 0, v[138:139]
	s_mov_b32 m0, s65
	s_nop 0
	global_load_lds_dwordx4 v[182:183], off
	v_lshl_add_u64 v[182:183], s[66:67], 0, v[142:143]
	s_add_i32 m0, s65, 0x2000
	s_nop 0
	global_load_lds_dwordx4 v[182:183], off
	v_lshl_add_u64 v[182:183], s[48:49], 0, v[136:137]
	s_mov_b32 m0, s20
	s_nop 0
	global_load_lds_dwordx4 v[182:183], off
	v_lshl_add_u64 v[182:183], s[48:49], 0, v[140:141]
	s_mov_b32 m0, s21
	s_nop 0
	global_load_lds_dwordx4 v[182:183], off
	s_waitcnt vmcnt(8)
	s_waitcnt lgkmcnt(0)
	s_barrier
; #define PG8_STAGE(bufoff, gbase, voff) do { _Pragma("unroll") for (int _i = 0; _i < 2; ++_i) \
;         __builtin_amdgcn_global_load_lds((const unsigned*)((const char*)(gbase) + (voff)[_i]), (PG8_LAS unsigned*)(lds + (bufoff) + ldsw + _i * 8192), 16, 0, 0); } while (0)
; #define PG8_LDA(dst, b, h) do { _Pragma("unroll") for (int m = 0; m < 4; ++m) _Pragma("unroll") for (int k = 0; k < 2; ++k) dst[m][k] = *(const PG8_LAS bf16x8*)(lds + PG8_SA(b, h) + aoff + m * 2048 + k * 1024); } while (0)
; #define PG8_LDB(dst, b, h) do { _Pragma("unroll") for (int n = 0; n < 2; ++n) _Pragma("unroll") for (int k = 0; k < 2; ++k) dst[n][k] = *(const PG8_LAS bf16x8*)(lds + PG8_SB(b, h) + boff + n * 2048 + k * 1024); } while (0)
; #define PG8_MMA(ai, bj, At, Bt) do { __builtin_amdgcn_s_setprio(1); _Pragma("unroll") for (int m = 0; m < 4; ++m) _Pragma("unroll") for (int n = 0; n < 2; ++n) _Pragma("unroll") for (int k = 0; k < 2; ++k) \
;         acc[ai][bj][m][n] = __builtin_amdgcn_mfma_f32_16x16x32_bf16(Bt[n][k], At[m][k], acc[ai][bj][m][n], 0, 0, 0); __builtin_amdgcn_s_setprio(0); } while (0)
; #define PG8_WAIT_V(n) asm volatile("s_waitcnt vmcnt(" #n ")" ::: "memory")
; #define PG8_WAIT_L(n) asm volatile("s_waitcnt lgkmcnt(" #n ")" ::: "memory")
; #define PG8_BAR __builtin_amdgcn_s_barrier()
; #define PG8_SCHED __builtin_amdgcn_sched_barrier(0)
; template <class Epi, class Sched, bool ALIGN_EPI = false, bool SP2 = false>
; __device__ __forceinline__ void gemm_phase(PG8_LAS unsigned char* lds, const Gemm g, const Sched& S, const Epi& E) {
;     ...
;             PG8_WAIT_V(8); PG8_WAIT_L(0); PG8_BAR; PG8_MMA(1, 0, At, B0); PG8_MMA(1, 1, At, B1); PG8_BAR; PG8_SCHED;
;             PG8_LDB(B0, 1, 0); PG8_LDB(B1, 1, 1); PG8_SCHED; PG8_LDA(At, 1, 0); PG8_STAGE(PG8_SA(0, 1), a2 + hstepA, voffA);
;             PG8_WAIT_V(8); PG8_WAIT_L(0); PG8_BAR; PG8_MMA(0, 0, At, B0); PG8_MMA(0, 1, At, B1); PG8_BAR; PG8_SCHED;
	s_waitcnt lgkmcnt(0)
	v_mfma_f32_16x16x32_bf16 v[92:95], v[128:131], v[190:193], v[92:95]
	v_mfma_f32_16x16x32_bf16 v[88:91], v[158:161], v[190:193], v[88:91]
	v_mfma_f32_16x16x32_bf16 v[84:87], v[128:131], v[198:201], v[84:87]
	v_mfma_f32_16x16x32_bf16 v[80:83], v[158:161], v[198:201], v[80:83]
	v_mfma_f32_16x16x32_bf16 v[76:79], v[128:131], v[206:209], v[76:79]
	v_mfma_f32_16x16x32_bf16 v[72:75], v[158:161], v[206:209], v[72:75]
	v_mfma_f32_16x16x32_bf16 v[68:71], v[128:131], v[214:217], v[68:71]
	v_mfma_f32_16x16x32_bf16 v[64:67], v[158:161], v[214:217], v[64:67]
	v_mfma_f32_16x16x32_bf16 v[92:95], v[132:135], v[194:197], v[92:95]
	v_mfma_f32_16x16x32_bf16 v[88:91], v[162:165], v[194:197], v[88:91]
	v_mfma_f32_16x16x32_bf16 v[84:87], v[132:135], v[202:205], v[84:87]
	v_mfma_f32_16x16x32_bf16 v[80:83], v[162:165], v[202:205], v[80:83]
	v_mfma_f32_16x16x32_bf16 v[76:79], v[132:135], v[210:213], v[76:79]
	v_mfma_f32_16x16x32_bf16 v[72:75], v[162:165], v[210:213], v[72:75]
	v_mfma_f32_16x16x32_bf16 v[68:71], v[132:135], v[218:221], v[68:71]
	v_mfma_f32_16x16x32_bf16 v[64:67], v[162:165], v[218:221], v[64:67]
	v_mfma_f32_16x16x32_bf16 v[28:31], v[166:169], v[190:193], v[28:31]
	v_mfma_f32_16x16x32_bf16 v[24:27], v[174:177], v[190:193], v[24:27]
	v_mfma_f32_16x16x32_bf16 v[20:23], v[166:169], v[198:201], v[20:23]
	v_mfma_f32_16x16x32_bf16 v[16:19], v[174:177], v[198:201], v[16:19]
	v_mfma_f32_16x16x32_bf16 v[12:15], v[166:169], v[206:209], v[12:15]
	v_mfma_f32_16x16x32_bf16 v[8:11], v[174:177], v[206:209], v[8:11]
	v_mfma_f32_16x16x32_bf16 v[4:7], v[166:169], v[214:217], v[4:7]
	v_mfma_f32_16x16x32_bf16 v[0:3], v[174:177], v[214:217], v[0:3]
	v_mfma_f32_16x16x32_bf16 v[28:31], v[170:173], v[194:197], v[28:31]
	v_mfma_f32_16x16x32_bf16 v[24:27], v[178:181], v[194:197], v[24:27]
	v_mfma_f32_16x16x32_bf16 v[20:23], v[170:173], v[202:205], v[20:23]
	v_mfma_f32_16x16x32_bf16 v[16:19], v[178:181], v[202:205], v[16:19]
	v_mfma_f32_16x16x32_bf16 v[12:15], v[170:173], v[210:213], v[12:15]
	v_mfma_f32_16x16x32_bf16 v[8:11], v[178:181], v[210:213], v[8:11]
	v_mfma_f32_16x16x32_bf16 v[4:7], v[170:173], v[218:221], v[4:7]
	v_mfma_f32_16x16x32_bf16 v[0:3], v[178:181], v[218:221], v[0:3]
	s_barrier
	s_add_i32 s65, 0, 0x18000
	v_add_u32_e32 v145, s65, v184
	s_add_i32 s66, 0, 0x1c000
	ds_read_b128 v[128:131], v145
	ds_read_b128 v[132:135], v145 offset:1024
	ds_read_b128 v[158:161], v145 offset:2048
	ds_read_b128 v[162:165], v145 offset:3072
	v_add_u32_e32 v145, s66, v184
	ds_read_b128 v[166:169], v145
	ds_read_b128 v[170:173], v145 offset:1024
	ds_read_b128 v[174:177], v145 offset:2048
	ds_read_b128 v[178:181], v145 offset:3072
	s_add_u32 s48, s48, 0x4000
	s_addc_u32 s49, s49, 0
	s_mov_b32 m0, s33
	v_lshl_add_u64 v[182:183], s[48:49], 0, v[136:137]
	ds_read_b128 v[190:193], v187 offset:32768
	ds_read_b128 v[194:197], v187 offset:33792
	ds_read_b128 v[198:201], v187 offset:34816
	ds_read_b128 v[202:205], v187 offset:35840
	ds_read_b128 v[206:209], v187 offset:36864
	ds_read_b128 v[210:213], v187 offset:37888
	ds_read_b128 v[214:217], v187 offset:38912
	ds_read_b128 v[218:221], v187 offset:39936
	global_load_lds_dwordx4 v[182:183], off
	v_lshl_add_u64 v[182:183], s[48:49], 0, v[140:141]
	s_mov_b32 m0, s50
	s_nop 0
	global_load_lds_dwordx4 v[182:183], off
	s_waitcnt vmcnt(8)
	s_waitcnt lgkmcnt(0)
	s_barrier
	s_waitcnt lgkmcnt(0)
	v_mfma_f32_16x16x32_bf16 v[124:127], v[128:131], v[190:193], v[124:127]
	v_mfma_f32_16x16x32_bf16 v[96:99], v[158:161], v[190:193], v[96:99]
	v_mfma_f32_16x16x32_bf16 v[120:123], v[128:131], v[198:201], v[120:123]
	v_mfma_f32_16x16x32_bf16 v[100:103], v[158:161], v[198:201], v[100:103]
	v_mfma_f32_16x16x32_bf16 v[116:119], v[128:131], v[206:209], v[116:119]
	v_mfma_f32_16x16x32_bf16 v[112:115], v[158:161], v[206:209], v[112:115]
	v_mfma_f32_16x16x32_bf16 v[108:111], v[128:131], v[214:217], v[108:111]
	v_mfma_f32_16x16x32_bf16 v[104:107], v[158:161], v[214:217], v[104:107]
	v_mfma_f32_16x16x32_bf16 v[124:127], v[132:135], v[194:197], v[124:127]
	v_mfma_f32_16x16x32_bf16 v[96:99], v[162:165], v[194:197], v[96:99]
	v_mfma_f32_16x16x32_bf16 v[120:123], v[132:135], v[202:205], v[120:123]
	v_mfma_f32_16x16x32_bf16 v[100:103], v[162:165], v[202:205], v[100:103]
	v_mfma_f32_16x16x32_bf16 v[116:119], v[132:135], v[210:213], v[116:119]
	v_mfma_f32_16x16x32_bf16 v[112:115], v[162:165], v[210:213], v[112:115]
	v_mfma_f32_16x16x32_bf16 v[108:111], v[132:135], v[218:221], v[108:111]
	v_mfma_f32_16x16x32_bf16 v[104:107], v[162:165], v[218:221], v[104:107]
	v_mfma_f32_16x16x32_bf16 v[60:63], v[166:169], v[190:193], v[60:63]
	v_mfma_f32_16x16x32_bf16 v[56:59], v[174:177], v[190:193], v[56:59]
	v_mfma_f32_16x16x32_bf16 v[52:55], v[166:169], v[198:201], v[52:55]
	v_mfma_f32_16x16x32_bf16 v[48:51], v[174:177], v[198:201], v[48:51]
	v_mfma_f32_16x16x32_bf16 v[44:47], v[166:169], v[206:209], v[44:47]
	v_mfma_f32_16x16x32_bf16 v[40:43], v[174:177], v[206:209], v[40:43]
	v_mfma_f32_16x16x32_bf16 v[36:39], v[166:169], v[214:217], v[36:39]
	v_mfma_f32_16x16x32_bf16 v[32:35], v[174:177], v[214:217], v[32:35]
	v_mfma_f32_16x16x32_bf16 v[60:63], v[170:173], v[194:197], v[60:63]
	v_mfma_f32_16x16x32_bf16 v[56:59], v[178:181], v[194:197], v[56:59]
	v_mfma_f32_16x16x32_bf16 v[52:55], v[170:173], v[202:205], v[52:55]
	v_mfma_f32_16x16x32_bf16 v[48:51], v[178:181], v[202:205], v[48:51]
	v_mfma_f32_16x16x32_bf16 v[44:47], v[170:173], v[210:213], v[44:47]
	v_mfma_f32_16x16x32_bf16 v[40:43], v[178:181], v[210:213], v[40:43]
	v_mfma_f32_16x16x32_bf16 v[36:39], v[170:173], v[218:221], v[36:39]
	v_mfma_f32_16x16x32_bf16 v[32:35], v[178:181], v[218:221], v[32:35]
	s_barrier
; #define PG8_STAGE(bufoff, gbase, voff) do { _Pragma("unroll") for (int _i = 0; _i < 2; ++_i) \
;         __builtin_amdgcn_global_load_lds((const unsigned*)((const char*)(gbase) + (voff)[_i]), (PG8_LAS unsigned*)(lds + (bufoff) + ldsw + _i * 8192), 16, 0, 0); } while (0)
; #define PG8_LDA(dst, b, h) do { _Pragma("unroll") for (int m = 0; m < 4; ++m) _Pragma("unroll") for (int k = 0; k < 2; ++k) dst[m][k] = *(const PG8_LAS bf16x8*)(lds + PG8_SA(b, h) + aoff + m * 2048 + k * 1024); } while (0)
; #define PG8_MMA(ai, bj, At, Bt) do { __builtin_amdgcn_s_setprio(1); _Pragma("unroll") for (int m = 0; m < 4; ++m) _Pragma("unroll") for (int n = 0; n < 2; ++n) _Pragma("unroll") for (int k = 0; k < 2; ++k) \
;         acc[ai][bj][m][n] = __builtin_amdgcn_mfma_f32_16x16x32_bf16(Bt[n][k], At[m][k], acc[ai][bj][m][n], 0, 0, 0); __builtin_amdgcn_s_setprio(0); } while (0)
; #define PG8_WAIT_V(n) asm volatile("s_waitcnt vmcnt(" #n ")" ::: "memory")
; #define PG8_WAIT_L(n) asm volatile("s_waitcnt lgkmcnt(" #n ")" ::: "memory")
; #define PG8_BAR __builtin_amdgcn_s_barrier()
; #define PG8_SCHED __builtin_amdgcn_sched_barrier(0)
; template <class Epi, class Sched, bool ALIGN_EPI = false, bool SP2 = false>
; __device__ __forceinline__ void gemm_phase(PG8_LAS unsigned char* lds, const Gemm g, const Sched& S, const Epi& E) {
;     ...
;         for (int t = 0; t < nt; t += 2) {
;             const bool last = (t == nt - 2);
;             const char* a1 = cA + (long)(t + 1) * kstepA;
;             const char* a2 = last ? nA : cA + (long)(t + 2) * kstepA; const char* b2 = last ? nB : cB + (long)(t + 2) * kstep;
;             const char* a3 = a2 + kstepA; const char* b3 = b2 + kstep;
;             if (last && has_next) S.a_ready(nxt);
;     ...
;             PG8_LDA(At, 1, 1); PG8_STAGE(PG8_SB(1, 0), b3, voffB); PG8_STAGE(PG8_SB(1, 1), b3 + hstepB, voffB); PG8_STAGE(PG8_SA(1, 0), a3, voffA);
;             PG8_WAIT_V(8); PG8_WAIT_L(0); PG8_BAR; PG8_MMA(1, 0, At, B0); PG8_MMA(1, 1, At, B1); PG8_BAR; PG8_SCHED;
	s_add_u32 s48, s46, 0x20000
	s_addc_u32 s49, s47, 0
	s_add_i32 s65, s65, s19
	v_lshl_add_u64 v[182:183], s[48:49], 0, v[138:139]
	s_mov_b32 m0, s65
	ds_read_b128 v[190:193], v187 offset:49152
	ds_read_b128 v[194:197], v187 offset:50176
	ds_read_b128 v[198:201], v187 offset:51200
	ds_read_b128 v[202:205], v187 offset:52224
	ds_read_b128 v[206:209], v187 offset:53248
	ds_read_b128 v[210:213], v187 offset:54272
	ds_read_b128 v[214:217], v187 offset:55296
	ds_read_b128 v[218:221], v187 offset:56320
	global_load_lds_dwordx4 v[182:183], off
	s_add_i32 m0, s65, 0x2000
	s_add_u32 s46, s46, 0x24000
	v_lshl_add_u64 v[182:183], s[48:49], 0, v[142:143]
	s_addc_u32 s47, s47, 0
	s_add_i32 s48, s66, s19
	global_load_lds_dwordx4 v[182:183], off
	v_lshl_add_u64 v[182:183], s[46:47], 0, v[138:139]
	s_mov_b32 m0, s48
	s_nop 0
	global_load_lds_dwordx4 v[182:183], off
	v_lshl_add_u64 v[182:183], s[46:47], 0, v[142:143]
	s_add_i32 m0, s48, 0x2000
	s_nop 0
	global_load_lds_dwordx4 v[182:183], off
	v_lshl_add_u64 v[182:183], s[44:45], 0, v[136:137]
	s_mov_b32 m0, s55
	s_nop 0
	global_load_lds_dwordx4 v[182:183], off
	v_lshl_add_u64 v[182:183], s[44:45], 0, v[140:141]
	s_mov_b32 m0, s56
	s_nop 0
	global_load_lds_dwordx4 v[182:183], off
	s_waitcnt vmcnt(8)
	s_waitcnt lgkmcnt(0)
	s_barrier
	s_waitcnt lgkmcnt(0)
	v_mfma_f32_16x16x32_bf16 v[92:95], v[128:131], v[190:193], v[92:95]
	v_mfma_f32_16x16x32_bf16 v[88:91], v[158:161], v[190:193], v[88:91]
	v_mfma_f32_16x16x32_bf16 v[84:87], v[128:131], v[198:201], v[84:87]
	v_mfma_f32_16x16x32_bf16 v[80:83], v[158:161], v[198:201], v[80:83]
	v_mfma_f32_16x16x32_bf16 v[76:79], v[128:131], v[206:209], v[76:79]
	v_mfma_f32_16x16x32_bf16 v[72:75], v[158:161], v[206:209], v[72:75]
	v_mfma_f32_16x16x32_bf16 v[68:71], v[128:131], v[214:217], v[68:71]
	v_mfma_f32_16x16x32_bf16 v[64:67], v[158:161], v[214:217], v[64:67]
	v_mfma_f32_16x16x32_bf16 v[92:95], v[132:135], v[194:197], v[92:95]
	v_mfma_f32_16x16x32_bf16 v[88:91], v[162:165], v[194:197], v[88:91]
	v_mfma_f32_16x16x32_bf16 v[84:87], v[132:135], v[202:205], v[84:87]
	v_mfma_f32_16x16x32_bf16 v[80:83], v[162:165], v[202:205], v[80:83]
	v_mfma_f32_16x16x32_bf16 v[76:79], v[132:135], v[210:213], v[76:79]
	v_mfma_f32_16x16x32_bf16 v[72:75], v[162:165], v[210:213], v[72:75]
	v_mfma_f32_16x16x32_bf16 v[68:71], v[132:135], v[218:221], v[68:71]
	v_mfma_f32_16x16x32_bf16 v[64:67], v[162:165], v[218:221], v[64:67]
	v_mfma_f32_16x16x32_bf16 v[28:31], v[166:169], v[190:193], v[28:31]
	v_mfma_f32_16x16x32_bf16 v[24:27], v[174:177], v[190:193], v[24:27]
	v_mfma_f32_16x16x32_bf16 v[20:23], v[166:169], v[198:201], v[20:23]
	v_mfma_f32_16x16x32_bf16 v[16:19], v[174:177], v[198:201], v[16:19]
	v_mfma_f32_16x16x32_bf16 v[12:15], v[166:169], v[206:209], v[12:15]
	v_mfma_f32_16x16x32_bf16 v[8:11], v[174:177], v[206:209], v[8:11]
	v_mfma_f32_16x16x32_bf16 v[4:7], v[166:169], v[214:217], v[4:7]
	v_mfma_f32_16x16x32_bf16 v[0:3], v[174:177], v[214:217], v[0:3]
	v_mfma_f32_16x16x32_bf16 v[28:31], v[170:173], v[194:197], v[28:31]
	v_mfma_f32_16x16x32_bf16 v[24:27], v[178:181], v[194:197], v[24:27]
	v_mfma_f32_16x16x32_bf16 v[20:23], v[170:173], v[202:205], v[20:23]
	v_mfma_f32_16x16x32_bf16 v[16:19], v[178:181], v[202:205], v[16:19]
	v_mfma_f32_16x16x32_bf16 v[12:15], v[170:173], v[210:213], v[12:15]
	v_mfma_f32_16x16x32_bf16 v[8:11], v[178:181], v[210:213], v[8:11]
	v_mfma_f32_16x16x32_bf16 v[4:7], v[170:173], v[218:221], v[4:7]
	v_mfma_f32_16x16x32_bf16 v[0:3], v[178:181], v[218:221], v[0:3]
	s_barrier
	s_add_u32 s31, s31, 0x40000
	s_addc_u32 s41, s41, 0
	s_add_u32 s42, s42, 0x800000
	s_addc_u32 s43, s43, 0
	s_cmp_ge_i32 s64, s52
	s_mov_b32 s44, s64
	s_cbranch_scc0 .LBB0_1602

; #define PG8_STAGE(bufoff, gbase, voff) do { _Pragma("unroll") for (int _i = 0; _i < 2; ++_i) \
;         __builtin_amdgcn_global_load_lds((const unsigned*)((const char*)(gbase) + (voff)[_i]), (PG8_LAS unsigned*)(lds + (bufoff) + ldsw + _i * 8192), 16, 0, 0); } while (0)
; #define PG8_LDA(dst, b, h) do { _Pragma("unroll") for (int m = 0; m < 4; ++m) _Pragma("unroll") for (int k = 0; k < 2; ++k) dst[m][k] = *(const PG8_LAS bf16x8*)(lds + PG8_SA(b, h) + aoff + m * 2048 + k * 1024); } while (0)
; #define PG8_LDB(dst, b, h) do { _Pragma("unroll") for (int n = 0; n < 2; ++n) _Pragma("unroll") for (int k = 0; k < 2; ++k) dst[n][k] = *(const PG8_LAS bf16x8*)(lds + PG8_SB(b, h) + boff + n * 2048 + k * 1024); } while (0)
; #define PG8_MMA(ai, bj, At, Bt) do { __builtin_amdgcn_s_setprio(1); _Pragma("unroll") for (int m = 0; m < 4; ++m) _Pragma("unroll") for (int n = 0; n < 2; ++n) _Pragma("unroll") for (int k = 0; k < 2; ++k) \
;         acc[ai][bj][m][n] = __builtin_amdgcn_mfma_f32_16x16x32_bf16(Bt[n][k], At[m][k], acc[ai][bj][m][n], 0, 0, 0); __builtin_amdgcn_s_setprio(0); } while (0)
; #define PG8_WAIT_V(n) asm volatile("s_waitcnt vmcnt(" #n ")" ::: "memory")
; #define PG8_WAIT_L(n) asm volatile("s_waitcnt lgkmcnt(" #n ")" ::: "memory")
; #define PG8_BAR __builtin_amdgcn_s_barrier()
; #define PG8_SCHED __builtin_amdgcn_sched_barrier(0)
; template <class Epi, class Sched, bool ALIGN_EPI = false, bool SP2 = false>
; __device__ __forceinline__ void gemm_phase(PG8_LAS unsigned char* lds, const Gemm g, const Sched& S, const Epi& E) {
;     ...
;             PG8_LDB(B0, 0, 0); PG8_LDB(B1, 0, 1); PG8_SCHED; PG8_LDA(At, 0, 0); PG8_STAGE(PG8_SA(1, 1), a1 + hstepA, voffA);
;             PG8_WAIT_V(8); PG8_WAIT_L(0); PG8_BAR; PG8_MMA(0, 0, At, B0); PG8_MMA(0, 1, At, B1); PG8_BAR; PG8_SCHED;
;             PG8_LDA(At, 0, 1); PG8_STAGE(PG8_SB(0, 0), b2, voffB); PG8_STAGE(PG8_SB(0, 1), b2 + hstepB, voffB); PG8_STAGE(PG8_SA(0, 0), a2, voffA);
;             PG8_WAIT_V(8); PG8_WAIT_L(0); PG8_BAR; PG8_MMA(1, 0, At, B0); PG8_MMA(1, 1, At, B1); PG8_BAR; PG8_SCHED;
.LBB0_1695:
	ds_read_b128 v[120:123], v183
	ds_read_b128 v[124:127], v183 offset:1024
	ds_read_b128 v[136:139], v183 offset:2048
	ds_read_b128 v[140:143], v183 offset:3072
	ds_read_b128 v[144:147], v187
	ds_read_b128 v[148:151], v187 offset:1024
	ds_read_b128 v[192:195], v187 offset:2048
	ds_read_b128 v[196:199], v187 offset:3072
	s_add_i32 s67, s36, 2
	s_add_u32 s37, s12, 0xfffc0080
	s_addc_u32 s52, s13, -1
	s_cmp_eq_u32 s63, s36
	s_cselect_b32 s36, s21, s45
	s_cselect_b32 s53, s11, s52
	s_cselect_b32 s52, s19, s37
	s_cselect_b32 s37, s20, s47
	v_lshl_add_u64 v[168:169], s[12:13], 0, v[160:161]
	s_add_i32 m0, s58, 0xc000
	ds_read_b128 v[200:203], v191
	ds_read_b128 v[204:207], v191 offset:1024
	ds_read_b128 v[208:211], v191 offset:2048
	ds_read_b128 v[212:215], v191 offset:3072
	ds_read_b128 v[216:219], v191 offset:4096
	ds_read_b128 v[220:223], v191 offset:5120
	ds_read_b128 v[224:227], v191 offset:6144
	ds_read_b128 v[228:231], v191 offset:7168
	global_load_lds_dwordx4 v[168:169], off
	v_lshl_add_u64 v[168:169], s[12:13], 0, v[162:163]
	s_add_i32 m0, s58, 0xe000
	s_nop 0
	global_load_lds_dwordx4 v[168:169], off
	s_waitcnt vmcnt(8)
	s_waitcnt lgkmcnt(0)
	s_barrier
	s_waitcnt lgkmcnt(0)
	v_mfma_f32_16x16x32_bf16 v[132:135], v[120:123], v[200:203], v[132:135]
	v_mfma_f32_16x16x32_bf16 v[128:131], v[136:139], v[200:203], v[128:131]
	v_mfma_f32_16x16x32_bf16 v[116:119], v[120:123], v[208:211], v[116:119]
	v_mfma_f32_16x16x32_bf16 v[112:115], v[136:139], v[208:211], v[112:115]
	v_mfma_f32_16x16x32_bf16 v[108:111], v[120:123], v[216:219], v[108:111]
	v_mfma_f32_16x16x32_bf16 v[104:107], v[136:139], v[216:219], v[104:107]
	v_mfma_f32_16x16x32_bf16 v[100:103], v[120:123], v[224:227], v[100:103]
	v_mfma_f32_16x16x32_bf16 v[96:99], v[136:139], v[224:227], v[96:99]
	v_mfma_f32_16x16x32_bf16 v[132:135], v[124:127], v[204:207], v[132:135]
	v_mfma_f32_16x16x32_bf16 v[128:131], v[140:143], v[204:207], v[128:131]
	v_mfma_f32_16x16x32_bf16 v[116:119], v[124:127], v[212:215], v[116:119]
	v_mfma_f32_16x16x32_bf16 v[112:115], v[140:143], v[212:215], v[112:115]
	v_mfma_f32_16x16x32_bf16 v[108:111], v[124:127], v[220:223], v[108:111]
	v_mfma_f32_16x16x32_bf16 v[104:107], v[140:143], v[220:223], v[104:107]
	v_mfma_f32_16x16x32_bf16 v[100:103], v[124:127], v[228:231], v[100:103]
	v_mfma_f32_16x16x32_bf16 v[96:99], v[140:143], v[228:231], v[96:99]
	v_mfma_f32_16x16x32_bf16 v[60:63], v[144:147], v[200:203], v[60:63]
	v_mfma_f32_16x16x32_bf16 v[56:59], v[192:195], v[200:203], v[56:59]
	v_mfma_f32_16x16x32_bf16 v[52:55], v[144:147], v[208:211], v[52:55]
	v_mfma_f32_16x16x32_bf16 v[48:51], v[192:195], v[208:211], v[48:51]
	v_mfma_f32_16x16x32_bf16 v[44:47], v[144:147], v[216:219], v[44:47]
	v_mfma_f32_16x16x32_bf16 v[40:43], v[192:195], v[216:219], v[40:43]
	v_mfma_f32_16x16x32_bf16 v[36:39], v[144:147], v[224:227], v[36:39]
	v_mfma_f32_16x16x32_bf16 v[32:35], v[192:195], v[224:227], v[32:35]
	v_mfma_f32_16x16x32_bf16 v[60:63], v[148:151], v[204:207], v[60:63]
	v_mfma_f32_16x16x32_bf16 v[56:59], v[196:199], v[204:207], v[56:59]
	v_mfma_f32_16x16x32_bf16 v[52:55], v[148:151], v[212:215], v[52:55]
	v_mfma_f32_16x16x32_bf16 v[48:51], v[196:199], v[212:215], v[48:51]
	v_mfma_f32_16x16x32_bf16 v[44:47], v[148:151], v[220:223], v[44:47]
	v_mfma_f32_16x16x32_bf16 v[40:43], v[196:199], v[220:223], v[40:43]
	v_mfma_f32_16x16x32_bf16 v[36:39], v[148:151], v[228:231], v[36:39]
	v_mfma_f32_16x16x32_bf16 v[32:35], v[196:199], v[228:231], v[32:35]
	s_barrier
	s_add_i32 s68, s65, s57
	v_lshl_add_u64 v[168:169], s[36:37], 0, v[154:155]
	s_mov_b32 m0, s68
	ds_read_b128 v[200:203], v191 offset:16384
	ds_read_b128 v[204:207], v191 offset:17408
	ds_read_b128 v[208:211], v191 offset:18432
	ds_read_b128 v[212:215], v191 offset:19456
	ds_read_b128 v[216:219], v191 offset:20480
	ds_read_b128 v[220:223], v191 offset:21504
	ds_read_b128 v[224:227], v191 offset:22528
	ds_read_b128 v[228:231], v191 offset:23552
	global_load_lds_dwordx4 v[168:169], off
	s_add_i32 m0, s68, 0x2000
	s_add_u32 s68, s36, 0x40000
	v_lshl_add_u64 v[172:173], s[36:37], 0, v[158:159]
	s_addc_u32 s69, s37, 0
	s_add_i32 s70, s66, s57
	global_load_lds_dwordx4 v[172:173], off
	v_lshl_add_u64 v[176:177], s[68:69], 0, v[154:155]
	s_mov_b32 m0, s70
	v_lshl_add_u64 v[180:181], s[52:53], 0, v[156:157]
	global_load_lds_dwordx4 v[176:177], off
	v_lshl_add_u64 v[176:177], s[68:69], 0, v[158:159]
	s_add_i32 m0, s70, 0x2000
	s_nop 0
	global_load_lds_dwordx4 v[176:177], off
	v_lshl_add_u64 v[176:177], s[52:53], 0, v[152:153]
	s_mov_b32 m0, s58
	s_nop 0
	global_load_lds_dwordx4 v[176:177], off
	s_mov_b32 m0, s33
	s_nop 0
	global_load_lds_dwordx4 v[180:181], off
	s_waitcnt vmcnt(8)
	s_waitcnt lgkmcnt(0)
	s_barrier
; #define PG8_STAGE(bufoff, gbase, voff) do { _Pragma("unroll") for (int _i = 0; _i < 2; ++_i) \
;         __builtin_amdgcn_global_load_lds((const unsigned*)((const char*)(gbase) + (voff)[_i]), (PG8_LAS unsigned*)(lds + (bufoff) + ldsw + _i * 8192), 16, 0, 0); } while (0)
; #define PG8_LDA(dst, b, h) do { _Pragma("unroll") for (int m = 0; m < 4; ++m) _Pragma("unroll") for (int k = 0; k < 2; ++k) dst[m][k] = *(const PG8_LAS bf16x8*)(lds + PG8_SA(b, h) + aoff + m * 2048 + k * 1024); } while (0)
; #define PG8_LDB(dst, b, h) do { _Pragma("unroll") for (int n = 0; n < 2; ++n) _Pragma("unroll") for (int k = 0; k < 2; ++k) dst[n][k] = *(const PG8_LAS bf16x8*)(lds + PG8_SB(b, h) + boff + n * 2048 + k * 1024); } while (0)
; #define PG8_MMA(ai, bj, At, Bt) do { __builtin_amdgcn_s_setprio(1); _Pragma("unroll") for (int m = 0; m < 4; ++m) _Pragma("unroll") for (int n = 0; n < 2; ++n) _Pragma("unroll") for (int k = 0; k < 2; ++k) \
;         acc[ai][bj][m][n] = __builtin_amdgcn_mfma_f32_16x16x32_bf16(Bt[n][k], At[m][k], acc[ai][bj][m][n], 0, 0, 0); __builtin_amdgcn_s_setprio(0); } while (0)
; #define PG8_WAIT_V(n) asm volatile("s_waitcnt vmcnt(" #n ")" ::: "memory")
; #define PG8_WAIT_L(n) asm volatile("s_waitcnt lgkmcnt(" #n ")" ::: "memory")
; #define PG8_BAR __builtin_amdgcn_s_barrier()
; #define PG8_SCHED __builtin_amdgcn_sched_barrier(0)
; template <class Epi, class Sched, bool ALIGN_EPI = false, bool SP2 = false>
; __device__ __forceinline__ void gemm_phase(PG8_LAS unsigned char* lds, const Gemm g, const Sched& S, const Epi& E) {
;     ...
;             PG8_WAIT_V(8); PG8_WAIT_L(0); PG8_BAR; PG8_MMA(1, 0, At, B0); PG8_MMA(1, 1, At, B1); PG8_BAR; PG8_SCHED;
;             PG8_LDB(B0, 1, 0); PG8_LDB(B1, 1, 1); PG8_SCHED; PG8_LDA(At, 1, 0); PG8_STAGE(PG8_SA(0, 1), a2 + hstepA, voffA);
;             PG8_WAIT_V(8); PG8_WAIT_L(0); PG8_BAR; PG8_MMA(0, 0, At, B0); PG8_MMA(0, 1, At, B1); PG8_BAR; PG8_SCHED;
	s_waitcnt lgkmcnt(0)
	v_mfma_f32_16x16x32_bf16 v[92:95], v[120:123], v[200:203], v[92:95]
	v_mfma_f32_16x16x32_bf16 v[88:91], v[136:139], v[200:203], v[88:91]
	v_mfma_f32_16x16x32_bf16 v[84:87], v[120:123], v[208:211], v[84:87]
	v_mfma_f32_16x16x32_bf16 v[80:83], v[136:139], v[208:211], v[80:83]
	v_mfma_f32_16x16x32_bf16 v[76:79], v[120:123], v[216:219], v[76:79]
	v_mfma_f32_16x16x32_bf16 v[72:75], v[136:139], v[216:219], v[72:75]
	v_mfma_f32_16x16x32_bf16 v[68:71], v[120:123], v[224:227], v[68:71]
	v_mfma_f32_16x16x32_bf16 v[64:67], v[136:139], v[224:227], v[64:67]
	v_mfma_f32_16x16x32_bf16 v[92:95], v[124:127], v[204:207], v[92:95]
	v_mfma_f32_16x16x32_bf16 v[88:91], v[140:143], v[204:207], v[88:91]
	v_mfma_f32_16x16x32_bf16 v[84:87], v[124:127], v[212:215], v[84:87]
	v_mfma_f32_16x16x32_bf16 v[80:83], v[140:143], v[212:215], v[80:83]
	v_mfma_f32_16x16x32_bf16 v[76:79], v[124:127], v[220:223], v[76:79]
	v_mfma_f32_16x16x32_bf16 v[72:75], v[140:143], v[220:223], v[72:75]
	v_mfma_f32_16x16x32_bf16 v[68:71], v[124:127], v[228:231], v[68:71]
	v_mfma_f32_16x16x32_bf16 v[64:67], v[140:143], v[228:231], v[64:67]
	v_mfma_f32_16x16x32_bf16 v[28:31], v[144:147], v[200:203], v[28:31]
	v_mfma_f32_16x16x32_bf16 v[24:27], v[192:195], v[200:203], v[24:27]
	v_mfma_f32_16x16x32_bf16 v[20:23], v[144:147], v[208:211], v[20:23]
	v_mfma_f32_16x16x32_bf16 v[16:19], v[192:195], v[208:211], v[16:19]
	v_mfma_f32_16x16x32_bf16 v[12:15], v[144:147], v[216:219], v[12:15]
	v_mfma_f32_16x16x32_bf16 v[8:11], v[192:195], v[216:219], v[8:11]
	v_mfma_f32_16x16x32_bf16 v[4:7], v[144:147], v[224:227], v[4:7]
	v_mfma_f32_16x16x32_bf16 v[0:3], v[192:195], v[224:227], v[0:3]
	v_mfma_f32_16x16x32_bf16 v[28:31], v[148:151], v[204:207], v[28:31]
	v_mfma_f32_16x16x32_bf16 v[24:27], v[196:199], v[204:207], v[24:27]
	v_mfma_f32_16x16x32_bf16 v[20:23], v[148:151], v[212:215], v[20:23]
	v_mfma_f32_16x16x32_bf16 v[16:19], v[196:199], v[212:215], v[16:19]
	v_mfma_f32_16x16x32_bf16 v[12:15], v[148:151], v[220:223], v[12:15]
	v_mfma_f32_16x16x32_bf16 v[8:11], v[196:199], v[220:223], v[8:11]
	v_mfma_f32_16x16x32_bf16 v[4:7], v[148:151], v[228:231], v[4:7]
	v_mfma_f32_16x16x32_bf16 v[0:3], v[196:199], v[228:231], v[0:3]
	s_barrier
	s_add_i32 s68, 0, 0x18000
	s_add_i32 s69, 0, 0x1c000
	v_add_u32_e32 v140, s68, v179
	v_add_u32_e32 v170, s69, v179
	ds_read_b128 v[120:123], v140
	ds_read_b128 v[124:127], v140 offset:1024
	ds_read_b128 v[136:139], v140 offset:2048
	ds_read_b128 v[140:143], v140 offset:3072
	ds_read_b128 v[144:147], v170
	ds_read_b128 v[148:151], v170 offset:1024
	ds_read_b128 v[192:195], v170 offset:2048
	ds_read_b128 v[196:199], v170 offset:3072
	s_add_u32 s52, s52, 0x40000
	s_addc_u32 s53, s53, 0
	s_mov_b32 m0, s59
	v_lshl_add_u64 v[184:185], s[52:53], 0, v[152:153]
	ds_read_b128 v[200:203], v191 offset:32768
	ds_read_b128 v[204:207], v191 offset:33792
	ds_read_b128 v[208:211], v191 offset:34816
	ds_read_b128 v[212:215], v191 offset:35840
	ds_read_b128 v[216:219], v191 offset:36864
	ds_read_b128 v[220:223], v191 offset:37888
	ds_read_b128 v[224:227], v191 offset:38912
	ds_read_b128 v[228:231], v191 offset:39936
	global_load_lds_dwordx4 v[184:185], off
	v_lshl_add_u64 v[184:185], s[52:53], 0, v[156:157]
	s_mov_b32 m0, s60
	s_nop 0
	global_load_lds_dwordx4 v[184:185], off
	s_waitcnt vmcnt(8)
	s_waitcnt lgkmcnt(0)
	s_barrier
	s_waitcnt lgkmcnt(0)
	v_mfma_f32_16x16x32_bf16 v[132:135], v[120:123], v[200:203], v[132:135]
	v_mfma_f32_16x16x32_bf16 v[128:131], v[136:139], v[200:203], v[128:131]
	v_mfma_f32_16x16x32_bf16 v[116:119], v[120:123], v[208:211], v[116:119]
	v_mfma_f32_16x16x32_bf16 v[112:115], v[136:139], v[208:211], v[112:115]
	v_mfma_f32_16x16x32_bf16 v[108:111], v[120:123], v[216:219], v[108:111]
	v_mfma_f32_16x16x32_bf16 v[104:107], v[136:139], v[216:219], v[104:107]
	v_mfma_f32_16x16x32_bf16 v[100:103], v[120:123], v[224:227], v[100:103]
	v_mfma_f32_16x16x32_bf16 v[96:99], v[136:139], v[224:227], v[96:99]
	v_mfma_f32_16x16x32_bf16 v[132:135], v[124:127], v[204:207], v[132:135]
	v_mfma_f32_16x16x32_bf16 v[128:131], v[140:143], v[204:207], v[128:131]
	v_mfma_f32_16x16x32_bf16 v[116:119], v[124:127], v[212:215], v[116:119]
	v_mfma_f32_16x16x32_bf16 v[112:115], v[140:143], v[212:215], v[112:115]
	v_mfma_f32_16x16x32_bf16 v[108:111], v[124:127], v[220:223], v[108:111]
	v_mfma_f32_16x16x32_bf16 v[104:107], v[140:143], v[220:223], v[104:107]
	v_mfma_f32_16x16x32_bf16 v[100:103], v[124:127], v[228:231], v[100:103]
	v_mfma_f32_16x16x32_bf16 v[96:99], v[140:143], v[228:231], v[96:99]
	v_mfma_f32_16x16x32_bf16 v[60:63], v[144:147], v[200:203], v[60:63]
	v_mfma_f32_16x16x32_bf16 v[56:59], v[192:195], v[200:203], v[56:59]
	v_mfma_f32_16x16x32_bf16 v[52:55], v[144:147], v[208:211], v[52:55]
	v_mfma_f32_16x16x32_bf16 v[48:51], v[192:195], v[208:211], v[48:51]
	v_mfma_f32_16x16x32_bf16 v[44:47], v[144:147], v[216:219], v[44:47]
	v_mfma_f32_16x16x32_bf16 v[40:43], v[192:195], v[216:219], v[40:43]
	v_mfma_f32_16x16x32_bf16 v[36:39], v[144:147], v[224:227], v[36:39]
	v_mfma_f32_16x16x32_bf16 v[32:35], v[192:195], v[224:227], v[32:35]
	v_mfma_f32_16x16x32_bf16 v[60:63], v[148:151], v[204:207], v[60:63]
	v_mfma_f32_16x16x32_bf16 v[56:59], v[196:199], v[204:207], v[56:59]
	v_mfma_f32_16x16x32_bf16 v[52:55], v[148:151], v[212:215], v[52:55]
	v_mfma_f32_16x16x32_bf16 v[48:51], v[196:199], v[212:215], v[48:51]
	v_mfma_f32_16x16x32_bf16 v[44:47], v[148:151], v[220:223], v[44:47]
	v_mfma_f32_16x16x32_bf16 v[40:43], v[196:199], v[220:223], v[40:43]
	v_mfma_f32_16x16x32_bf16 v[36:39], v[148:151], v[228:231], v[36:39]
	v_mfma_f32_16x16x32_bf16 v[32:35], v[196:199], v[228:231], v[32:35]
	s_barrier
; #define PG8_STAGE(bufoff, gbase, voff) do { _Pragma("unroll") for (int _i = 0; _i < 2; ++_i) \
;         __builtin_amdgcn_global_load_lds((const unsigned*)((const char*)(gbase) + (voff)[_i]), (PG8_LAS unsigned*)(lds + (bufoff) + ldsw + _i * 8192), 16, 0, 0); } while (0)
; #define PG8_LDA(dst, b, h) do { _Pragma("unroll") for (int m = 0; m < 4; ++m) _Pragma("unroll") for (int k = 0; k < 2; ++k) dst[m][k] = *(const PG8_LAS bf16x8*)(lds + PG8_SA(b, h) + aoff + m * 2048 + k * 1024); } while (0)
; #define PG8_MMA(ai, bj, At, Bt) do { __builtin_amdgcn_s_setprio(1); _Pragma("unroll") for (int m = 0; m < 4; ++m) _Pragma("unroll") for (int n = 0; n < 2; ++n) _Pragma("unroll") for (int k = 0; k < 2; ++k) \
;         acc[ai][bj][m][n] = __builtin_amdgcn_mfma_f32_16x16x32_bf16(Bt[n][k], At[m][k], acc[ai][bj][m][n], 0, 0, 0); __builtin_amdgcn_s_setprio(0); } while (0)
; #define PG8_WAIT_V(n) asm volatile("s_waitcnt vmcnt(" #n ")" ::: "memory")
; #define PG8_WAIT_L(n) asm volatile("s_waitcnt lgkmcnt(" #n ")" ::: "memory")
; #define PG8_BAR __builtin_amdgcn_s_barrier()
; #define PG8_SCHED __builtin_amdgcn_sched_barrier(0)
; template <class Epi, class Sched, bool ALIGN_EPI = false, bool SP2 = false>
; __device__ __forceinline__ void gemm_phase(PG8_LAS unsigned char* lds, const Gemm g, const Sched& S, const Epi& E) {
;     ...
;         for (int t = 0; t < nt; t += 2) {
;             const bool last = (t == nt - 2);
;             const char* a1 = cA + (long)(t + 1) * kstepA;
;             const char* a2 = last ? nA : cA + (long)(t + 2) * kstepA; const char* b2 = last ? nB : cB + (long)(t + 2) * kstep;
;             const char* a3 = a2 + kstepA; const char* b3 = b2 + kstep;
;             if (last && has_next) S.a_ready(nxt);
;     ...
;             PG8_LDA(At, 1, 1); PG8_STAGE(PG8_SB(1, 0), b3, voffB); PG8_STAGE(PG8_SB(1, 1), b3 + hstepB, voffB); PG8_STAGE(PG8_SA(1, 0), a3, voffA);
;             PG8_WAIT_V(8); PG8_WAIT_L(0); PG8_BAR; PG8_MMA(1, 0, At, B0); PG8_MMA(1, 1, At, B1); PG8_BAR; PG8_SCHED;
	s_add_i32 s52, s68, s57
	v_lshl_add_u64 v[168:169], v[168:169], 0, s[30:31]
	s_mov_b32 m0, s52
	ds_read_b128 v[200:203], v191 offset:49152
	ds_read_b128 v[204:207], v191 offset:50176
	ds_read_b128 v[208:211], v191 offset:51200
	ds_read_b128 v[212:215], v191 offset:52224
	ds_read_b128 v[216:219], v191 offset:53248
	ds_read_b128 v[220:223], v191 offset:54272
	ds_read_b128 v[224:227], v191 offset:55296
	ds_read_b128 v[228:231], v191 offset:56320
	global_load_lds_dwordx4 v[168:169], off
	s_add_i32 m0, s52, 0x2000
	s_add_u32 s36, s36, 0x40080
	v_lshl_add_u64 v[168:169], v[172:173], 0, s[30:31]
	s_addc_u32 s37, s37, 0
	s_add_i32 s52, s69, s57
	global_load_lds_dwordx4 v[168:169], off
	v_lshl_add_u64 v[168:169], s[36:37], 0, v[154:155]
	s_mov_b32 m0, s52
	s_nop 0
	global_load_lds_dwordx4 v[168:169], off
	v_lshl_add_u64 v[168:169], s[36:37], 0, v[158:159]
	s_add_i32 m0, s52, 0x2000
	s_nop 0
	global_load_lds_dwordx4 v[168:169], off
	v_lshl_add_u64 v[168:169], v[176:177], 0, s[30:31]
	s_mov_b32 m0, s17
	s_nop 0
	global_load_lds_dwordx4 v[168:169], off
	v_lshl_add_u64 v[168:169], v[180:181], 0, s[30:31]
	s_mov_b32 m0, s62
	s_nop 0
	global_load_lds_dwordx4 v[168:169], off
	s_waitcnt vmcnt(8)
	s_waitcnt lgkmcnt(0)
	s_barrier
	s_waitcnt lgkmcnt(0)
	v_mfma_f32_16x16x32_bf16 v[92:95], v[120:123], v[200:203], v[92:95]
	v_mfma_f32_16x16x32_bf16 v[88:91], v[136:139], v[200:203], v[88:91]
	v_mfma_f32_16x16x32_bf16 v[84:87], v[120:123], v[208:211], v[84:87]
	v_mfma_f32_16x16x32_bf16 v[80:83], v[136:139], v[208:211], v[80:83]
	v_mfma_f32_16x16x32_bf16 v[76:79], v[120:123], v[216:219], v[76:79]
	v_mfma_f32_16x16x32_bf16 v[72:75], v[136:139], v[216:219], v[72:75]
	v_mfma_f32_16x16x32_bf16 v[68:71], v[120:123], v[224:227], v[68:71]
	v_mfma_f32_16x16x32_bf16 v[64:67], v[136:139], v[224:227], v[64:67]
	v_mfma_f32_16x16x32_bf16 v[92:95], v[124:127], v[204:207], v[92:95]
	v_mfma_f32_16x16x32_bf16 v[88:91], v[140:143], v[204:207], v[88:91]
	v_mfma_f32_16x16x32_bf16 v[84:87], v[124:127], v[212:215], v[84:87]
	v_mfma_f32_16x16x32_bf16 v[80:83], v[140:143], v[212:215], v[80:83]
	v_mfma_f32_16x16x32_bf16 v[76:79], v[124:127], v[220:223], v[76:79]
	v_mfma_f32_16x16x32_bf16 v[72:75], v[140:143], v[220:223], v[72:75]
	v_mfma_f32_16x16x32_bf16 v[68:71], v[124:127], v[228:231], v[68:71]
	v_mfma_f32_16x16x32_bf16 v[64:67], v[140:143], v[228:231], v[64:67]
	v_mfma_f32_16x16x32_bf16 v[28:31], v[144:147], v[200:203], v[28:31]
	v_mfma_f32_16x16x32_bf16 v[24:27], v[192:195], v[200:203], v[24:27]
	v_mfma_f32_16x16x32_bf16 v[20:23], v[144:147], v[208:211], v[20:23]
	v_mfma_f32_16x16x32_bf16 v[16:19], v[192:195], v[208:211], v[16:19]
	v_mfma_f32_16x16x32_bf16 v[12:15], v[144:147], v[216:219], v[12:15]
	v_mfma_f32_16x16x32_bf16 v[8:11], v[192:195], v[216:219], v[8:11]
	v_mfma_f32_16x16x32_bf16 v[4:7], v[144:147], v[224:227], v[4:7]
	v_mfma_f32_16x16x32_bf16 v[0:3], v[192:195], v[224:227], v[0:3]
	v_mfma_f32_16x16x32_bf16 v[28:31], v[148:151], v[204:207], v[28:31]
	v_mfma_f32_16x16x32_bf16 v[24:27], v[196:199], v[204:207], v[24:27]
	v_mfma_f32_16x16x32_bf16 v[20:23], v[148:151], v[212:215], v[20:23]
	v_mfma_f32_16x16x32_bf16 v[16:19], v[196:199], v[212:215], v[16:19]
	v_mfma_f32_16x16x32_bf16 v[12:15], v[148:151], v[220:223], v[12:15]
	v_mfma_f32_16x16x32_bf16 v[8:11], v[196:199], v[220:223], v[8:11]
	v_mfma_f32_16x16x32_bf16 v[4:7], v[148:151], v[228:231], v[4:7]
	v_mfma_f32_16x16x32_bf16 v[0:3], v[196:199], v[228:231], v[0:3]
	s_barrier
	s_add_u32 s12, s12, 0x100
	s_addc_u32 s13, s13, 0
	s_add_u32 s45, s45, 0x100
	s_addc_u32 s47, s47, 0
	s_cmp_ge_i32 s67, s14
	s_mov_b32 s36, s67
	s_cbranch_scc0 .LBB0_1695

; #define PG8_STAGE(bufoff, gbase, voff) do { _Pragma("unroll") for (int _i = 0; _i < 2; ++_i) \
;         __builtin_amdgcn_global_load_lds((const unsigned*)((const char*)(gbase) + (voff)[_i]), (PG8_LAS unsigned*)(lds + (bufoff) + ldsw + _i * 8192), 16, 0, 0); } while (0)
; #define PG8_LDA(dst, b, h) do { _Pragma("unroll") for (int m = 0; m < 4; ++m) _Pragma("unroll") for (int k = 0; k < 2; ++k) dst[m][k] = *(const PG8_LAS bf16x8*)(lds + PG8_SA(b, h) + aoff + m * 2048 + k * 1024); } while (0)
; #define PG8_LDB(dst, b, h) do { _Pragma("unroll") for (int n = 0; n < 2; ++n) _Pragma("unroll") for (int k = 0; k < 2; ++k) dst[n][k] = *(const PG8_LAS bf16x8*)(lds + PG8_SB(b, h) + boff + n * 2048 + k * 1024); } while (0)
; #define PG8_MMA(ai, bj, At, Bt) do { __builtin_amdgcn_s_setprio(1); _Pragma("unroll") for (int m = 0; m < 4; ++m) _Pragma("unroll") for (int n = 0; n < 2; ++n) _Pragma("unroll") for (int k = 0; k < 2; ++k) \
;         acc[ai][bj][m][n] = __builtin_amdgcn_mfma_f32_16x16x32_bf16(Bt[n][k], At[m][k], acc[ai][bj][m][n], 0, 0, 0); __builtin_amdgcn_s_setprio(0); } while (0)
; #define PG8_WAIT_V(n) asm volatile("s_waitcnt vmcnt(" #n ")" ::: "memory")
; #define PG8_WAIT_L(n) asm volatile("s_waitcnt lgkmcnt(" #n ")" ::: "memory")
; #define PG8_BAR __builtin_amdgcn_s_barrier()
; #define PG8_SCHED __builtin_amdgcn_sched_barrier(0)
; template <class Epi, class Sched, bool ALIGN_EPI = false, bool SP2 = false>
; __device__ __forceinline__ void gemm_phase(PG8_LAS unsigned char* lds, const Gemm g, const Sched& S, const Epi& E) {
;     ...
;             PG8_LDB(B0, 0, 0); PG8_LDB(B1, 0, 1); PG8_SCHED; PG8_LDA(At, 0, 0); PG8_STAGE(PG8_SA(1, 1), a1 + hstepA, voffA);
;             PG8_WAIT_V(8); PG8_WAIT_L(0); PG8_BAR; PG8_MMA(0, 0, At, B0); PG8_MMA(0, 1, At, B1); PG8_BAR; PG8_SCHED;
;             PG8_LDA(At, 0, 1); PG8_STAGE(PG8_SB(0, 0), b2, voffB); PG8_STAGE(PG8_SB(0, 1), b2 + hstepB, voffB); PG8_STAGE(PG8_SA(0, 0), a2, voffA);
;             PG8_WAIT_V(8); PG8_WAIT_L(0); PG8_BAR; PG8_MMA(1, 0, At, B0); PG8_MMA(1, 1, At, B1); PG8_BAR; PG8_SCHED;
.LBB0_2190:
	ds_read_b128 v[112:115], v195
	ds_read_b128 v[116:119], v195 offset:1024
	ds_read_b128 v[120:123], v195 offset:2048
	ds_read_b128 v[124:127], v195 offset:3072
	ds_read_b128 v[128:131], v199
	ds_read_b128 v[132:135], v199 offset:1024
	ds_read_b128 v[136:139], v199 offset:2048
	ds_read_b128 v[140:143], v199 offset:3072
	s_add_i32 s67, s36, 2
	s_add_u32 s37, s12, 0xfffc0080
	s_addc_u32 s56, s13, -1
	s_cmp_eq_u32 s63, s36
	s_cselect_b32 s36, s21, s49
	s_cselect_b32 s57, s18, s56
	s_cselect_b32 s56, s19, s37
	s_cselect_b32 s37, s20, s51
	v_lshl_add_u64 v[180:181], s[12:13], 0, v[172:173]
	s_add_i32 m0, s15, 0xc000
	ds_read_b128 v[160:163], v203
	ds_read_b128 v[204:207], v203 offset:1024
	ds_read_b128 v[208:211], v203 offset:2048
	ds_read_b128 v[212:215], v203 offset:3072
	ds_read_b128 v[216:219], v203 offset:4096
	ds_read_b128 v[220:223], v203 offset:5120
	ds_read_b128 v[224:227], v203 offset:6144
	ds_read_b128 v[228:231], v203 offset:7168
	global_load_lds_dwordx4 v[180:181], off
	v_lshl_add_u64 v[180:181], s[12:13], 0, v[174:175]
	s_add_i32 m0, s15, 0xe000
	s_nop 0
	global_load_lds_dwordx4 v[180:181], off
	s_waitcnt vmcnt(8)
	s_waitcnt lgkmcnt(0)
	s_barrier
	s_waitcnt lgkmcnt(0)
	v_mfma_f32_16x16x32_bf16 v[156:159], v[112:115], v[160:163], v[156:159]
	v_mfma_f32_16x16x32_bf16 v[152:155], v[120:123], v[160:163], v[152:155]
	v_mfma_f32_16x16x32_bf16 v[148:151], v[112:115], v[208:211], v[148:151]
	v_mfma_f32_16x16x32_bf16 v[144:147], v[120:123], v[208:211], v[144:147]
	v_mfma_f32_16x16x32_bf16 v[108:111], v[112:115], v[216:219], v[108:111]
	v_mfma_f32_16x16x32_bf16 v[104:107], v[120:123], v[216:219], v[104:107]
	v_mfma_f32_16x16x32_bf16 v[100:103], v[112:115], v[224:227], v[100:103]
	v_mfma_f32_16x16x32_bf16 v[96:99], v[120:123], v[224:227], v[96:99]
	v_mfma_f32_16x16x32_bf16 v[156:159], v[116:119], v[204:207], v[156:159]
	v_mfma_f32_16x16x32_bf16 v[152:155], v[124:127], v[204:207], v[152:155]
	v_mfma_f32_16x16x32_bf16 v[148:151], v[116:119], v[212:215], v[148:151]
	v_mfma_f32_16x16x32_bf16 v[144:147], v[124:127], v[212:215], v[144:147]
	v_mfma_f32_16x16x32_bf16 v[108:111], v[116:119], v[220:223], v[108:111]
	v_mfma_f32_16x16x32_bf16 v[104:107], v[124:127], v[220:223], v[104:107]
	v_mfma_f32_16x16x32_bf16 v[100:103], v[116:119], v[228:231], v[100:103]
	v_mfma_f32_16x16x32_bf16 v[96:99], v[124:127], v[228:231], v[96:99]
	v_mfma_f32_16x16x32_bf16 v[60:63], v[128:131], v[160:163], v[60:63]
	v_mfma_f32_16x16x32_bf16 v[56:59], v[136:139], v[160:163], v[56:59]
	v_mfma_f32_16x16x32_bf16 v[52:55], v[128:131], v[208:211], v[52:55]
	v_mfma_f32_16x16x32_bf16 v[48:51], v[136:139], v[208:211], v[48:51]
	v_mfma_f32_16x16x32_bf16 v[44:47], v[128:131], v[216:219], v[44:47]
	v_mfma_f32_16x16x32_bf16 v[40:43], v[136:139], v[216:219], v[40:43]
	v_mfma_f32_16x16x32_bf16 v[36:39], v[128:131], v[224:227], v[36:39]
	v_mfma_f32_16x16x32_bf16 v[32:35], v[136:139], v[224:227], v[32:35]
	v_mfma_f32_16x16x32_bf16 v[60:63], v[132:135], v[204:207], v[60:63]
	v_mfma_f32_16x16x32_bf16 v[56:59], v[140:143], v[204:207], v[56:59]
	v_mfma_f32_16x16x32_bf16 v[52:55], v[132:135], v[212:215], v[52:55]
	v_mfma_f32_16x16x32_bf16 v[48:51], v[140:143], v[212:215], v[48:51]
	v_mfma_f32_16x16x32_bf16 v[44:47], v[132:135], v[220:223], v[44:47]
	v_mfma_f32_16x16x32_bf16 v[40:43], v[140:143], v[220:223], v[40:43]
	v_mfma_f32_16x16x32_bf16 v[36:39], v[132:135], v[228:231], v[36:39]
	v_mfma_f32_16x16x32_bf16 v[32:35], v[140:143], v[228:231], v[32:35]
	s_barrier
	s_add_i32 s68, s65, s14
	v_lshl_add_u64 v[180:181], s[36:37], 0, v[166:167]
	s_mov_b32 m0, s68
	ds_read_b128 v[160:163], v203 offset:16384
	ds_read_b128 v[204:207], v203 offset:17408
	ds_read_b128 v[208:211], v203 offset:18432
	ds_read_b128 v[212:215], v203 offset:19456
	ds_read_b128 v[216:219], v203 offset:20480
	ds_read_b128 v[220:223], v203 offset:21504
	ds_read_b128 v[224:227], v203 offset:22528
	ds_read_b128 v[228:231], v203 offset:23552
	global_load_lds_dwordx4 v[180:181], off
	s_add_i32 m0, s68, 0x2000
	s_add_u32 s68, s36, 0x40000
	v_lshl_add_u64 v[184:185], s[36:37], 0, v[170:171]
	s_addc_u32 s69, s37, 0
	s_add_i32 s70, s66, s14
	global_load_lds_dwordx4 v[184:185], off
	v_lshl_add_u64 v[188:189], s[68:69], 0, v[166:167]
	s_mov_b32 m0, s70
	v_lshl_add_u64 v[192:193], s[56:57], 0, v[168:169]
	global_load_lds_dwordx4 v[188:189], off
	v_lshl_add_u64 v[188:189], s[68:69], 0, v[170:171]
	s_add_i32 m0, s70, 0x2000
	s_nop 0
	global_load_lds_dwordx4 v[188:189], off
	v_lshl_add_u64 v[188:189], s[56:57], 0, v[164:165]
	s_mov_b32 m0, s15
	s_nop 0
	global_load_lds_dwordx4 v[188:189], off
	s_mov_b32 m0, s16
	s_nop 0
	global_load_lds_dwordx4 v[192:193], off
	s_waitcnt vmcnt(8)
	s_waitcnt lgkmcnt(0)
	s_barrier
; #define PG8_STAGE(bufoff, gbase, voff) do { _Pragma("unroll") for (int _i = 0; _i < 2; ++_i) \
;         __builtin_amdgcn_global_load_lds((const unsigned*)((const char*)(gbase) + (voff)[_i]), (PG8_LAS unsigned*)(lds + (bufoff) + ldsw + _i * 8192), 16, 0, 0); } while (0)
; #define PG8_LDA(dst, b, h) do { _Pragma("unroll") for (int m = 0; m < 4; ++m) _Pragma("unroll") for (int k = 0; k < 2; ++k) dst[m][k] = *(const PG8_LAS bf16x8*)(lds + PG8_SA(b, h) + aoff + m * 2048 + k * 1024); } while (0)
; #define PG8_LDB(dst, b, h) do { _Pragma("unroll") for (int n = 0; n < 2; ++n) _Pragma("unroll") for (int k = 0; k < 2; ++k) dst[n][k] = *(const PG8_LAS bf16x8*)(lds + PG8_SB(b, h) + boff + n * 2048 + k * 1024); } while (0)
; #define PG8_MMA(ai, bj, At, Bt) do { __builtin_amdgcn_s_setprio(1); _Pragma("unroll") for (int m = 0; m < 4; ++m) _Pragma("unroll") for (int n = 0; n < 2; ++n) _Pragma("unroll") for (int k = 0; k < 2; ++k) \
;         acc[ai][bj][m][n] = __builtin_amdgcn_mfma_f32_16x16x32_bf16(Bt[n][k], At[m][k], acc[ai][bj][m][n], 0, 0, 0); __builtin_amdgcn_s_setprio(0); } while (0)
; #define PG8_WAIT_V(n) asm volatile("s_waitcnt vmcnt(" #n ")" ::: "memory")
; #define PG8_WAIT_L(n) asm volatile("s_waitcnt lgkmcnt(" #n ")" ::: "memory")
; #define PG8_BAR __builtin_amdgcn_s_barrier()
; #define PG8_SCHED __builtin_amdgcn_sched_barrier(0)
; template <class Epi, class Sched, bool ALIGN_EPI = false, bool SP2 = false>
; __device__ __forceinline__ void gemm_phase(PG8_LAS unsigned char* lds, const Gemm g, const Sched& S, const Epi& E) {
;     ...
;             PG8_WAIT_V(8); PG8_WAIT_L(0); PG8_BAR; PG8_MMA(1, 0, At, B0); PG8_MMA(1, 1, At, B1); PG8_BAR; PG8_SCHED;
;             PG8_LDB(B0, 1, 0); PG8_LDB(B1, 1, 1); PG8_SCHED; PG8_LDA(At, 1, 0); PG8_STAGE(PG8_SA(0, 1), a2 + hstepA, voffA);
;             PG8_WAIT_V(8); PG8_WAIT_L(0); PG8_BAR; PG8_MMA(0, 0, At, B0); PG8_MMA(0, 1, At, B1); PG8_BAR; PG8_SCHED;
	s_waitcnt lgkmcnt(0)
	v_mfma_f32_16x16x32_bf16 v[92:95], v[112:115], v[160:163], v[92:95]
	v_mfma_f32_16x16x32_bf16 v[88:91], v[120:123], v[160:163], v[88:91]
	v_mfma_f32_16x16x32_bf16 v[84:87], v[112:115], v[208:211], v[84:87]
	v_mfma_f32_16x16x32_bf16 v[80:83], v[120:123], v[208:211], v[80:83]
	v_mfma_f32_16x16x32_bf16 v[76:79], v[112:115], v[216:219], v[76:79]
	v_mfma_f32_16x16x32_bf16 v[72:75], v[120:123], v[216:219], v[72:75]
	v_mfma_f32_16x16x32_bf16 v[68:71], v[112:115], v[224:227], v[68:71]
	v_mfma_f32_16x16x32_bf16 v[64:67], v[120:123], v[224:227], v[64:67]
	v_mfma_f32_16x16x32_bf16 v[92:95], v[116:119], v[204:207], v[92:95]
	v_mfma_f32_16x16x32_bf16 v[88:91], v[124:127], v[204:207], v[88:91]
	v_mfma_f32_16x16x32_bf16 v[84:87], v[116:119], v[212:215], v[84:87]
	v_mfma_f32_16x16x32_bf16 v[80:83], v[124:127], v[212:215], v[80:83]
	v_mfma_f32_16x16x32_bf16 v[76:79], v[116:119], v[220:223], v[76:79]
	v_mfma_f32_16x16x32_bf16 v[72:75], v[124:127], v[220:223], v[72:75]
	v_mfma_f32_16x16x32_bf16 v[68:71], v[116:119], v[228:231], v[68:71]
	v_mfma_f32_16x16x32_bf16 v[64:67], v[124:127], v[228:231], v[64:67]
	v_mfma_f32_16x16x32_bf16 v[28:31], v[128:131], v[160:163], v[28:31]
	v_mfma_f32_16x16x32_bf16 v[24:27], v[136:139], v[160:163], v[24:27]
	v_mfma_f32_16x16x32_bf16 v[20:23], v[128:131], v[208:211], v[20:23]
	v_mfma_f32_16x16x32_bf16 v[16:19], v[136:139], v[208:211], v[16:19]
	v_mfma_f32_16x16x32_bf16 v[12:15], v[128:131], v[216:219], v[12:15]
	v_mfma_f32_16x16x32_bf16 v[8:11], v[136:139], v[216:219], v[8:11]
	v_mfma_f32_16x16x32_bf16 v[4:7], v[128:131], v[224:227], v[4:7]
	v_mfma_f32_16x16x32_bf16 v[0:3], v[136:139], v[224:227], v[0:3]
	v_mfma_f32_16x16x32_bf16 v[28:31], v[132:135], v[204:207], v[28:31]
	v_mfma_f32_16x16x32_bf16 v[24:27], v[140:143], v[204:207], v[24:27]
	v_mfma_f32_16x16x32_bf16 v[20:23], v[132:135], v[212:215], v[20:23]
	v_mfma_f32_16x16x32_bf16 v[16:19], v[140:143], v[212:215], v[16:19]
	v_mfma_f32_16x16x32_bf16 v[12:15], v[132:135], v[220:223], v[12:15]
	v_mfma_f32_16x16x32_bf16 v[8:11], v[140:143], v[220:223], v[8:11]
	v_mfma_f32_16x16x32_bf16 v[4:7], v[132:135], v[228:231], v[4:7]
	v_mfma_f32_16x16x32_bf16 v[0:3], v[140:143], v[228:231], v[0:3]
	s_barrier
	s_add_i32 s68, 0, 0x18000
	s_add_i32 s69, 0, 0x1c000
	v_add_u32_e32 v124, s68, v191
	v_add_u32_e32 v140, s69, v191
	ds_read_b128 v[112:115], v124
	ds_read_b128 v[116:119], v124 offset:1024
	ds_read_b128 v[120:123], v124 offset:2048
	ds_read_b128 v[124:127], v124 offset:3072
	ds_read_b128 v[128:131], v140
	ds_read_b128 v[132:135], v140 offset:1024
	ds_read_b128 v[136:139], v140 offset:2048
	ds_read_b128 v[140:143], v140 offset:3072
	s_add_u32 s56, s56, 0x40000
	s_addc_u32 s57, s57, 0
	s_mov_b32 m0, s17
	v_lshl_add_u64 v[196:197], s[56:57], 0, v[164:165]
	ds_read_b128 v[160:163], v203 offset:32768
	ds_read_b128 v[204:207], v203 offset:33792
	ds_read_b128 v[208:211], v203 offset:34816
	ds_read_b128 v[212:215], v203 offset:35840
	ds_read_b128 v[216:219], v203 offset:36864
	ds_read_b128 v[220:223], v203 offset:37888
	ds_read_b128 v[224:227], v203 offset:38912
	ds_read_b128 v[228:231], v203 offset:39936
	global_load_lds_dwordx4 v[196:197], off
	v_lshl_add_u64 v[196:197], s[56:57], 0, v[168:169]
	s_mov_b32 m0, s33
	s_nop 0
	global_load_lds_dwordx4 v[196:197], off
	s_waitcnt vmcnt(8)
	s_waitcnt lgkmcnt(0)
	s_barrier
	s_waitcnt lgkmcnt(0)
	v_mfma_f32_16x16x32_bf16 v[156:159], v[112:115], v[160:163], v[156:159]
	v_mfma_f32_16x16x32_bf16 v[152:155], v[120:123], v[160:163], v[152:155]
	v_mfma_f32_16x16x32_bf16 v[148:151], v[112:115], v[208:211], v[148:151]
	v_mfma_f32_16x16x32_bf16 v[144:147], v[120:123], v[208:211], v[144:147]
	v_mfma_f32_16x16x32_bf16 v[108:111], v[112:115], v[216:219], v[108:111]
	v_mfma_f32_16x16x32_bf16 v[104:107], v[120:123], v[216:219], v[104:107]
	v_mfma_f32_16x16x32_bf16 v[100:103], v[112:115], v[224:227], v[100:103]
	v_mfma_f32_16x16x32_bf16 v[96:99], v[120:123], v[224:227], v[96:99]
	v_mfma_f32_16x16x32_bf16 v[156:159], v[116:119], v[204:207], v[156:159]
	v_mfma_f32_16x16x32_bf16 v[152:155], v[124:127], v[204:207], v[152:155]
	v_mfma_f32_16x16x32_bf16 v[148:151], v[116:119], v[212:215], v[148:151]
	v_mfma_f32_16x16x32_bf16 v[144:147], v[124:127], v[212:215], v[144:147]
	v_mfma_f32_16x16x32_bf16 v[108:111], v[116:119], v[220:223], v[108:111]
	v_mfma_f32_16x16x32_bf16 v[104:107], v[124:127], v[220:223], v[104:107]
	v_mfma_f32_16x16x32_bf16 v[100:103], v[116:119], v[228:231], v[100:103]
	v_mfma_f32_16x16x32_bf16 v[96:99], v[124:127], v[228:231], v[96:99]
	v_mfma_f32_16x16x32_bf16 v[60:63], v[128:131], v[160:163], v[60:63]
	v_mfma_f32_16x16x32_bf16 v[56:59], v[136:139], v[160:163], v[56:59]
	v_mfma_f32_16x16x32_bf16 v[52:55], v[128:131], v[208:211], v[52:55]
	v_mfma_f32_16x16x32_bf16 v[48:51], v[136:139], v[208:211], v[48:51]
	v_mfma_f32_16x16x32_bf16 v[44:47], v[128:131], v[216:219], v[44:47]
	v_mfma_f32_16x16x32_bf16 v[40:43], v[136:139], v[216:219], v[40:43]
	v_mfma_f32_16x16x32_bf16 v[36:39], v[128:131], v[224:227], v[36:39]
	v_mfma_f32_16x16x32_bf16 v[32:35], v[136:139], v[224:227], v[32:35]
	v_mfma_f32_16x16x32_bf16 v[60:63], v[132:135], v[204:207], v[60:63]
	v_mfma_f32_16x16x32_bf16 v[56:59], v[140:143], v[204:207], v[56:59]
	v_mfma_f32_16x16x32_bf16 v[52:55], v[132:135], v[212:215], v[52:55]
	v_mfma_f32_16x16x32_bf16 v[48:51], v[140:143], v[212:215], v[48:51]
	v_mfma_f32_16x16x32_bf16 v[44:47], v[132:135], v[220:223], v[44:47]
	v_mfma_f32_16x16x32_bf16 v[40:43], v[140:143], v[220:223], v[40:43]
	v_mfma_f32_16x16x32_bf16 v[36:39], v[132:135], v[228:231], v[36:39]
	v_mfma_f32_16x16x32_bf16 v[32:35], v[140:143], v[228:231], v[32:35]
	s_barrier
; #define PG8_STAGE(bufoff, gbase, voff) do { _Pragma("unroll") for (int _i = 0; _i < 2; ++_i) \
;         __builtin_amdgcn_global_load_lds((const unsigned*)((const char*)(gbase) + (voff)[_i]), (PG8_LAS unsigned*)(lds + (bufoff) + ldsw + _i * 8192), 16, 0, 0); } while (0)
; #define PG8_LDA(dst, b, h) do { _Pragma("unroll") for (int m = 0; m < 4; ++m) _Pragma("unroll") for (int k = 0; k < 2; ++k) dst[m][k] = *(const PG8_LAS bf16x8*)(lds + PG8_SA(b, h) + aoff + m * 2048 + k * 1024); } while (0)
; #define PG8_MMA(ai, bj, At, Bt) do { __builtin_amdgcn_s_setprio(1); _Pragma("unroll") for (int m = 0; m < 4; ++m) _Pragma("unroll") for (int n = 0; n < 2; ++n) _Pragma("unroll") for (int k = 0; k < 2; ++k) \
;         acc[ai][bj][m][n] = __builtin_amdgcn_mfma_f32_16x16x32_bf16(Bt[n][k], At[m][k], acc[ai][bj][m][n], 0, 0, 0); __builtin_amdgcn_s_setprio(0); } while (0)
; #define PG8_WAIT_V(n) asm volatile("s_waitcnt vmcnt(" #n ")" ::: "memory")
; #define PG8_WAIT_L(n) asm volatile("s_waitcnt lgkmcnt(" #n ")" ::: "memory")
; #define PG8_BAR __builtin_amdgcn_s_barrier()
; #define PG8_SCHED __builtin_amdgcn_sched_barrier(0)
; template <class Epi, class Sched, bool ALIGN_EPI = false, bool SP2 = false>
; __device__ __forceinline__ void gemm_phase(PG8_LAS unsigned char* lds, const Gemm g, const Sched& S, const Epi& E) {
;     ...
;         for (int t = 0; t < nt; t += 2) {
;             const bool last = (t == nt - 2);
;             const char* a1 = cA + (long)(t + 1) * kstepA;
;             const char* a2 = last ? nA : cA + (long)(t + 2) * kstepA; const char* b2 = last ? nB : cB + (long)(t + 2) * kstep;
;             const char* a3 = a2 + kstepA; const char* b3 = b2 + kstep;
;             if (last && has_next) S.a_ready(nxt);
;     ...
;             PG8_LDA(At, 1, 1); PG8_STAGE(PG8_SB(1, 0), b3, voffB); PG8_STAGE(PG8_SB(1, 1), b3 + hstepB, voffB); PG8_STAGE(PG8_SA(1, 0), a3, voffA);
;             PG8_WAIT_V(8); PG8_WAIT_L(0); PG8_BAR; PG8_MMA(1, 0, At, B0); PG8_MMA(1, 1, At, B1); PG8_BAR; PG8_SCHED;
	s_add_i32 s56, s68, s14
	v_lshl_add_u64 v[180:181], v[180:181], 0, s[40:41]
	s_mov_b32 m0, s56
	ds_read_b128 v[160:163], v203 offset:49152
	ds_read_b128 v[204:207], v203 offset:50176
	ds_read_b128 v[208:211], v203 offset:51200
	ds_read_b128 v[212:215], v203 offset:52224
	ds_read_b128 v[216:219], v203 offset:53248
	ds_read_b128 v[220:223], v203 offset:54272
	ds_read_b128 v[224:227], v203 offset:55296
	ds_read_b128 v[228:231], v203 offset:56320
	global_load_lds_dwordx4 v[180:181], off
	s_add_i32 m0, s56, 0x2000
	s_add_u32 s36, s36, 0x40080
	v_lshl_add_u64 v[180:181], v[184:185], 0, s[40:41]
	s_addc_u32 s37, s37, 0
	s_add_i32 s56, s69, s14
	global_load_lds_dwordx4 v[180:181], off
	v_lshl_add_u64 v[180:181], s[36:37], 0, v[166:167]
	s_mov_b32 m0, s56
	s_nop 0
	global_load_lds_dwordx4 v[180:181], off
	v_lshl_add_u64 v[180:181], s[36:37], 0, v[170:171]
	s_add_i32 m0, s56, 0x2000
	s_nop 0
	global_load_lds_dwordx4 v[180:181], off
	v_lshl_add_u64 v[180:181], v[188:189], 0, s[40:41]
	s_mov_b32 m0, s61
	s_nop 0
	global_load_lds_dwordx4 v[180:181], off
	v_lshl_add_u64 v[180:181], v[192:193], 0, s[40:41]
	s_mov_b32 m0, s62
	s_nop 0
	global_load_lds_dwordx4 v[180:181], off
	s_waitcnt vmcnt(8)
	s_waitcnt lgkmcnt(0)
	s_barrier
	s_waitcnt lgkmcnt(0)
	v_mfma_f32_16x16x32_bf16 v[92:95], v[112:115], v[160:163], v[92:95]
	v_mfma_f32_16x16x32_bf16 v[88:91], v[120:123], v[160:163], v[88:91]
	v_mfma_f32_16x16x32_bf16 v[84:87], v[112:115], v[208:211], v[84:87]
	v_mfma_f32_16x16x32_bf16 v[80:83], v[120:123], v[208:211], v[80:83]
	v_mfma_f32_16x16x32_bf16 v[76:79], v[112:115], v[216:219], v[76:79]
	v_mfma_f32_16x16x32_bf16 v[72:75], v[120:123], v[216:219], v[72:75]
	v_mfma_f32_16x16x32_bf16 v[68:71], v[112:115], v[224:227], v[68:71]
	v_mfma_f32_16x16x32_bf16 v[64:67], v[120:123], v[224:227], v[64:67]
	v_mfma_f32_16x16x32_bf16 v[92:95], v[116:119], v[204:207], v[92:95]
	v_mfma_f32_16x16x32_bf16 v[88:91], v[124:127], v[204:207], v[88:91]
	v_mfma_f32_16x16x32_bf16 v[84:87], v[116:119], v[212:215], v[84:87]
	v_mfma_f32_16x16x32_bf16 v[80:83], v[124:127], v[212:215], v[80:83]
	v_mfma_f32_16x16x32_bf16 v[76:79], v[116:119], v[220:223], v[76:79]
	v_mfma_f32_16x16x32_bf16 v[72:75], v[124:127], v[220:223], v[72:75]
	v_mfma_f32_16x16x32_bf16 v[68:71], v[116:119], v[228:231], v[68:71]
	v_mfma_f32_16x16x32_bf16 v[64:67], v[124:127], v[228:231], v[64:67]
	v_mfma_f32_16x16x32_bf16 v[28:31], v[128:131], v[160:163], v[28:31]
	v_mfma_f32_16x16x32_bf16 v[24:27], v[136:139], v[160:163], v[24:27]
	v_mfma_f32_16x16x32_bf16 v[20:23], v[128:131], v[208:211], v[20:23]
	v_mfma_f32_16x16x32_bf16 v[16:19], v[136:139], v[208:211], v[16:19]
	v_mfma_f32_16x16x32_bf16 v[12:15], v[128:131], v[216:219], v[12:15]
	v_mfma_f32_16x16x32_bf16 v[8:11], v[136:139], v[216:219], v[8:11]
	v_mfma_f32_16x16x32_bf16 v[4:7], v[128:131], v[224:227], v[4:7]
	v_mfma_f32_16x16x32_bf16 v[0:3], v[136:139], v[224:227], v[0:3]
	v_mfma_f32_16x16x32_bf16 v[28:31], v[132:135], v[204:207], v[28:31]
	v_mfma_f32_16x16x32_bf16 v[24:27], v[140:143], v[204:207], v[24:27]
	v_mfma_f32_16x16x32_bf16 v[20:23], v[132:135], v[212:215], v[20:23]
	v_mfma_f32_16x16x32_bf16 v[16:19], v[140:143], v[212:215], v[16:19]
	v_mfma_f32_16x16x32_bf16 v[12:15], v[132:135], v[220:223], v[12:15]
	v_mfma_f32_16x16x32_bf16 v[8:11], v[140:143], v[220:223], v[8:11]
	v_mfma_f32_16x16x32_bf16 v[4:7], v[132:135], v[228:231], v[4:7]
	v_mfma_f32_16x16x32_bf16 v[0:3], v[140:143], v[228:231], v[0:3]
	s_barrier
	s_add_u32 s12, s12, 0x100
	s_addc_u32 s13, s13, 0
	s_add_u32 s49, s49, 0x100
	s_addc_u32 s51, s51, 0
	s_cmp_ge_i32 s67, s58
	s_mov_b32 s36, s67
	s_cbranch_scc0 .LBB0_2190
